# out-proj epilogue: bf16 stores merged to 16B via permlane16_swap + fmac ssq chain; FoX mask-free tile variant off-diagonal; Z stores without nt
# speedup vs baseline: 1.0144x; 1.0102x over previous
; template <int MODE>
; __device__ __forceinline__ void attn_item(LAS unsigned char* lds, const AttnArgs& a, const int tid) {
;     ...
;         if (t <= tw) {
;             LAS unsigned char* kb = lds + b * 32768;
;             f32x16 s[2];
; #pragma unroll
;             for (int i = 0; i < 16; ++i) { s[0][i] = 0.f; s[1][i] = 0.f; }
;             constexpr int KD = AT_KD, VD = AT_VD;
;             bf16x8 kf[KD];
;     ...
; #pragma unroll
;             for (int i = 0; i < KD; ++i) kf[i] = AT_KLD(i);
; #pragma unroll
;             for (int i = 0; i < 2 * NKS; ++i) { s[i & 1] = MFMA32(kf[i % KD], qf[i >> 1], s[i & 1]); if (i + KD < 2 * NKS) kf[i % KD] = AT_KLD(i + KD); }
;     ...
;             bf16x8 vf[VD];
;     ...
; #pragma unroll
;             for (int j = 0; j < VD; ++j) AT_VLD(j);
;             const float sc = a.sc;
;             const bool diag = (MODE == 1) && (t * 64 + 63 > qw0);
;             const bool near = (MODE == 2) && (t >= tw - 2);
;             bf16x8 pf[2];
; #pragma unroll
;             for (int kt = 0; kt < 2; ++kt) {
;                 if (MODE == 1) {
;                     const LAS float* csb = (const LAS float*)(lds + A_CS) + t * 64 + 32 * kt + 4 * h;
;                     const int mb = t * 64 + 32 * kt + 4 * h - (qw0 + r);
; #pragma unroll
;                     for (int g = 0; g < 4; ++g) { const f32x4 cv = *(const LAS f32x4*)(csb + 8 * g);
; #pragma unroll
;                         for (int e = 0; e < 4; ++e) { float x = fmaf(s[kt][4 * g + e], sc, addc) + cv[e]; if (diag && (mb + 8 * g + e > 0)) x = -1e30f; s[kt][4 * g + e] = x; } }
;                 } else if (MODE == 2) {
;                     if (near) {
;                         const LAS float* lut = (const LAS float*)(lds + A_LUT) + (t * 64 + 32 * kt + 4 * h - (qw0 + r) + 191);
; #pragma unroll
;                         for (int i = 0; i < 16; ++i) s[kt][i] = fmaf(s[kt][i], sc, lut[8 * (i >> 2) + (i & 3)]);
;                     } else {
; #pragma unroll
;                         for (int i = 0; i < 16; ++i) s[kt][i] = fmaf(s[kt][i], sc, addc);
;                     }
;                 } else {
; #pragma unroll
;                     for (int i = 0; i < 16; ++i) s[kt][i] = fmaf(s[kt][i], sc, addc);
;                 }
;                 float ls = 0.f;
; #pragma unroll
;                 for (int i = 0; i < 16; ++i) { const float pv = fast_exp2(s[kt][i]); s[kt][i] = pv; ls += pv; }
;                 l += ls;
.LBB0_61:
	s_cmp_gt_i32 s34, s55
	v_add_u32_e32 v227, s60, v225
	s_cbranch_scc1 .LBB0_63
	s_sub_i32 s28, s60, 64
	s_cmp_gt_i32 s28, s51
	s_cbranch_scc1 .Lmy_fox_diag1
	ds_read_b128 v[2:5], v198
	ds_read_b128 v[6:9], v198 offset:8192
	ds_read_b128 v[10:13], v199
	ds_read_b128 v[156:159], v199 offset:8192
	s_sub_i32 s28, s60, 64
	s_waitcnt lgkmcnt(3)
	v_mfma_f32_32x32x16_bf16 v[96:111], v[2:5], v[116:119], 0
	ds_read_b128 v[2:5], v200
	s_cmp_gt_i32 s28, s51
	v_add_u32_e32 v0, 0xffffff81, v227
	s_cselect_b64 s[28:29], -1, 0
	s_movk_i32 s35, 0xffef
	s_waitcnt lgkmcnt(3)
	v_mfma_f32_32x32x16_bf16 v[80:95], v[6:9], v[116:119], 0
	ds_read_b128 v[6:9], v200 offset:8192
	s_movk_i32 s61, 0xffee
	s_movk_i32 s62, 0xffed
	s_movk_i32 s63, 0xffe8
	s_movk_i32 s40, 0xffe7
	s_movk_i32 s81, 0xffe6
	s_movk_i32 s23, 0xffe5
	s_waitcnt lgkmcnt(3)
	v_mfma_f32_32x32x16_bf16 v[96:111], v[10:13], v[120:123], v[96:111]
	ds_read_b128 v[10:13], v201
	s_waitcnt lgkmcnt(3)
	v_mfma_f32_32x32x16_bf16 v[80:95], v[156:159], v[120:123], v[80:95]
	ds_read_b128 v[156:159], v201 offset:8192
	s_waitcnt lgkmcnt(3)
	v_mfma_f32_32x32x16_bf16 v[96:111], v[2:5], v[124:127], v[96:111]
	ds_read_b128 v[2:5], v213
	s_waitcnt lgkmcnt(3)
	v_mfma_f32_32x32x16_bf16 v[80:95], v[6:9], v[124:127], v[80:95]
	ds_read_b128 v[6:9], v213 offset:8192
	s_waitcnt lgkmcnt(3)
	v_mfma_f32_32x32x16_bf16 v[96:111], v[10:13], v[128:131], v[96:111]
	ds_read_b128 v[10:13], v214
	s_waitcnt lgkmcnt(3)
	v_mfma_f32_32x32x16_bf16 v[80:95], v[156:159], v[128:131], v[80:95]
	ds_read_b128 v[156:159], v214 offset:8192
	s_waitcnt lgkmcnt(3)
	v_mfma_f32_32x32x16_bf16 v[96:111], v[2:5], v[132:135], v[96:111]
	ds_read_b128 v[2:5], v215
	s_waitcnt lgkmcnt(3)
	v_mfma_f32_32x32x16_bf16 v[80:95], v[6:9], v[132:135], v[80:95]
	ds_read_b128 v[6:9], v215 offset:8192
	s_waitcnt lgkmcnt(3)
	v_mfma_f32_32x32x16_bf16 v[96:111], v[10:13], v[136:139], v[96:111]
	ds_read_b128 v[10:13], v216
	s_waitcnt lgkmcnt(3)
	v_mfma_f32_32x32x16_bf16 v[80:95], v[156:159], v[136:139], v[80:95]
	ds_read_b128 v[156:159], v216 offset:8192
	s_waitcnt lgkmcnt(3)
	v_mfma_f32_32x32x16_bf16 v[96:111], v[2:5], v[140:143], v[96:111]
	s_waitcnt lgkmcnt(2)
	v_mfma_f32_32x32x16_bf16 v[80:95], v[6:9], v[140:143], v[80:95]
	s_waitcnt lgkmcnt(1)
	v_mfma_f32_32x32x16_bf16 v[96:111], v[10:13], v[144:147], v[96:111]
	ds_read_b64_tr_b16 v[6:7], v217 offset:16384
	ds_read_b64_tr_b16 v[8:9], v218 offset:16384
	ds_read_b64_tr_b16 v[10:11], v219 offset:16384
	ds_read_b64_tr_b16 v[12:13], v220 offset:16384
	ds_read_b64_tr_b16 v[2:3], v221 offset:16384
	ds_read_b64_tr_b16 v[4:5], v222 offset:16384
	s_nop 5
	v_fmamk_f32 v14, v96, 0x3e0293ee, v151
	s_waitcnt lgkmcnt(6)
	v_mfma_f32_32x32x16_bf16 v[80:95], v[156:159], v[144:147], v[80:95]
	ds_read_b128 v[156:159], v226
	ds_read_b128 v[160:163], v226 offset:32
	v_fmamk_f32 v15, v97, 0x3e0293ee, v151
	v_fmamk_f32 v96, v98, 0x3e0293ee, v151
	s_waitcnt lgkmcnt(1)
	v_add_f32_e32 v14, v14, v156
	v_add_f32_e32 v15, v15, v157
	v_add_f32_e32 v96, v96, v158
	v_mov_b32_e32 v155, v96
	v_fmamk_f32 v96, v99, 0x3e0293ee, v151
	v_add_f32_e32 v96, v96, v159
	v_mov_b32_e32 v156, v96
	v_fmamk_f32 v96, v100, 0x3e0293ee, v151
	s_waitcnt lgkmcnt(0)
	v_add_f32_e32 v96, v96, v160
	v_mov_b32_e32 v157, v96
	v_fmamk_f32 v96, v101, 0x3e0293ee, v151
	v_add_f32_e32 v96, v96, v161
	v_mov_b32_e32 v101, v96
	v_fmamk_f32 v96, v102, 0x3e0293ee, v151
	v_add_f32_e32 v96, v96, v162
	v_mov_b32_e32 v158, v96
	v_fmamk_f32 v96, v103, 0x3e0293ee, v151
	v_add_f32_e32 v96, v96, v163
	v_mov_b32_e32 v103, v96
	ds_read_b128 v[96:99], v226 offset:64
	v_fmamk_f32 v100, v104, 0x3e0293ee, v151
	v_exp_f32_e32 v14, v14
	s_waitcnt lgkmcnt(0)
	v_add_f32_e32 v96, v100, v96
	v_mov_b32_e32 v159, v96
	v_fmamk_f32 v96, v105, 0x3e0293ee, v151
	v_add_f32_e32 v96, v96, v97
	v_mov_b32_e32 v105, v96
	v_fmamk_f32 v96, v106, 0x3e0293ee, v151
	v_add_f32_e32 v96, v96, v98
	v_mov_b32_e32 v161, v96
	v_fmamk_f32 v96, v107, 0x3e0293ee, v151
	v_add_f32_e32 v96, v96, v99
	v_mov_b32_e32 v107, v96
	ds_read_b128 v[96:99], v226 offset:96
	v_fmamk_f32 v100, v108, 0x3e0293ee, v151
	v_exp_f32_e32 v104, v155
	s_waitcnt lgkmcnt(0)
	v_add_f32_e32 v96, v100, v96
	v_fmamk_f32 v100, v109, 0x3e0293ee, v151
	v_add_f32_e32 v97, v100, v97
	v_fmamk_f32 v100, v110, 0x3e0293ee, v151
	v_add_f32_e32 v98, v100, v98
	v_fmamk_f32 v100, v111, 0x3e0293ee, v151
	v_add_f32_e32 v99, v100, v99
	v_exp_f32_e32 v100, v15
	v_exp_f32_e32 v102, v156
	v_exp_f32_e32 v106, v157
	v_exp_f32_e32 v108, v101
	v_exp_f32_e32 v156, v158
	v_exp_f32_e32 v110, v103
	v_exp_f32_e32 v168, v96
	v_exp_f32_e32 v166, v97
	v_exp_f32_e32 v172, v98
	v_exp_f32_e32 v170, v99
	v_cvt_pk_bf16_f32 v96, v14, v100
	v_cvt_pk_bf16_f32 v97, v104, v102
	v_cvt_pk_bf16_f32 v98, v106, v108
	v_cvt_pk_bf16_f32 v99, v156, v110
	v_exp_f32_e32 v160, v159
	v_exp_f32_e32 v158, v105
	v_mfma_f32_32x32x16_bf16 v[64:79], v[6:9], v[96:99], v[64:79]
	ds_read_b64_tr_b16 v[6:7], v223 offset:16384
	ds_read_b64_tr_b16 v[8:9], v224 offset:16384
	v_exp_f32_e32 v164, v161
	v_exp_f32_e32 v162, v107
	v_cvt_pk_bf16_f32 v232, v160, v158
	v_cvt_pk_bf16_f32 v234, v168, v166
	v_cvt_pk_bf16_f32 v235, v172, v170
	v_cvt_pk_bf16_f32 v233, v164, v162
	v_mfma_f32_32x32x16_bf16 v[48:63], v[10:13], v[96:99], v[48:63]
	ds_read_b64_tr_b16 v[10:11], v217 offset:20480
	ds_read_b64_tr_b16 v[12:13], v218 offset:20480
	v_add_f32_e32 v0, 0, v14
	v_fmamk_f32 v15, v88, 0x3e0293ee, v151
	v_mfma_f32_32x32x16_bf16 v[32:47], v[2:5], v[96:99], v[32:47]
	ds_read_b64_tr_b16 v[2:3], v219 offset:20480
	ds_read_b64_tr_b16 v[4:5], v220 offset:20480
	s_waitcnt lgkmcnt(4)
; #define LAS __attribute__((address_space(3)))
; #define MFMA32(a, b, c) __builtin_amdgcn_mfma_f32_32x32x16_bf16((a), (b), (c), 0, 0, 0)
; template <int MODE>
; __device__ __forceinline__ void attn_item(LAS unsigned char* lds, const AttnArgs& a, const int tid) {
;     ...
;             for (int kt = 0; kt < 2; ++kt) {
;                 if (MODE == 1) {
;                     const LAS float* csb = (const LAS float*)(lds + A_CS) + t * 64 + 32 * kt + 4 * h;
;                     const int mb = t * 64 + 32 * kt + 4 * h - (qw0 + r);
; #pragma unroll
;                     for (int g = 0; g < 4; ++g) { const f32x4 cv = *(const LAS f32x4*)(csb + 8 * g);
; #pragma unroll
;                         for (int e = 0; e < 4; ++e) { float x = fmaf(s[kt][4 * g + e], sc, addc) + cv[e]; if (diag && (mb + 8 * g + e > 0)) x = -1e30f; s[kt][4 * g + e] = x; } }
;                 } else if (MODE == 2) {
;                     if (near) {
;                         const LAS float* lut = (const LAS float*)(lds + A_LUT) + (t * 64 + 32 * kt + 4 * h - (qw0 + r) + 191);
; #pragma unroll
;                         for (int i = 0; i < 16; ++i) s[kt][i] = fmaf(s[kt][i], sc, lut[8 * (i >> 2) + (i & 3)]);
;                     } else {
; #pragma unroll
;                         for (int i = 0; i < 16; ++i) s[kt][i] = fmaf(s[kt][i], sc, addc);
;                     }
;                 } else {
; #pragma unroll
;                     for (int i = 0; i < 16; ++i) s[kt][i] = fmaf(s[kt][i], sc, addc);
;                 }
;                 float ls = 0.f;
; #pragma unroll
;                 for (int i = 0; i < 16; ++i) { const float pv = fast_exp2(s[kt][i]); s[kt][i] = pv; ls += pv; }
;                 l += ls;
; #pragma unroll
;                 for (int ss = 0; ss < 2; ++ss) { u32x4 w;
;                     w.x = pk2(s[kt][8 * ss + 0], s[kt][8 * ss + 1]); w.y = pk2(s[kt][8 * ss + 2], s[kt][8 * ss + 3]);
;                     w.z = pk2(s[kt][8 * ss + 4], s[kt][8 * ss + 5]); w.w = pk2(s[kt][8 * ss + 6], s[kt][8 * ss + 7]);
;                     pf[ss] = __builtin_bit_cast(bf16x8, w); }
; #pragma unroll
;                 for (int jj = 0; jj < 8; ++jj) { const int j = 8 * kt + jj;
;                     o[jj & 3] = MFMA32(vf[j % VD], pf[jj >> 2], o[jj & 3]);
;                     if (j + VD < 16) AT_VLD(j + VD); }
;             }
	v_mfma_f32_32x32x16_bf16 v[16:31], v[6:9], v[96:99], v[16:31]
	ds_read_b64_tr_b16 v[6:7], v221 offset:20480
	ds_read_b64_tr_b16 v[8:9], v222 offset:20480
	s_waitcnt lgkmcnt(4)
	v_mfma_f32_32x32x16_bf16 v[64:79], v[10:13], v[232:235], v[64:79]
	ds_read_b64_tr_b16 v[10:11], v223 offset:20480
	ds_read_b64_tr_b16 v[12:13], v224 offset:20480
	ds_read_b64_tr_b16 v[236:237], v217 offset:24576
	ds_read_b64_tr_b16 v[238:239], v218 offset:24576
	ds_read_b64_tr_b16 v[240:241], v219 offset:24576
	ds_read_b64_tr_b16 v[242:243], v220 offset:24576
	ds_read_b64_tr_b16 v[96:97], v221 offset:24576
	ds_read_b64_tr_b16 v[98:99], v222 offset:24576
	s_waitcnt lgkmcnt(10)
	v_mfma_f32_32x32x16_bf16 v[48:63], v[2:5], v[232:235], v[48:63]
	ds_read_b128 v[2:5], v226 offset:128
	s_waitcnt lgkmcnt(9)
	v_mfma_f32_32x32x16_bf16 v[32:47], v[6:9], v[232:235], v[32:47]
	v_add_u32_e32 v6, 0xffffffa1, v227
	v_fmamk_f32 v7, v80, 0x3e0293ee, v151
	s_waitcnt lgkmcnt(0)
	v_add_f32_e32 v2, v7, v2
	v_mov_b32_e32 v7, v2
	v_fmamk_f32 v2, v81, 0x3e0293ee, v151
	v_add_f32_e32 v2, v2, v3
	v_mov_b32_e32 v8, v2
	v_fmamk_f32 v2, v82, 0x3e0293ee, v151
	v_add_f32_e32 v2, v2, v4
	v_mov_b32_e32 v9, v2
	v_fmamk_f32 v2, v83, 0x3e0293ee, v151
	v_add_f32_e32 v2, v2, v5
	v_mfma_f32_32x32x16_bf16 v[16:31], v[10:13], v[232:235], v[16:31]
	v_mov_b32_e32 v10, v2
	ds_read_b128 v[2:5], v226 offset:160
	v_fmamk_f32 v11, v84, 0x3e0293ee, v151
	v_fmamk_f32 v83, v92, 0x3e0293ee, v151
	s_waitcnt lgkmcnt(0)
	v_add_f32_e32 v2, v11, v2
	v_mov_b32_e32 v11, v2
	v_fmamk_f32 v2, v85, 0x3e0293ee, v151
	v_add_f32_e32 v2, v2, v3
	v_mov_b32_e32 v12, v2
	v_fmamk_f32 v2, v86, 0x3e0293ee, v151
	v_add_f32_e32 v2, v2, v4
	v_mov_b32_e32 v13, v2
	v_fmamk_f32 v2, v87, 0x3e0293ee, v151
	v_add_f32_e32 v2, v2, v5
	v_mov_b32_e32 v14, v2
	ds_read_b128 v[2:5], v226 offset:192
	v_exp_f32_e32 v101, v7
	v_exp_f32_e32 v105, v8
	s_waitcnt lgkmcnt(0)
	v_add_f32_e32 v2, v15, v2
	v_mov_b32_e32 v15, v2
	v_fmamk_f32 v2, v89, 0x3e0293ee, v151
	v_add_f32_e32 v2, v2, v3
	v_mov_b32_e32 v80, v2
	v_fmamk_f32 v2, v90, 0x3e0293ee, v151
	v_add_f32_e32 v2, v2, v4
	v_mov_b32_e32 v81, v2
	v_fmamk_f32 v2, v91, 0x3e0293ee, v151
	v_add_f32_e32 v2, v2, v5
	v_mov_b32_e32 v82, v2
	ds_read_b128 v[2:5], v226 offset:224
	v_exp_f32_e32 v103, v9
	v_exp_f32_e32 v107, v10
	s_waitcnt lgkmcnt(0)
	v_add_f32_e32 v2, v83, v2
	v_mov_b32_e32 v83, v2
	v_fmamk_f32 v2, v93, 0x3e0293ee, v151
	v_add_f32_e32 v2, v2, v3
	v_mov_b32_e32 v84, v2
	v_fmamk_f32 v2, v94, 0x3e0293ee, v151
	v_add_f32_e32 v2, v2, v4
	v_mov_b32_e32 v4, v2
	v_fmamk_f32 v2, v95, 0x3e0293ee, v151
	v_add_f32_e32 v2, v2, v5
	v_mov_b32_e32 v5, v2
	v_pk_add_f32 v[2:3], v[100:101], v[0:1]
	v_exp_f32_e32 v109, v11
	v_pk_add_f32 v[2:3], v[104:105], v[2:3]
	v_exp_f32_e32 v157, v12
	v_pk_add_f32 v[2:3], v[102:103], v[2:3]
	v_exp_f32_e32 v111, v13
	v_pk_add_f32 v[2:3], v[106:107], v[2:3]
	v_exp_f32_e32 v161, v14
	ds_read_b64_tr_b16 v[10:11], v223 offset:24576
	ds_read_b64_tr_b16 v[12:13], v224 offset:24576
	v_exp_f32_e32 v159, v15
	v_pk_add_f32 v[2:3], v[108:109], v[2:3]
	v_exp_f32_e32 v165, v80
	v_pk_add_f32 v[2:3], v[156:157], v[2:3]
	v_exp_f32_e32 v163, v81
	v_pk_add_f32 v[2:3], v[110:111], v[2:3]
	v_exp_f32_e32 v169, v82
	v_pk_add_f32 v[2:3], v[160:161], v[2:3]
	v_cvt_pk_bf16_f32 v6, v101, v105
	v_cvt_pk_bf16_f32 v7, v103, v107
	v_cvt_pk_bf16_f32 v8, v109, v157
	v_cvt_pk_bf16_f32 v9, v111, v161
	v_exp_f32_e32 v167, v83
	v_pk_add_f32 v[2:3], v[158:159], v[2:3]
	v_mfma_f32_32x32x16_bf16 v[64:79], v[236:239], v[6:9], v[64:79]
	v_exp_f32_e32 v173, v84
	v_pk_add_f32 v[2:3], v[164:165], v[2:3]
	v_exp_f32_e32 v171, v4
	v_pk_add_f32 v[2:3], v[162:163], v[2:3]
	v_exp_f32_e32 v155, v5
	v_pk_add_f32 v[2:3], v[168:169], v[2:3]
	ds_read_b64_tr_b16 v[84:85], v217 offset:28672
	ds_read_b64_tr_b16 v[86:87], v218 offset:28672
	v_mfma_f32_32x32x16_bf16 v[48:63], v[240:243], v[6:9], v[48:63]
	ds_read_b64_tr_b16 v[80:81], v219 offset:28672
	ds_read_b64_tr_b16 v[82:83], v220 offset:28672
	v_add_f32_e64 v2, v166, v2
	v_add_f32_e64 v3, v167, v3
	v_cvt_pk_bf16_f32 v4, v167, v173
	v_pk_add_f32 v[2:3], v[172:173], v[2:3]
	v_cvt_pk_bf16_f32 v5, v171, v155
	v_pk_add_f32 v[2:3], v[170:171], v[2:3]
	v_mfma_f32_32x32x16_bf16 v[32:47], v[96:99], v[6:9], v[32:47]
	v_add_f32_e64 v14, v154, v2
	v_add_f32_e64 v15, v155, v3
	v_cvt_pk_bf16_f32 v2, v159, v165
	v_cvt_pk_bf16_f32 v3, v163, v169
	v_add_f32_e32 v154, v14, v15
	s_waitcnt lgkmcnt(4)
	v_mfma_f32_32x32x16_bf16 v[16:31], v[10:13], v[6:9], v[16:31]
	ds_read_b64_tr_b16 v[6:7], v221 offset:28672
	ds_read_b64_tr_b16 v[8:9], v222 offset:28672
	ds_read_b64_tr_b16 v[10:11], v223 offset:28672
	ds_read_b64_tr_b16 v[12:13], v224 offset:28672
	s_waitcnt lgkmcnt(6)
	v_mfma_f32_32x32x16_bf16 v[64:79], v[84:87], v[2:5], v[64:79]
	s_waitcnt lgkmcnt(4)
	v_mfma_f32_32x32x16_bf16 v[48:63], v[80:83], v[2:5], v[48:63]
	s_waitcnt lgkmcnt(2)
	v_mfma_f32_32x32x16_bf16 v[32:47], v[6:9], v[2:5], v[32:47]
	s_waitcnt lgkmcnt(0)
	v_mfma_f32_32x32x16_bf16 v[16:31], v[10:13], v[2:5], v[16:31]
	s_branch .LBB0_63
; #define LAS __attribute__((address_space(3)))
; #define MFMA32(a, b, c) __builtin_amdgcn_mfma_f32_32x32x16_bf16((a), (b), (c), 0, 0, 0)
; template <int MODE>
; __device__ __forceinline__ void attn_item(LAS unsigned char* lds, const AttnArgs& a, const int tid) {
;     ...
; #pragma unroll
;             for (int i = 0; i < 16; ++i) { s[0][i] = 0.f; s[1][i] = 0.f; }
;             constexpr int KD = AT_KD, VD = AT_VD;
;             bf16x8 kf[KD];
;     ...
; #pragma unroll
;             for (int i = 0; i < KD; ++i) kf[i] = AT_KLD(i);
; #pragma unroll
;             for (int i = 0; i < 2 * NKS; ++i) { s[i & 1] = MFMA32(kf[i % KD], qf[i >> 1], s[i & 1]); if (i + KD < 2 * NKS) kf[i % KD] = AT_KLD(i + KD); }
;     ...
;             bf16x8 vf[VD];
;     ...
; #pragma unroll
;             for (int j = 0; j < VD; ++j) AT_VLD(j);
;             const float sc = a.sc;
;             const bool diag = (MODE == 1) && (t * 64 + 63 > qw0);
;             const bool near = (MODE == 2) && (t >= tw - 2);
;             bf16x8 pf[2];
; #pragma unroll
;             for (int kt = 0; kt < 2; ++kt) {
;                 if (MODE == 1) {
;                     const LAS float* csb = (const LAS float*)(lds + A_CS) + t * 64 + 32 * kt + 4 * h;
;                     const int mb = t * 64 + 32 * kt + 4 * h - (qw0 + r);
; #pragma unroll
;                     for (int g = 0; g < 4; ++g) { const f32x4 cv = *(const LAS f32x4*)(csb + 8 * g);
; #pragma unroll
;                         for (int e = 0; e < 4; ++e) { float x = fmaf(s[kt][4 * g + e], sc, addc) + cv[e]; if (diag && (mb + 8 * g + e > 0)) x = -1e30f; s[kt][4 * g + e] = x; } }
.Lmy_fox_diag1:
	ds_read_b128 v[2:5], v198
	ds_read_b128 v[6:9], v198 offset:8192
	ds_read_b128 v[10:13], v199
	ds_read_b128 v[156:159], v199 offset:8192
	s_sub_i32 s28, s60, 64
	s_waitcnt lgkmcnt(3)
	v_mfma_f32_32x32x16_bf16 v[96:111], v[2:5], v[116:119], 0
	ds_read_b128 v[2:5], v200
	s_cmp_gt_i32 s28, s51
	v_add_u32_e32 v0, 0xffffff81, v227
	s_cselect_b64 s[28:29], -1, 0
	v_cmp_lt_i32_e32 vcc, 0, v0
	s_and_b64 vcc, s[28:29], vcc
	s_movk_i32 s35, 0xffef
	s_waitcnt lgkmcnt(3)
	v_mfma_f32_32x32x16_bf16 v[80:95], v[6:9], v[116:119], 0
	ds_read_b128 v[6:9], v200 offset:8192
	s_movk_i32 s61, 0xffee
	s_movk_i32 s62, 0xffed
	s_movk_i32 s63, 0xffe8
	s_movk_i32 s40, 0xffe7
	s_movk_i32 s81, 0xffe6
	s_movk_i32 s23, 0xffe5
	s_waitcnt lgkmcnt(3)
	v_mfma_f32_32x32x16_bf16 v[96:111], v[10:13], v[120:123], v[96:111]
	ds_read_b128 v[10:13], v201
	s_waitcnt lgkmcnt(3)
	v_mfma_f32_32x32x16_bf16 v[80:95], v[156:159], v[120:123], v[80:95]
	ds_read_b128 v[156:159], v201 offset:8192
	s_waitcnt lgkmcnt(3)
	v_mfma_f32_32x32x16_bf16 v[96:111], v[2:5], v[124:127], v[96:111]
	ds_read_b128 v[2:5], v213
	s_waitcnt lgkmcnt(3)
	v_mfma_f32_32x32x16_bf16 v[80:95], v[6:9], v[124:127], v[80:95]
	ds_read_b128 v[6:9], v213 offset:8192
	s_waitcnt lgkmcnt(3)
	v_mfma_f32_32x32x16_bf16 v[96:111], v[10:13], v[128:131], v[96:111]
	ds_read_b128 v[10:13], v214
	s_waitcnt lgkmcnt(3)
	v_mfma_f32_32x32x16_bf16 v[80:95], v[156:159], v[128:131], v[80:95]
	ds_read_b128 v[156:159], v214 offset:8192
	s_waitcnt lgkmcnt(3)
	v_mfma_f32_32x32x16_bf16 v[96:111], v[2:5], v[132:135], v[96:111]
	ds_read_b128 v[2:5], v215
	s_waitcnt lgkmcnt(3)
	v_mfma_f32_32x32x16_bf16 v[80:95], v[6:9], v[132:135], v[80:95]
	ds_read_b128 v[6:9], v215 offset:8192
	s_waitcnt lgkmcnt(3)
	v_mfma_f32_32x32x16_bf16 v[96:111], v[10:13], v[136:139], v[96:111]
	ds_read_b128 v[10:13], v216
	s_waitcnt lgkmcnt(3)
	v_mfma_f32_32x32x16_bf16 v[80:95], v[156:159], v[136:139], v[80:95]
	ds_read_b128 v[156:159], v216 offset:8192
	s_waitcnt lgkmcnt(3)
	v_mfma_f32_32x32x16_bf16 v[96:111], v[2:5], v[140:143], v[96:111]
	s_waitcnt lgkmcnt(2)
	v_mfma_f32_32x32x16_bf16 v[80:95], v[6:9], v[140:143], v[80:95]
	s_waitcnt lgkmcnt(1)
	v_mfma_f32_32x32x16_bf16 v[96:111], v[10:13], v[144:147], v[96:111]
	ds_read_b64_tr_b16 v[6:7], v217 offset:16384
	ds_read_b64_tr_b16 v[8:9], v218 offset:16384
	ds_read_b64_tr_b16 v[10:11], v219 offset:16384
	ds_read_b64_tr_b16 v[12:13], v220 offset:16384
	ds_read_b64_tr_b16 v[2:3], v221 offset:16384
	ds_read_b64_tr_b16 v[4:5], v222 offset:16384
	s_nop 5
	v_fmamk_f32 v14, v96, 0x3e0293ee, v151
	s_waitcnt lgkmcnt(6)
	v_mfma_f32_32x32x16_bf16 v[80:95], v[156:159], v[144:147], v[80:95]
	ds_read_b128 v[156:159], v226
	ds_read_b128 v[160:163], v226 offset:32
	v_fmamk_f32 v15, v97, 0x3e0293ee, v151
	v_fmamk_f32 v96, v98, 0x3e0293ee, v151
	s_waitcnt lgkmcnt(1)
	v_add_f32_e32 v14, v14, v156
	v_cndmask_b32_e32 v14, v14, v210, vcc
	v_cmp_lt_i32_e32 vcc, -1, v0
	v_add_f32_e32 v15, v15, v157
	s_and_b64 vcc, s[28:29], vcc
	v_cndmask_b32_e32 v15, v15, v210, vcc
	v_cmp_lt_i32_e32 vcc, -2, v0
	v_add_f32_e32 v96, v96, v158
	s_and_b64 vcc, s[28:29], vcc
	v_cndmask_b32_e32 v155, v96, v210, vcc
	v_fmamk_f32 v96, v99, 0x3e0293ee, v151
	v_cmp_lt_i32_e32 vcc, -3, v0
	v_add_f32_e32 v96, v96, v159
	s_and_b64 vcc, s[28:29], vcc
	v_cndmask_b32_e32 v156, v96, v210, vcc
	v_fmamk_f32 v96, v100, 0x3e0293ee, v151
	v_cmp_lt_i32_e32 vcc, -8, v0
	s_waitcnt lgkmcnt(0)
	v_add_f32_e32 v96, v96, v160
	s_and_b64 vcc, s[28:29], vcc
	v_cndmask_b32_e32 v157, v96, v210, vcc
	v_fmamk_f32 v96, v101, 0x3e0293ee, v151
	v_cmp_lt_i32_e32 vcc, -9, v0
	v_add_f32_e32 v96, v96, v161
	s_and_b64 vcc, s[28:29], vcc
	v_cndmask_b32_e32 v101, v96, v210, vcc
	v_fmamk_f32 v96, v102, 0x3e0293ee, v151
	v_cmp_lt_i32_e32 vcc, -10, v0
	v_add_f32_e32 v96, v96, v162
	s_and_b64 vcc, s[28:29], vcc
	v_cndmask_b32_e32 v158, v96, v210, vcc
	v_fmamk_f32 v96, v103, 0x3e0293ee, v151
	v_cmp_lt_i32_e32 vcc, -11, v0
	v_add_f32_e32 v96, v96, v163
	s_and_b64 vcc, s[28:29], vcc
	v_cndmask_b32_e32 v103, v96, v210, vcc
	ds_read_b128 v[96:99], v226 offset:64
	v_fmamk_f32 v100, v104, 0x3e0293ee, v151
	v_cmp_lt_i32_e32 vcc, -16, v0
	s_and_b64 vcc, s[28:29], vcc
	v_exp_f32_e32 v14, v14
	s_waitcnt lgkmcnt(0)
	v_add_f32_e32 v96, v100, v96
	v_cndmask_b32_e32 v159, v96, v210, vcc
	v_fmamk_f32 v96, v105, 0x3e0293ee, v151
	v_cmp_lt_i32_e32 vcc, s35, v0
	v_add_f32_e32 v96, v96, v97
	s_and_b64 vcc, s[28:29], vcc
	v_cndmask_b32_e32 v105, v96, v210, vcc
	v_fmamk_f32 v96, v106, 0x3e0293ee, v151
	v_cmp_lt_i32_e32 vcc, s61, v0
	v_add_f32_e32 v96, v96, v98
	s_and_b64 vcc, s[28:29], vcc
	v_cndmask_b32_e32 v161, v96, v210, vcc
	v_fmamk_f32 v96, v107, 0x3e0293ee, v151
	v_cmp_lt_i32_e32 vcc, s62, v0
	v_add_f32_e32 v96, v96, v99
	s_and_b64 vcc, s[28:29], vcc
	v_cndmask_b32_e32 v107, v96, v210, vcc
	ds_read_b128 v[96:99], v226 offset:96
	v_fmamk_f32 v100, v108, 0x3e0293ee, v151
	v_cmp_lt_i32_e32 vcc, s63, v0
	s_and_b64 vcc, s[28:29], vcc
	v_exp_f32_e32 v104, v155
	s_waitcnt lgkmcnt(0)
; #define LAS __attribute__((address_space(3)))
; #define MFMA32(a, b, c) __builtin_amdgcn_mfma_f32_32x32x16_bf16((a), (b), (c), 0, 0, 0)
; __device__ __forceinline__ float fast_exp2(float x) { return __builtin_amdgcn_exp2f(x); }
; template <int MODE>
; __device__ __forceinline__ void attn_item(LAS unsigned char* lds, const AttnArgs& a, const int tid) {
;     ...
;             for (int kt = 0; kt < 2; ++kt) {
;                 if (MODE == 1) {
;                     const LAS float* csb = (const LAS float*)(lds + A_CS) + t * 64 + 32 * kt + 4 * h;
;                     const int mb = t * 64 + 32 * kt + 4 * h - (qw0 + r);
; #pragma unroll
;                     for (int g = 0; g < 4; ++g) { const f32x4 cv = *(const LAS f32x4*)(csb + 8 * g);
; #pragma unroll
;                         for (int e = 0; e < 4; ++e) { float x = fmaf(s[kt][4 * g + e], sc, addc) + cv[e]; if (diag && (mb + 8 * g + e > 0)) x = -1e30f; s[kt][4 * g + e] = x; } }
;                 } else if (MODE == 2) {
;                     if (near) {
;                         const LAS float* lut = (const LAS float*)(lds + A_LUT) + (t * 64 + 32 * kt + 4 * h - (qw0 + r) + 191);
; #pragma unroll
;                         for (int i = 0; i < 16; ++i) s[kt][i] = fmaf(s[kt][i], sc, lut[8 * (i >> 2) + (i & 3)]);
;                     } else {
; #pragma unroll
;                         for (int i = 0; i < 16; ++i) s[kt][i] = fmaf(s[kt][i], sc, addc);
;                     }
;                 } else {
; #pragma unroll
;                     for (int i = 0; i < 16; ++i) s[kt][i] = fmaf(s[kt][i], sc, addc);
;                 }
;                 float ls = 0.f;
; #pragma unroll
;                 for (int i = 0; i < 16; ++i) { const float pv = fast_exp2(s[kt][i]); s[kt][i] = pv; ls += pv; }
;                 l += ls;
; #pragma unroll
;                 for (int ss = 0; ss < 2; ++ss) { u32x4 w;
;                     w.x = pk2(s[kt][8 * ss + 0], s[kt][8 * ss + 1]); w.y = pk2(s[kt][8 * ss + 2], s[kt][8 * ss + 3]);
;                     w.z = pk2(s[kt][8 * ss + 4], s[kt][8 * ss + 5]); w.w = pk2(s[kt][8 * ss + 6], s[kt][8 * ss + 7]);
;                     pf[ss] = __builtin_bit_cast(bf16x8, w); }
; #pragma unroll
;                 for (int jj = 0; jj < 8; ++jj) { const int j = 8 * kt + jj;
;                     o[jj & 3] = MFMA32(vf[j % VD], pf[jj >> 2], o[jj & 3]);
;                     if (j + VD < 16) AT_VLD(j + VD); }
	v_add_f32_e32 v96, v100, v96
	v_cndmask_b32_e32 v96, v96, v210, vcc
	v_fmamk_f32 v100, v109, 0x3e0293ee, v151
	v_cmp_lt_i32_e32 vcc, s40, v0
	v_add_f32_e32 v97, v100, v97
	s_and_b64 vcc, s[28:29], vcc
	v_fmamk_f32 v100, v110, 0x3e0293ee, v151
	v_cndmask_b32_e32 v97, v97, v210, vcc
	v_add_f32_e32 v98, v100, v98
	v_cmp_lt_i32_e32 vcc, s81, v0
	v_fmamk_f32 v100, v111, 0x3e0293ee, v151
	s_and_b64 vcc, s[28:29], vcc
	v_add_f32_e32 v99, v100, v99
	v_exp_f32_e32 v100, v15
	v_exp_f32_e32 v102, v156
	v_exp_f32_e32 v106, v157
	v_exp_f32_e32 v108, v101
	v_exp_f32_e32 v156, v158
	v_exp_f32_e32 v110, v103
	v_cndmask_b32_e32 v98, v98, v210, vcc
	v_cmp_lt_i32_e32 vcc, s23, v0
	s_and_b64 vcc, s[28:29], vcc
	v_exp_f32_e32 v168, v96
	v_cndmask_b32_e32 v99, v99, v210, vcc
	v_exp_f32_e32 v166, v97
	v_exp_f32_e32 v172, v98
	v_exp_f32_e32 v170, v99
	v_cvt_pk_bf16_f32 v96, v14, v100
	v_cvt_pk_bf16_f32 v97, v104, v102
	v_cvt_pk_bf16_f32 v98, v106, v108
	v_cvt_pk_bf16_f32 v99, v156, v110
	v_exp_f32_e32 v160, v159
	v_exp_f32_e32 v158, v105
	v_mfma_f32_32x32x16_bf16 v[64:79], v[6:9], v[96:99], v[64:79]
	ds_read_b64_tr_b16 v[6:7], v223 offset:16384
	ds_read_b64_tr_b16 v[8:9], v224 offset:16384
	v_exp_f32_e32 v164, v161
	v_exp_f32_e32 v162, v107
	v_cvt_pk_bf16_f32 v232, v160, v158
	v_cvt_pk_bf16_f32 v234, v168, v166
	v_cvt_pk_bf16_f32 v235, v172, v170
	v_cvt_pk_bf16_f32 v233, v164, v162
	v_mfma_f32_32x32x16_bf16 v[48:63], v[10:13], v[96:99], v[48:63]
	ds_read_b64_tr_b16 v[10:11], v217 offset:20480
	ds_read_b64_tr_b16 v[12:13], v218 offset:20480
	v_add_f32_e32 v0, 0, v14
	v_fmamk_f32 v15, v88, 0x3e0293ee, v151
	v_mfma_f32_32x32x16_bf16 v[32:47], v[2:5], v[96:99], v[32:47]
	ds_read_b64_tr_b16 v[2:3], v219 offset:20480
	ds_read_b64_tr_b16 v[4:5], v220 offset:20480
	s_waitcnt lgkmcnt(4)
	v_mfma_f32_32x32x16_bf16 v[16:31], v[6:9], v[96:99], v[16:31]
	ds_read_b64_tr_b16 v[6:7], v221 offset:20480
	ds_read_b64_tr_b16 v[8:9], v222 offset:20480
	s_waitcnt lgkmcnt(4)
	v_mfma_f32_32x32x16_bf16 v[64:79], v[10:13], v[232:235], v[64:79]
	ds_read_b64_tr_b16 v[10:11], v223 offset:20480
	ds_read_b64_tr_b16 v[12:13], v224 offset:20480
	ds_read_b64_tr_b16 v[236:237], v217 offset:24576
	ds_read_b64_tr_b16 v[238:239], v218 offset:24576
	ds_read_b64_tr_b16 v[240:241], v219 offset:24576
	ds_read_b64_tr_b16 v[242:243], v220 offset:24576
	ds_read_b64_tr_b16 v[96:97], v221 offset:24576
	ds_read_b64_tr_b16 v[98:99], v222 offset:24576
	s_waitcnt lgkmcnt(10)
	v_mfma_f32_32x32x16_bf16 v[48:63], v[2:5], v[232:235], v[48:63]
	ds_read_b128 v[2:5], v226 offset:128
	s_waitcnt lgkmcnt(9)
	v_mfma_f32_32x32x16_bf16 v[32:47], v[6:9], v[232:235], v[32:47]
	v_add_u32_e32 v6, 0xffffffa1, v227
	v_fmamk_f32 v7, v80, 0x3e0293ee, v151
	v_cmp_lt_i32_e32 vcc, 0, v6
	s_waitcnt lgkmcnt(0)
	v_add_f32_e32 v2, v7, v2
	s_and_b64 vcc, s[28:29], vcc
	v_cndmask_b32_e32 v7, v2, v210, vcc
	v_fmamk_f32 v2, v81, 0x3e0293ee, v151
	v_cmp_lt_i32_e32 vcc, -1, v6
	v_add_f32_e32 v2, v2, v3
	s_and_b64 vcc, s[28:29], vcc
	v_cndmask_b32_e32 v8, v2, v210, vcc
	v_fmamk_f32 v2, v82, 0x3e0293ee, v151
	v_cmp_lt_i32_e32 vcc, -2, v6
	v_add_f32_e32 v2, v2, v4
	s_and_b64 vcc, s[28:29], vcc
	v_cndmask_b32_e32 v9, v2, v210, vcc
	v_fmamk_f32 v2, v83, 0x3e0293ee, v151
	v_cmp_lt_i32_e32 vcc, -3, v6
	v_add_f32_e32 v2, v2, v5
	s_and_b64 vcc, s[28:29], vcc
	v_mfma_f32_32x32x16_bf16 v[16:31], v[10:13], v[232:235], v[16:31]
	v_cndmask_b32_e32 v10, v2, v210, vcc
	ds_read_b128 v[2:5], v226 offset:160
	v_fmamk_f32 v11, v84, 0x3e0293ee, v151
	v_cmp_lt_i32_e32 vcc, -8, v6
	s_and_b64 vcc, s[28:29], vcc
	v_fmamk_f32 v83, v92, 0x3e0293ee, v151
	s_waitcnt lgkmcnt(0)
	v_add_f32_e32 v2, v11, v2
	v_cndmask_b32_e32 v11, v2, v210, vcc
	v_fmamk_f32 v2, v85, 0x3e0293ee, v151
	v_cmp_lt_i32_e32 vcc, -9, v6
	v_add_f32_e32 v2, v2, v3
	s_and_b64 vcc, s[28:29], vcc
	v_cndmask_b32_e32 v12, v2, v210, vcc
	v_fmamk_f32 v2, v86, 0x3e0293ee, v151
	v_cmp_lt_i32_e32 vcc, -10, v6
	v_add_f32_e32 v2, v2, v4
	s_and_b64 vcc, s[28:29], vcc
	v_cndmask_b32_e32 v13, v2, v210, vcc
	v_fmamk_f32 v2, v87, 0x3e0293ee, v151
	v_cmp_lt_i32_e32 vcc, -11, v6
	v_add_f32_e32 v2, v2, v5
	s_and_b64 vcc, s[28:29], vcc
	v_cndmask_b32_e32 v14, v2, v210, vcc
	ds_read_b128 v[2:5], v226 offset:192
	v_cmp_lt_i32_e32 vcc, -16, v6
	s_and_b64 vcc, s[28:29], vcc
	v_exp_f32_e32 v101, v7
	v_exp_f32_e32 v105, v8
	s_waitcnt lgkmcnt(0)
; #define MFMA32(a, b, c) __builtin_amdgcn_mfma_f32_32x32x16_bf16((a), (b), (c), 0, 0, 0)
; __device__ __forceinline__ unsigned pk2(float lo, float hi) { const f32x2v v = {lo, hi}; return __builtin_bit_cast(unsigned, __builtin_convertvector(v, bf16x2v)); }
; __device__ __forceinline__ float fast_exp2(float x) { return __builtin_amdgcn_exp2f(x); }
; template <int MODE>
; __device__ __forceinline__ void attn_item(LAS unsigned char* lds, const AttnArgs& a, const int tid) {
;     ...
;                 float ls = 0.f;
; #pragma unroll
;                 for (int i = 0; i < 16; ++i) { const float pv = fast_exp2(s[kt][i]); s[kt][i] = pv; ls += pv; }
;                 l += ls;
; #pragma unroll
;                 for (int ss = 0; ss < 2; ++ss) { u32x4 w;
;                     w.x = pk2(s[kt][8 * ss + 0], s[kt][8 * ss + 1]); w.y = pk2(s[kt][8 * ss + 2], s[kt][8 * ss + 3]);
;                     w.z = pk2(s[kt][8 * ss + 4], s[kt][8 * ss + 5]); w.w = pk2(s[kt][8 * ss + 6], s[kt][8 * ss + 7]);
;                     pf[ss] = __builtin_bit_cast(bf16x8, w); }
; #pragma unroll
;                 for (int jj = 0; jj < 8; ++jj) { const int j = 8 * kt + jj;
;                     o[jj & 3] = MFMA32(vf[j % VD], pf[jj >> 2], o[jj & 3]);
;                     if (j + VD < 16) AT_VLD(j + VD); }
;             }
	v_add_f32_e32 v2, v15, v2
	v_cndmask_b32_e32 v15, v2, v210, vcc
	v_fmamk_f32 v2, v89, 0x3e0293ee, v151
	v_cmp_lt_i32_e32 vcc, s35, v6
	v_add_f32_e32 v2, v2, v3
	s_and_b64 vcc, s[28:29], vcc
	v_cndmask_b32_e32 v80, v2, v210, vcc
	v_fmamk_f32 v2, v90, 0x3e0293ee, v151
	v_cmp_lt_i32_e32 vcc, s61, v6
	v_add_f32_e32 v2, v2, v4
	s_and_b64 vcc, s[28:29], vcc
	v_cndmask_b32_e32 v81, v2, v210, vcc
	v_fmamk_f32 v2, v91, 0x3e0293ee, v151
	v_cmp_lt_i32_e32 vcc, s62, v6
	v_add_f32_e32 v2, v2, v5
	s_and_b64 vcc, s[28:29], vcc
	v_cndmask_b32_e32 v82, v2, v210, vcc
	ds_read_b128 v[2:5], v226 offset:224
	v_cmp_lt_i32_e32 vcc, s63, v6
	s_and_b64 vcc, s[28:29], vcc
	v_exp_f32_e32 v103, v9
	v_exp_f32_e32 v107, v10
	s_waitcnt lgkmcnt(0)
	v_add_f32_e32 v2, v83, v2
	v_cndmask_b32_e32 v83, v2, v210, vcc
	v_fmamk_f32 v2, v93, 0x3e0293ee, v151
	v_cmp_lt_i32_e32 vcc, s40, v6
	v_add_f32_e32 v2, v2, v3
	s_and_b64 vcc, s[28:29], vcc
	v_cndmask_b32_e32 v84, v2, v210, vcc
	v_fmamk_f32 v2, v94, 0x3e0293ee, v151
	v_cmp_lt_i32_e32 vcc, s81, v6
	v_add_f32_e32 v2, v2, v4
	s_and_b64 vcc, s[28:29], vcc
	v_cndmask_b32_e32 v4, v2, v210, vcc
	v_fmamk_f32 v2, v95, 0x3e0293ee, v151
	v_cmp_lt_i32_e32 vcc, s23, v6
	v_add_f32_e32 v2, v2, v5
	s_and_b64 vcc, s[28:29], vcc
	v_cndmask_b32_e32 v5, v2, v210, vcc
	v_pk_add_f32 v[2:3], v[100:101], v[0:1]
	v_exp_f32_e32 v109, v11
	v_pk_add_f32 v[2:3], v[104:105], v[2:3]
	v_exp_f32_e32 v157, v12
	v_pk_add_f32 v[2:3], v[102:103], v[2:3]
	v_exp_f32_e32 v111, v13
	v_pk_add_f32 v[2:3], v[106:107], v[2:3]
	v_exp_f32_e32 v161, v14
	ds_read_b64_tr_b16 v[10:11], v223 offset:24576
	ds_read_b64_tr_b16 v[12:13], v224 offset:24576
	v_exp_f32_e32 v159, v15
	v_pk_add_f32 v[2:3], v[108:109], v[2:3]
	v_exp_f32_e32 v165, v80
	v_pk_add_f32 v[2:3], v[156:157], v[2:3]
	v_exp_f32_e32 v163, v81
	v_pk_add_f32 v[2:3], v[110:111], v[2:3]
	v_exp_f32_e32 v169, v82
	v_pk_add_f32 v[2:3], v[160:161], v[2:3]
	v_cvt_pk_bf16_f32 v6, v101, v105
	v_cvt_pk_bf16_f32 v7, v103, v107
	v_cvt_pk_bf16_f32 v8, v109, v157
	v_cvt_pk_bf16_f32 v9, v111, v161
	v_exp_f32_e32 v167, v83
	v_pk_add_f32 v[2:3], v[158:159], v[2:3]
	v_mfma_f32_32x32x16_bf16 v[64:79], v[236:239], v[6:9], v[64:79]
	v_exp_f32_e32 v173, v84
	v_pk_add_f32 v[2:3], v[164:165], v[2:3]
	v_exp_f32_e32 v171, v4
	v_pk_add_f32 v[2:3], v[162:163], v[2:3]
	v_exp_f32_e32 v155, v5
	v_pk_add_f32 v[2:3], v[168:169], v[2:3]
	ds_read_b64_tr_b16 v[84:85], v217 offset:28672
	ds_read_b64_tr_b16 v[86:87], v218 offset:28672
	v_mfma_f32_32x32x16_bf16 v[48:63], v[240:243], v[6:9], v[48:63]
	ds_read_b64_tr_b16 v[80:81], v219 offset:28672
	ds_read_b64_tr_b16 v[82:83], v220 offset:28672
	v_add_f32_e64 v2, v166, v2
	v_add_f32_e64 v3, v167, v3
	v_cvt_pk_bf16_f32 v4, v167, v173
	v_pk_add_f32 v[2:3], v[172:173], v[2:3]
	v_cvt_pk_bf16_f32 v5, v171, v155
	v_pk_add_f32 v[2:3], v[170:171], v[2:3]
	v_mfma_f32_32x32x16_bf16 v[32:47], v[96:99], v[6:9], v[32:47]
	v_add_f32_e64 v14, v154, v2
	v_add_f32_e64 v15, v155, v3
	v_cvt_pk_bf16_f32 v2, v159, v165
	v_cvt_pk_bf16_f32 v3, v163, v169
	v_add_f32_e32 v154, v14, v15
	s_waitcnt lgkmcnt(4)
	v_mfma_f32_32x32x16_bf16 v[16:31], v[10:13], v[6:9], v[16:31]
	ds_read_b64_tr_b16 v[6:7], v221 offset:28672
	ds_read_b64_tr_b16 v[8:9], v222 offset:28672
	ds_read_b64_tr_b16 v[10:11], v223 offset:28672
	ds_read_b64_tr_b16 v[12:13], v224 offset:28672
	s_waitcnt lgkmcnt(6)
	v_mfma_f32_32x32x16_bf16 v[64:79], v[84:87], v[2:5], v[64:79]
	s_waitcnt lgkmcnt(4)
	v_mfma_f32_32x32x16_bf16 v[48:63], v[80:83], v[2:5], v[48:63]
	s_waitcnt lgkmcnt(2)
	v_mfma_f32_32x32x16_bf16 v[32:47], v[6:9], v[2:5], v[32:47]
	s_waitcnt lgkmcnt(0)
	v_mfma_f32_32x32x16_bf16 v[16:31], v[10:13], v[2:5], v[16:31]

; template <int MODE>
; __device__ __forceinline__ void attn_item(LAS unsigned char* lds, const AttnArgs& a, const int tid) {
;     ...
;         if (t <= tw) {
;             LAS unsigned char* kb = lds + b * 32768;
;             f32x16 s[2];
; #pragma unroll
;             for (int i = 0; i < 16; ++i) { s[0][i] = 0.f; s[1][i] = 0.f; }
;             constexpr int KD = AT_KD, VD = AT_VD;
;             bf16x8 kf[KD];
;     ...
; #pragma unroll
;             for (int i = 0; i < KD; ++i) kf[i] = AT_KLD(i);
; #pragma unroll
;             for (int i = 0; i < 2 * NKS; ++i) { s[i & 1] = MFMA32(kf[i % KD], qf[i >> 1], s[i & 1]); if (i + KD < 2 * NKS) kf[i % KD] = AT_KLD(i + KD); }
;     ...
;             bf16x8 vf[VD];
;     ...
; #pragma unroll
;             for (int j = 0; j < VD; ++j) AT_VLD(j);
;             const float sc = a.sc;
;             const bool diag = (MODE == 1) && (t * 64 + 63 > qw0);
;             const bool near = (MODE == 2) && (t >= tw - 2);
;             bf16x8 pf[2];
; #pragma unroll
;             for (int kt = 0; kt < 2; ++kt) {
;                 if (MODE == 1) {
;                     const LAS float* csb = (const LAS float*)(lds + A_CS) + t * 64 + 32 * kt + 4 * h;
;                     const int mb = t * 64 + 32 * kt + 4 * h - (qw0 + r);
; #pragma unroll
;                     for (int g = 0; g < 4; ++g) { const f32x4 cv = *(const LAS f32x4*)(csb + 8 * g);
; #pragma unroll
;                         for (int e = 0; e < 4; ++e) { float x = fmaf(s[kt][4 * g + e], sc, addc) + cv[e]; if (diag && (mb + 8 * g + e > 0)) x = -1e30f; s[kt][4 * g + e] = x; } }
;                 } else if (MODE == 2) {
;                     if (near) {
;                         const LAS float* lut = (const LAS float*)(lds + A_LUT) + (t * 64 + 32 * kt + 4 * h - (qw0 + r) + 191);
; #pragma unroll
;                         for (int i = 0; i < 16; ++i) s[kt][i] = fmaf(s[kt][i], sc, lut[8 * (i >> 2) + (i & 3)]);
;                     } else {
; #pragma unroll
;                         for (int i = 0; i < 16; ++i) s[kt][i] = fmaf(s[kt][i], sc, addc);
;                     }
;                 } else {
; #pragma unroll
;                     for (int i = 0; i < 16; ++i) s[kt][i] = fmaf(s[kt][i], sc, addc);
;                 }
;                 float ls = 0.f;
; #pragma unroll
;                 for (int i = 0; i < 16; ++i) { const float pv = fast_exp2(s[kt][i]); s[kt][i] = pv; ls += pv; }
;                 l += ls;
.LBB0_65:
	s_cmp_ge_i32 s34, s55
	s_cbranch_scc1 .LBB0_67
	s_cmp_gt_i32 s60, s51
	s_cbranch_scc1 .Lmy_fox_diag2
	ds_read_b128 v[2:5], v198 offset:32768
	ds_read_b128 v[6:9], v198 offset:40960
	ds_read_b128 v[10:13], v199 offset:32768
	ds_read_b128 v[156:159], v199 offset:40960
	s_cmp_gt_i32 s60, s51
	s_waitcnt lgkmcnt(3)
	v_mfma_f32_32x32x16_bf16 v[96:111], v[2:5], v[116:119], 0
	ds_read_b128 v[2:5], v200 offset:32768
	v_subrev_u32_e32 v0, 63, v227
	s_cselect_b64 s[34:35], -1, 0
	s_movk_i32 s62, 0xffef
	s_movk_i32 s63, 0xffee
	s_waitcnt lgkmcnt(3)
	v_mfma_f32_32x32x16_bf16 v[80:95], v[6:9], v[116:119], 0
	ds_read_b128 v[6:9], v200 offset:40960
	s_movk_i32 s97, 0xffed
	s_movk_i32 s40, 0xffe8
	s_movk_i32 s81, 0xffe7
	s_movk_i32 s23, 0xffe6
	s_movk_i32 s0, 0xffe5
	s_waitcnt lgkmcnt(3)
	v_mfma_f32_32x32x16_bf16 v[96:111], v[10:13], v[120:123], v[96:111]
	ds_read_b128 v[10:13], v201 offset:32768
	s_waitcnt lgkmcnt(3)
	v_mfma_f32_32x32x16_bf16 v[80:95], v[156:159], v[120:123], v[80:95]
	ds_read_b128 v[156:159], v201 offset:40960
	s_waitcnt lgkmcnt(3)
	v_mfma_f32_32x32x16_bf16 v[96:111], v[2:5], v[124:127], v[96:111]
	ds_read_b128 v[2:5], v213 offset:32768
	s_waitcnt lgkmcnt(3)
	v_mfma_f32_32x32x16_bf16 v[80:95], v[6:9], v[124:127], v[80:95]
	ds_read_b128 v[6:9], v213 offset:40960
	s_waitcnt lgkmcnt(3)
	v_mfma_f32_32x32x16_bf16 v[96:111], v[10:13], v[128:131], v[96:111]
	ds_read_b128 v[10:13], v214 offset:32768
	s_waitcnt lgkmcnt(3)
	v_mfma_f32_32x32x16_bf16 v[80:95], v[156:159], v[128:131], v[80:95]
	ds_read_b128 v[156:159], v214 offset:40960
	s_waitcnt lgkmcnt(3)
	v_mfma_f32_32x32x16_bf16 v[96:111], v[2:5], v[132:135], v[96:111]
	ds_read_b128 v[2:5], v215 offset:32768
	s_waitcnt lgkmcnt(3)
	v_mfma_f32_32x32x16_bf16 v[80:95], v[6:9], v[132:135], v[80:95]
	ds_read_b128 v[6:9], v215 offset:40960
	s_waitcnt lgkmcnt(3)
	v_mfma_f32_32x32x16_bf16 v[96:111], v[10:13], v[136:139], v[96:111]
	ds_read_b128 v[10:13], v216 offset:32768
	s_waitcnt lgkmcnt(3)
	v_mfma_f32_32x32x16_bf16 v[80:95], v[156:159], v[136:139], v[80:95]
	ds_read_b128 v[156:159], v216 offset:40960
	s_waitcnt lgkmcnt(3)
	v_mfma_f32_32x32x16_bf16 v[96:111], v[2:5], v[140:143], v[96:111]
	s_waitcnt lgkmcnt(2)
	v_mfma_f32_32x32x16_bf16 v[80:95], v[6:9], v[140:143], v[80:95]
	s_waitcnt lgkmcnt(1)
	v_mfma_f32_32x32x16_bf16 v[96:111], v[10:13], v[144:147], v[96:111]
	ds_read_b64_tr_b16 v[6:7], v217 offset:49152
	ds_read_b64_tr_b16 v[8:9], v218 offset:49152
	ds_read_b64_tr_b16 v[10:11], v219 offset:49152
	ds_read_b64_tr_b16 v[12:13], v220 offset:49152
	ds_read_b64_tr_b16 v[2:3], v221 offset:49152
	ds_read_b64_tr_b16 v[4:5], v222 offset:49152
	s_nop 5
	v_fmamk_f32 v14, v96, 0x3e0293ee, v151
	s_waitcnt lgkmcnt(6)
	v_mfma_f32_32x32x16_bf16 v[80:95], v[156:159], v[144:147], v[80:95]
	ds_read_b128 v[156:159], v226 offset:256
	ds_read_b128 v[160:163], v226 offset:288
	v_fmamk_f32 v15, v97, 0x3e0293ee, v151
	v_fmamk_f32 v96, v98, 0x3e0293ee, v151
	s_waitcnt lgkmcnt(1)
	v_add_f32_e32 v14, v14, v156
	v_add_f32_e32 v15, v15, v157
	v_add_f32_e32 v96, v96, v158
	v_mov_b32_e32 v155, v96
	v_fmamk_f32 v96, v99, 0x3e0293ee, v151
	v_add_f32_e32 v96, v96, v159
	v_mov_b32_e32 v156, v96
	v_fmamk_f32 v96, v100, 0x3e0293ee, v151
	s_waitcnt lgkmcnt(0)
	v_add_f32_e32 v96, v96, v160
	v_mov_b32_e32 v157, v96
	v_fmamk_f32 v96, v101, 0x3e0293ee, v151
	v_add_f32_e32 v96, v96, v161
	v_mov_b32_e32 v101, v96
	v_fmamk_f32 v96, v102, 0x3e0293ee, v151
	v_add_f32_e32 v96, v96, v162
	v_mov_b32_e32 v158, v96
	v_fmamk_f32 v96, v103, 0x3e0293ee, v151
	v_add_f32_e32 v96, v96, v163
	v_mov_b32_e32 v103, v96
	ds_read_b128 v[96:99], v226 offset:320
	v_fmamk_f32 v100, v104, 0x3e0293ee, v151
	v_exp_f32_e32 v14, v14
	s_waitcnt lgkmcnt(0)
	v_add_f32_e32 v96, v100, v96
	v_mov_b32_e32 v159, v96
	v_fmamk_f32 v96, v105, 0x3e0293ee, v151
	v_add_f32_e32 v96, v96, v97
	v_mov_b32_e32 v105, v96
	v_fmamk_f32 v96, v106, 0x3e0293ee, v151
	v_add_f32_e32 v96, v96, v98
	v_mov_b32_e32 v161, v96
	v_fmamk_f32 v96, v107, 0x3e0293ee, v151
	v_add_f32_e32 v96, v96, v99
	v_mov_b32_e32 v107, v96
	ds_read_b128 v[96:99], v226 offset:352
	v_fmamk_f32 v100, v108, 0x3e0293ee, v151
	v_exp_f32_e32 v104, v155
	s_waitcnt lgkmcnt(0)
	v_add_f32_e32 v96, v100, v96
	v_fmamk_f32 v100, v109, 0x3e0293ee, v151
	v_add_f32_e32 v97, v100, v97
	v_fmamk_f32 v100, v110, 0x3e0293ee, v151
	v_add_f32_e32 v98, v100, v98
	v_fmamk_f32 v100, v111, 0x3e0293ee, v151
	v_add_f32_e32 v99, v100, v99
	v_exp_f32_e32 v100, v15
	v_exp_f32_e32 v102, v156
	v_exp_f32_e32 v106, v157
	v_exp_f32_e32 v108, v101
	v_exp_f32_e32 v156, v158
	v_exp_f32_e32 v110, v103
	v_exp_f32_e32 v168, v96
	v_exp_f32_e32 v166, v97
	v_exp_f32_e32 v172, v98
	v_exp_f32_e32 v170, v99
	v_cvt_pk_bf16_f32 v96, v14, v100
	v_cvt_pk_bf16_f32 v97, v104, v102
	v_cvt_pk_bf16_f32 v98, v106, v108
	v_cvt_pk_bf16_f32 v99, v156, v110
	v_exp_f32_e32 v160, v159
	v_exp_f32_e32 v158, v105
	v_mfma_f32_32x32x16_bf16 v[64:79], v[6:9], v[96:99], v[64:79]
	ds_read_b64_tr_b16 v[6:7], v223 offset:49152
	ds_read_b64_tr_b16 v[8:9], v224 offset:49152
	v_exp_f32_e32 v164, v161
	v_exp_f32_e32 v162, v107
	v_cvt_pk_bf16_f32 v232, v160, v158
	v_cvt_pk_bf16_f32 v234, v168, v166
	v_cvt_pk_bf16_f32 v235, v172, v170
	v_cvt_pk_bf16_f32 v233, v164, v162
	v_mfma_f32_32x32x16_bf16 v[48:63], v[10:13], v[96:99], v[48:63]
	ds_read_b64_tr_b16 v[10:11], v217 offset:53248
	ds_read_b64_tr_b16 v[12:13], v218 offset:53248
	v_add_f32_e32 v0, 0, v14
	v_fmamk_f32 v15, v88, 0x3e0293ee, v151
	v_mfma_f32_32x32x16_bf16 v[32:47], v[2:5], v[96:99], v[32:47]
	ds_read_b64_tr_b16 v[2:3], v219 offset:53248
	ds_read_b64_tr_b16 v[4:5], v220 offset:53248
	s_waitcnt lgkmcnt(4)
; #define LAS __attribute__((address_space(3)))
; #define MFMA32(a, b, c) __builtin_amdgcn_mfma_f32_32x32x16_bf16((a), (b), (c), 0, 0, 0)
; template <int MODE>
; __device__ __forceinline__ void attn_item(LAS unsigned char* lds, const AttnArgs& a, const int tid) {
;     ...
;             for (int kt = 0; kt < 2; ++kt) {
;                 if (MODE == 1) {
;                     const LAS float* csb = (const LAS float*)(lds + A_CS) + t * 64 + 32 * kt + 4 * h;
;                     const int mb = t * 64 + 32 * kt + 4 * h - (qw0 + r);
; #pragma unroll
;                     for (int g = 0; g < 4; ++g) { const f32x4 cv = *(const LAS f32x4*)(csb + 8 * g);
; #pragma unroll
;                         for (int e = 0; e < 4; ++e) { float x = fmaf(s[kt][4 * g + e], sc, addc) + cv[e]; if (diag && (mb + 8 * g + e > 0)) x = -1e30f; s[kt][4 * g + e] = x; } }
;                 } else if (MODE == 2) {
;                     if (near) {
;                         const LAS float* lut = (const LAS float*)(lds + A_LUT) + (t * 64 + 32 * kt + 4 * h - (qw0 + r) + 191);
; #pragma unroll
;                         for (int i = 0; i < 16; ++i) s[kt][i] = fmaf(s[kt][i], sc, lut[8 * (i >> 2) + (i & 3)]);
;                     } else {
; #pragma unroll
;                         for (int i = 0; i < 16; ++i) s[kt][i] = fmaf(s[kt][i], sc, addc);
;                     }
;                 } else {
; #pragma unroll
;                     for (int i = 0; i < 16; ++i) s[kt][i] = fmaf(s[kt][i], sc, addc);
;                 }
;                 float ls = 0.f;
; #pragma unroll
;                 for (int i = 0; i < 16; ++i) { const float pv = fast_exp2(s[kt][i]); s[kt][i] = pv; ls += pv; }
;                 l += ls;
; #pragma unroll
;                 for (int ss = 0; ss < 2; ++ss) { u32x4 w;
;                     w.x = pk2(s[kt][8 * ss + 0], s[kt][8 * ss + 1]); w.y = pk2(s[kt][8 * ss + 2], s[kt][8 * ss + 3]);
;                     w.z = pk2(s[kt][8 * ss + 4], s[kt][8 * ss + 5]); w.w = pk2(s[kt][8 * ss + 6], s[kt][8 * ss + 7]);
;                     pf[ss] = __builtin_bit_cast(bf16x8, w); }
; #pragma unroll
;                 for (int jj = 0; jj < 8; ++jj) { const int j = 8 * kt + jj;
;                     o[jj & 3] = MFMA32(vf[j % VD], pf[jj >> 2], o[jj & 3]);
;                     if (j + VD < 16) AT_VLD(j + VD); }
;             }
	v_mfma_f32_32x32x16_bf16 v[16:31], v[6:9], v[96:99], v[16:31]
	ds_read_b64_tr_b16 v[6:7], v221 offset:53248
	ds_read_b64_tr_b16 v[8:9], v222 offset:53248
	s_waitcnt lgkmcnt(4)
	v_mfma_f32_32x32x16_bf16 v[64:79], v[10:13], v[232:235], v[64:79]
	ds_read_b64_tr_b16 v[10:11], v223 offset:53248
	ds_read_b64_tr_b16 v[12:13], v224 offset:53248
	ds_read_b64_tr_b16 v[236:237], v217 offset:57344
	ds_read_b64_tr_b16 v[238:239], v218 offset:57344
	ds_read_b64_tr_b16 v[240:241], v219 offset:57344
	ds_read_b64_tr_b16 v[242:243], v220 offset:57344
	ds_read_b64_tr_b16 v[96:97], v221 offset:57344
	ds_read_b64_tr_b16 v[98:99], v222 offset:57344
	s_waitcnt lgkmcnt(10)
	v_mfma_f32_32x32x16_bf16 v[48:63], v[2:5], v[232:235], v[48:63]
	ds_read_b128 v[2:5], v226 offset:384
	s_waitcnt lgkmcnt(9)
	v_mfma_f32_32x32x16_bf16 v[32:47], v[6:9], v[232:235], v[32:47]
	v_subrev_u32_e32 v6, 31, v227
	v_fmamk_f32 v7, v80, 0x3e0293ee, v151
	s_waitcnt lgkmcnt(0)
	v_add_f32_e32 v2, v7, v2
	v_mov_b32_e32 v7, v2
	v_fmamk_f32 v2, v81, 0x3e0293ee, v151
	v_add_f32_e32 v2, v2, v3
	v_mov_b32_e32 v8, v2
	v_fmamk_f32 v2, v82, 0x3e0293ee, v151
	v_add_f32_e32 v2, v2, v4
	v_mov_b32_e32 v9, v2
	v_fmamk_f32 v2, v83, 0x3e0293ee, v151
	v_add_f32_e32 v2, v2, v5
	v_mfma_f32_32x32x16_bf16 v[16:31], v[10:13], v[232:235], v[16:31]
	v_mov_b32_e32 v10, v2
	ds_read_b128 v[2:5], v226 offset:416
	v_fmamk_f32 v11, v84, 0x3e0293ee, v151
	v_fmamk_f32 v83, v92, 0x3e0293ee, v151
	s_waitcnt lgkmcnt(0)
	v_add_f32_e32 v2, v11, v2
	v_mov_b32_e32 v11, v2
	v_fmamk_f32 v2, v85, 0x3e0293ee, v151
	v_add_f32_e32 v2, v2, v3
	v_mov_b32_e32 v12, v2
	v_fmamk_f32 v2, v86, 0x3e0293ee, v151
	v_add_f32_e32 v2, v2, v4
	v_mov_b32_e32 v13, v2
	v_fmamk_f32 v2, v87, 0x3e0293ee, v151
	v_add_f32_e32 v2, v2, v5
	v_mov_b32_e32 v14, v2
	ds_read_b128 v[2:5], v226 offset:448
	v_exp_f32_e32 v101, v7
	v_exp_f32_e32 v105, v8
	s_waitcnt lgkmcnt(0)
	v_add_f32_e32 v2, v15, v2
	v_mov_b32_e32 v15, v2
	v_fmamk_f32 v2, v89, 0x3e0293ee, v151
	v_add_f32_e32 v2, v2, v3
	v_mov_b32_e32 v80, v2
	v_fmamk_f32 v2, v90, 0x3e0293ee, v151
	v_add_f32_e32 v2, v2, v4
	v_mov_b32_e32 v81, v2
	v_fmamk_f32 v2, v91, 0x3e0293ee, v151
	v_add_f32_e32 v2, v2, v5
	v_mov_b32_e32 v82, v2
	ds_read_b128 v[2:5], v226 offset:480
	v_exp_f32_e32 v103, v9
	v_exp_f32_e32 v107, v10
	s_waitcnt lgkmcnt(0)
	v_add_f32_e32 v2, v83, v2
	v_mov_b32_e32 v83, v2
	v_fmamk_f32 v2, v93, 0x3e0293ee, v151
	v_add_f32_e32 v2, v2, v3
	v_mov_b32_e32 v84, v2
	v_fmamk_f32 v2, v94, 0x3e0293ee, v151
	v_add_f32_e32 v2, v2, v4
	v_mov_b32_e32 v4, v2
	v_fmamk_f32 v2, v95, 0x3e0293ee, v151
	v_add_f32_e32 v2, v2, v5
	v_mov_b32_e32 v5, v2
	v_pk_add_f32 v[2:3], v[100:101], v[0:1]
	v_exp_f32_e32 v109, v11
	v_pk_add_f32 v[2:3], v[104:105], v[2:3]
	v_exp_f32_e32 v157, v12
	v_pk_add_f32 v[2:3], v[102:103], v[2:3]
	v_exp_f32_e32 v111, v13
	v_pk_add_f32 v[2:3], v[106:107], v[2:3]
	v_exp_f32_e32 v161, v14
	ds_read_b64_tr_b16 v[10:11], v223 offset:57344
	ds_read_b64_tr_b16 v[12:13], v224 offset:57344
	v_exp_f32_e32 v159, v15
	v_pk_add_f32 v[2:3], v[108:109], v[2:3]
	v_exp_f32_e32 v165, v80
	v_pk_add_f32 v[2:3], v[156:157], v[2:3]
	v_exp_f32_e32 v163, v81
	v_pk_add_f32 v[2:3], v[110:111], v[2:3]
	v_exp_f32_e32 v169, v82
	v_pk_add_f32 v[2:3], v[160:161], v[2:3]
	v_cvt_pk_bf16_f32 v6, v101, v105
	v_cvt_pk_bf16_f32 v7, v103, v107
	v_cvt_pk_bf16_f32 v8, v109, v157
	v_cvt_pk_bf16_f32 v9, v111, v161
	v_exp_f32_e32 v167, v83
	v_pk_add_f32 v[2:3], v[158:159], v[2:3]
	v_mfma_f32_32x32x16_bf16 v[64:79], v[236:239], v[6:9], v[64:79]
	v_exp_f32_e32 v173, v84
	v_pk_add_f32 v[2:3], v[164:165], v[2:3]
	v_exp_f32_e32 v171, v4
	v_pk_add_f32 v[2:3], v[162:163], v[2:3]
	v_exp_f32_e32 v155, v5
	v_pk_add_f32 v[2:3], v[168:169], v[2:3]
	ds_read_b64_tr_b16 v[84:85], v217 offset:61440
	ds_read_b64_tr_b16 v[86:87], v218 offset:61440
	v_mfma_f32_32x32x16_bf16 v[48:63], v[240:243], v[6:9], v[48:63]
	ds_read_b64_tr_b16 v[80:81], v219 offset:61440
	ds_read_b64_tr_b16 v[82:83], v220 offset:61440
	v_add_f32_e64 v2, v166, v2
	v_add_f32_e64 v3, v167, v3
	v_cvt_pk_bf16_f32 v4, v167, v173
	v_pk_add_f32 v[2:3], v[172:173], v[2:3]
	v_cvt_pk_bf16_f32 v5, v171, v155
	v_pk_add_f32 v[2:3], v[170:171], v[2:3]
	v_mfma_f32_32x32x16_bf16 v[32:47], v[96:99], v[6:9], v[32:47]
	v_add_f32_e64 v14, v154, v2
	v_add_f32_e64 v15, v155, v3
	v_cvt_pk_bf16_f32 v2, v159, v165
	v_cvt_pk_bf16_f32 v3, v163, v169
	v_add_f32_e32 v154, v14, v15
	s_waitcnt lgkmcnt(4)
	v_mfma_f32_32x32x16_bf16 v[16:31], v[10:13], v[6:9], v[16:31]
	ds_read_b64_tr_b16 v[6:7], v221 offset:61440
	ds_read_b64_tr_b16 v[8:9], v222 offset:61440
	ds_read_b64_tr_b16 v[10:11], v223 offset:61440
	ds_read_b64_tr_b16 v[12:13], v224 offset:61440
	s_waitcnt lgkmcnt(6)
	v_mfma_f32_32x32x16_bf16 v[64:79], v[84:87], v[2:5], v[64:79]
	s_waitcnt lgkmcnt(4)
	v_mfma_f32_32x32x16_bf16 v[48:63], v[80:83], v[2:5], v[48:63]
	s_waitcnt lgkmcnt(2)
	v_mfma_f32_32x32x16_bf16 v[32:47], v[6:9], v[2:5], v[32:47]
	s_waitcnt lgkmcnt(0)
	v_mfma_f32_32x32x16_bf16 v[16:31], v[10:13], v[2:5], v[16:31]
	s_branch .LBB0_67
; #define LAS __attribute__((address_space(3)))
; #define MFMA32(a, b, c) __builtin_amdgcn_mfma_f32_32x32x16_bf16((a), (b), (c), 0, 0, 0)
; template <int MODE>
; __device__ __forceinline__ void attn_item(LAS unsigned char* lds, const AttnArgs& a, const int tid) {
;     ...
; #pragma unroll
;             for (int i = 0; i < 16; ++i) { s[0][i] = 0.f; s[1][i] = 0.f; }
;             constexpr int KD = AT_KD, VD = AT_VD;
;             bf16x8 kf[KD];
;     ...
; #pragma unroll
;             for (int i = 0; i < KD; ++i) kf[i] = AT_KLD(i);
; #pragma unroll
;             for (int i = 0; i < 2 * NKS; ++i) { s[i & 1] = MFMA32(kf[i % KD], qf[i >> 1], s[i & 1]); if (i + KD < 2 * NKS) kf[i % KD] = AT_KLD(i + KD); }
;     ...
;             bf16x8 vf[VD];
;     ...
; #pragma unroll
;             for (int j = 0; j < VD; ++j) AT_VLD(j);
;             const float sc = a.sc;
;             const bool diag = (MODE == 1) && (t * 64 + 63 > qw0);
;             const bool near = (MODE == 2) && (t >= tw - 2);
;             bf16x8 pf[2];
; #pragma unroll
;             for (int kt = 0; kt < 2; ++kt) {
;                 if (MODE == 1) {
;                     const LAS float* csb = (const LAS float*)(lds + A_CS) + t * 64 + 32 * kt + 4 * h;
;                     const int mb = t * 64 + 32 * kt + 4 * h - (qw0 + r);
; #pragma unroll
;                     for (int g = 0; g < 4; ++g) { const f32x4 cv = *(const LAS f32x4*)(csb + 8 * g);
; #pragma unroll
;                         for (int e = 0; e < 4; ++e) { float x = fmaf(s[kt][4 * g + e], sc, addc) + cv[e]; if (diag && (mb + 8 * g + e > 0)) x = -1e30f; s[kt][4 * g + e] = x; } }
.Lmy_fox_diag2:
	ds_read_b128 v[2:5], v198 offset:32768
	ds_read_b128 v[6:9], v198 offset:40960
	ds_read_b128 v[10:13], v199 offset:32768
	ds_read_b128 v[156:159], v199 offset:40960
	s_cmp_gt_i32 s60, s51
	s_waitcnt lgkmcnt(3)
	v_mfma_f32_32x32x16_bf16 v[96:111], v[2:5], v[116:119], 0
	ds_read_b128 v[2:5], v200 offset:32768
	v_subrev_u32_e32 v0, 63, v227
	s_cselect_b64 s[34:35], -1, 0
	v_cmp_lt_i32_e32 vcc, 0, v0
	s_and_b64 vcc, s[34:35], vcc
	s_movk_i32 s62, 0xffef
	s_movk_i32 s63, 0xffee
	s_waitcnt lgkmcnt(3)
	v_mfma_f32_32x32x16_bf16 v[80:95], v[6:9], v[116:119], 0
	ds_read_b128 v[6:9], v200 offset:40960
	s_movk_i32 s97, 0xffed
	s_movk_i32 s40, 0xffe8
	s_movk_i32 s81, 0xffe7
	s_movk_i32 s23, 0xffe6
	s_movk_i32 s0, 0xffe5
	s_waitcnt lgkmcnt(3)
	v_mfma_f32_32x32x16_bf16 v[96:111], v[10:13], v[120:123], v[96:111]
	ds_read_b128 v[10:13], v201 offset:32768
	s_waitcnt lgkmcnt(3)
	v_mfma_f32_32x32x16_bf16 v[80:95], v[156:159], v[120:123], v[80:95]
	ds_read_b128 v[156:159], v201 offset:40960
	s_waitcnt lgkmcnt(3)
	v_mfma_f32_32x32x16_bf16 v[96:111], v[2:5], v[124:127], v[96:111]
	ds_read_b128 v[2:5], v213 offset:32768
	s_waitcnt lgkmcnt(3)
	v_mfma_f32_32x32x16_bf16 v[80:95], v[6:9], v[124:127], v[80:95]
	ds_read_b128 v[6:9], v213 offset:40960
	s_waitcnt lgkmcnt(3)
	v_mfma_f32_32x32x16_bf16 v[96:111], v[10:13], v[128:131], v[96:111]
	ds_read_b128 v[10:13], v214 offset:32768
	s_waitcnt lgkmcnt(3)
	v_mfma_f32_32x32x16_bf16 v[80:95], v[156:159], v[128:131], v[80:95]
	ds_read_b128 v[156:159], v214 offset:40960
	s_waitcnt lgkmcnt(3)
	v_mfma_f32_32x32x16_bf16 v[96:111], v[2:5], v[132:135], v[96:111]
	ds_read_b128 v[2:5], v215 offset:32768
	s_waitcnt lgkmcnt(3)
	v_mfma_f32_32x32x16_bf16 v[80:95], v[6:9], v[132:135], v[80:95]
	ds_read_b128 v[6:9], v215 offset:40960
	s_waitcnt lgkmcnt(3)
	v_mfma_f32_32x32x16_bf16 v[96:111], v[10:13], v[136:139], v[96:111]
	ds_read_b128 v[10:13], v216 offset:32768
	s_waitcnt lgkmcnt(3)
	v_mfma_f32_32x32x16_bf16 v[80:95], v[156:159], v[136:139], v[80:95]
	ds_read_b128 v[156:159], v216 offset:40960
	s_waitcnt lgkmcnt(3)
	v_mfma_f32_32x32x16_bf16 v[96:111], v[2:5], v[140:143], v[96:111]
	s_waitcnt lgkmcnt(2)
	v_mfma_f32_32x32x16_bf16 v[80:95], v[6:9], v[140:143], v[80:95]
	s_waitcnt lgkmcnt(1)
	v_mfma_f32_32x32x16_bf16 v[96:111], v[10:13], v[144:147], v[96:111]
	ds_read_b64_tr_b16 v[6:7], v217 offset:49152
	ds_read_b64_tr_b16 v[8:9], v218 offset:49152
	ds_read_b64_tr_b16 v[10:11], v219 offset:49152
	ds_read_b64_tr_b16 v[12:13], v220 offset:49152
	ds_read_b64_tr_b16 v[2:3], v221 offset:49152
	ds_read_b64_tr_b16 v[4:5], v222 offset:49152
	s_nop 5
	v_fmamk_f32 v14, v96, 0x3e0293ee, v151
	s_waitcnt lgkmcnt(6)
	v_mfma_f32_32x32x16_bf16 v[80:95], v[156:159], v[144:147], v[80:95]
	ds_read_b128 v[156:159], v226 offset:256
	ds_read_b128 v[160:163], v226 offset:288
	v_fmamk_f32 v15, v97, 0x3e0293ee, v151
	v_fmamk_f32 v96, v98, 0x3e0293ee, v151
	s_waitcnt lgkmcnt(1)
	v_add_f32_e32 v14, v14, v156
	v_cndmask_b32_e32 v14, v14, v210, vcc
	v_cmp_lt_i32_e32 vcc, -1, v0
	v_add_f32_e32 v15, v15, v157
	s_and_b64 vcc, s[34:35], vcc
	v_cndmask_b32_e32 v15, v15, v210, vcc
	v_cmp_lt_i32_e32 vcc, -2, v0
	v_add_f32_e32 v96, v96, v158
	s_and_b64 vcc, s[34:35], vcc
	v_cndmask_b32_e32 v155, v96, v210, vcc
	v_fmamk_f32 v96, v99, 0x3e0293ee, v151
	v_cmp_lt_i32_e32 vcc, -3, v0
	v_add_f32_e32 v96, v96, v159
	s_and_b64 vcc, s[34:35], vcc
	v_cndmask_b32_e32 v156, v96, v210, vcc
	v_fmamk_f32 v96, v100, 0x3e0293ee, v151
	v_cmp_lt_i32_e32 vcc, -8, v0
	s_waitcnt lgkmcnt(0)
	v_add_f32_e32 v96, v96, v160
	s_and_b64 vcc, s[34:35], vcc
	v_cndmask_b32_e32 v157, v96, v210, vcc
	v_fmamk_f32 v96, v101, 0x3e0293ee, v151
	v_cmp_lt_i32_e32 vcc, -9, v0
	v_add_f32_e32 v96, v96, v161
	s_and_b64 vcc, s[34:35], vcc
	v_cndmask_b32_e32 v101, v96, v210, vcc
	v_fmamk_f32 v96, v102, 0x3e0293ee, v151
	v_cmp_lt_i32_e32 vcc, -10, v0
	v_add_f32_e32 v96, v96, v162
	s_and_b64 vcc, s[34:35], vcc
	v_cndmask_b32_e32 v158, v96, v210, vcc
	v_fmamk_f32 v96, v103, 0x3e0293ee, v151
	v_cmp_lt_i32_e32 vcc, -11, v0
	v_add_f32_e32 v96, v96, v163
	s_and_b64 vcc, s[34:35], vcc
	v_cndmask_b32_e32 v103, v96, v210, vcc
	ds_read_b128 v[96:99], v226 offset:320
	v_fmamk_f32 v100, v104, 0x3e0293ee, v151
	v_cmp_lt_i32_e32 vcc, -16, v0
	s_and_b64 vcc, s[34:35], vcc
	v_exp_f32_e32 v14, v14
	s_waitcnt lgkmcnt(0)
	v_add_f32_e32 v96, v100, v96
	v_cndmask_b32_e32 v159, v96, v210, vcc
	v_fmamk_f32 v96, v105, 0x3e0293ee, v151
	v_cmp_lt_i32_e32 vcc, s62, v0
	v_add_f32_e32 v96, v96, v97
	s_and_b64 vcc, s[34:35], vcc
	v_cndmask_b32_e32 v105, v96, v210, vcc
	v_fmamk_f32 v96, v106, 0x3e0293ee, v151
	v_cmp_lt_i32_e32 vcc, s63, v0
	v_add_f32_e32 v96, v96, v98
	s_and_b64 vcc, s[34:35], vcc
	v_cndmask_b32_e32 v161, v96, v210, vcc
	v_fmamk_f32 v96, v107, 0x3e0293ee, v151
	v_cmp_lt_i32_e32 vcc, s97, v0
	v_add_f32_e32 v96, v96, v99
	s_and_b64 vcc, s[34:35], vcc
	v_cndmask_b32_e32 v107, v96, v210, vcc
	ds_read_b128 v[96:99], v226 offset:352
	v_fmamk_f32 v100, v108, 0x3e0293ee, v151
	v_cmp_lt_i32_e32 vcc, s40, v0
	s_and_b64 vcc, s[34:35], vcc
	v_exp_f32_e32 v104, v155
	s_waitcnt lgkmcnt(0)
; #define LAS __attribute__((address_space(3)))
; #define MFMA32(a, b, c) __builtin_amdgcn_mfma_f32_32x32x16_bf16((a), (b), (c), 0, 0, 0)
; __device__ __forceinline__ float fast_exp2(float x) { return __builtin_amdgcn_exp2f(x); }
; template <int MODE>
; __device__ __forceinline__ void attn_item(LAS unsigned char* lds, const AttnArgs& a, const int tid) {
;     ...
;             for (int kt = 0; kt < 2; ++kt) {
;                 if (MODE == 1) {
;                     const LAS float* csb = (const LAS float*)(lds + A_CS) + t * 64 + 32 * kt + 4 * h;
;                     const int mb = t * 64 + 32 * kt + 4 * h - (qw0 + r);
; #pragma unroll
;                     for (int g = 0; g < 4; ++g) { const f32x4 cv = *(const LAS f32x4*)(csb + 8 * g);
; #pragma unroll
;                         for (int e = 0; e < 4; ++e) { float x = fmaf(s[kt][4 * g + e], sc, addc) + cv[e]; if (diag && (mb + 8 * g + e > 0)) x = -1e30f; s[kt][4 * g + e] = x; } }
;                 } else if (MODE == 2) {
;                     if (near) {
;                         const LAS float* lut = (const LAS float*)(lds + A_LUT) + (t * 64 + 32 * kt + 4 * h - (qw0 + r) + 191);
; #pragma unroll
;                         for (int i = 0; i < 16; ++i) s[kt][i] = fmaf(s[kt][i], sc, lut[8 * (i >> 2) + (i & 3)]);
;                     } else {
; #pragma unroll
;                         for (int i = 0; i < 16; ++i) s[kt][i] = fmaf(s[kt][i], sc, addc);
;                     }
;                 } else {
; #pragma unroll
;                     for (int i = 0; i < 16; ++i) s[kt][i] = fmaf(s[kt][i], sc, addc);
;                 }
;                 float ls = 0.f;
; #pragma unroll
;                 for (int i = 0; i < 16; ++i) { const float pv = fast_exp2(s[kt][i]); s[kt][i] = pv; ls += pv; }
;                 l += ls;
; #pragma unroll
;                 for (int ss = 0; ss < 2; ++ss) { u32x4 w;
;                     w.x = pk2(s[kt][8 * ss + 0], s[kt][8 * ss + 1]); w.y = pk2(s[kt][8 * ss + 2], s[kt][8 * ss + 3]);
;                     w.z = pk2(s[kt][8 * ss + 4], s[kt][8 * ss + 5]); w.w = pk2(s[kt][8 * ss + 6], s[kt][8 * ss + 7]);
;                     pf[ss] = __builtin_bit_cast(bf16x8, w); }
; #pragma unroll
;                 for (int jj = 0; jj < 8; ++jj) { const int j = 8 * kt + jj;
;                     o[jj & 3] = MFMA32(vf[j % VD], pf[jj >> 2], o[jj & 3]);
;                     if (j + VD < 16) AT_VLD(j + VD); }
	v_add_f32_e32 v96, v100, v96
	v_cndmask_b32_e32 v96, v96, v210, vcc
	v_fmamk_f32 v100, v109, 0x3e0293ee, v151
	v_cmp_lt_i32_e32 vcc, s81, v0
	v_add_f32_e32 v97, v100, v97
	s_and_b64 vcc, s[34:35], vcc
	v_fmamk_f32 v100, v110, 0x3e0293ee, v151
	v_cndmask_b32_e32 v97, v97, v210, vcc
	v_add_f32_e32 v98, v100, v98
	v_cmp_lt_i32_e32 vcc, s23, v0
	v_fmamk_f32 v100, v111, 0x3e0293ee, v151
	s_and_b64 vcc, s[34:35], vcc
	v_add_f32_e32 v99, v100, v99
	v_exp_f32_e32 v100, v15
	v_exp_f32_e32 v102, v156
	v_exp_f32_e32 v106, v157
	v_exp_f32_e32 v108, v101
	v_exp_f32_e32 v156, v158
	v_exp_f32_e32 v110, v103
	v_cndmask_b32_e32 v98, v98, v210, vcc
	v_cmp_lt_i32_e32 vcc, s0, v0
	s_and_b64 vcc, s[34:35], vcc
	v_exp_f32_e32 v168, v96
	v_cndmask_b32_e32 v99, v99, v210, vcc
	v_exp_f32_e32 v166, v97
	v_exp_f32_e32 v172, v98
	v_exp_f32_e32 v170, v99
	v_cvt_pk_bf16_f32 v96, v14, v100
	v_cvt_pk_bf16_f32 v97, v104, v102
	v_cvt_pk_bf16_f32 v98, v106, v108
	v_cvt_pk_bf16_f32 v99, v156, v110
	v_exp_f32_e32 v160, v159
	v_exp_f32_e32 v158, v105
	v_mfma_f32_32x32x16_bf16 v[64:79], v[6:9], v[96:99], v[64:79]
	ds_read_b64_tr_b16 v[6:7], v223 offset:49152
	ds_read_b64_tr_b16 v[8:9], v224 offset:49152
	v_exp_f32_e32 v164, v161
	v_exp_f32_e32 v162, v107
	v_cvt_pk_bf16_f32 v232, v160, v158
	v_cvt_pk_bf16_f32 v234, v168, v166
	v_cvt_pk_bf16_f32 v235, v172, v170
	v_cvt_pk_bf16_f32 v233, v164, v162
	v_mfma_f32_32x32x16_bf16 v[48:63], v[10:13], v[96:99], v[48:63]
	ds_read_b64_tr_b16 v[10:11], v217 offset:53248
	ds_read_b64_tr_b16 v[12:13], v218 offset:53248
	v_add_f32_e32 v0, 0, v14
	v_fmamk_f32 v15, v88, 0x3e0293ee, v151
	v_mfma_f32_32x32x16_bf16 v[32:47], v[2:5], v[96:99], v[32:47]
	ds_read_b64_tr_b16 v[2:3], v219 offset:53248
	ds_read_b64_tr_b16 v[4:5], v220 offset:53248
	s_waitcnt lgkmcnt(4)
	v_mfma_f32_32x32x16_bf16 v[16:31], v[6:9], v[96:99], v[16:31]
	ds_read_b64_tr_b16 v[6:7], v221 offset:53248
	ds_read_b64_tr_b16 v[8:9], v222 offset:53248
	s_waitcnt lgkmcnt(4)
	v_mfma_f32_32x32x16_bf16 v[64:79], v[10:13], v[232:235], v[64:79]
	ds_read_b64_tr_b16 v[10:11], v223 offset:53248
	ds_read_b64_tr_b16 v[12:13], v224 offset:53248
	ds_read_b64_tr_b16 v[236:237], v217 offset:57344
	ds_read_b64_tr_b16 v[238:239], v218 offset:57344
	ds_read_b64_tr_b16 v[240:241], v219 offset:57344
	ds_read_b64_tr_b16 v[242:243], v220 offset:57344
	ds_read_b64_tr_b16 v[96:97], v221 offset:57344
	ds_read_b64_tr_b16 v[98:99], v222 offset:57344
	s_waitcnt lgkmcnt(10)
	v_mfma_f32_32x32x16_bf16 v[48:63], v[2:5], v[232:235], v[48:63]
	ds_read_b128 v[2:5], v226 offset:384
	s_waitcnt lgkmcnt(9)
	v_mfma_f32_32x32x16_bf16 v[32:47], v[6:9], v[232:235], v[32:47]
	v_subrev_u32_e32 v6, 31, v227
	v_fmamk_f32 v7, v80, 0x3e0293ee, v151
	v_cmp_lt_i32_e32 vcc, 0, v6
	s_waitcnt lgkmcnt(0)
	v_add_f32_e32 v2, v7, v2
	s_and_b64 vcc, s[34:35], vcc
	v_cndmask_b32_e32 v7, v2, v210, vcc
	v_fmamk_f32 v2, v81, 0x3e0293ee, v151
	v_cmp_lt_i32_e32 vcc, -1, v6
	v_add_f32_e32 v2, v2, v3
	s_and_b64 vcc, s[34:35], vcc
	v_cndmask_b32_e32 v8, v2, v210, vcc
	v_fmamk_f32 v2, v82, 0x3e0293ee, v151
	v_cmp_lt_i32_e32 vcc, -2, v6
	v_add_f32_e32 v2, v2, v4
	s_and_b64 vcc, s[34:35], vcc
	v_cndmask_b32_e32 v9, v2, v210, vcc
	v_fmamk_f32 v2, v83, 0x3e0293ee, v151
	v_cmp_lt_i32_e32 vcc, -3, v6
	v_add_f32_e32 v2, v2, v5
	s_and_b64 vcc, s[34:35], vcc
	v_mfma_f32_32x32x16_bf16 v[16:31], v[10:13], v[232:235], v[16:31]
	v_cndmask_b32_e32 v10, v2, v210, vcc
	ds_read_b128 v[2:5], v226 offset:416
	v_fmamk_f32 v11, v84, 0x3e0293ee, v151
	v_cmp_lt_i32_e32 vcc, -8, v6
	s_and_b64 vcc, s[34:35], vcc
	v_fmamk_f32 v83, v92, 0x3e0293ee, v151
	s_waitcnt lgkmcnt(0)
	v_add_f32_e32 v2, v11, v2
	v_cndmask_b32_e32 v11, v2, v210, vcc
	v_fmamk_f32 v2, v85, 0x3e0293ee, v151
	v_cmp_lt_i32_e32 vcc, -9, v6
	v_add_f32_e32 v2, v2, v3
	s_and_b64 vcc, s[34:35], vcc
	v_cndmask_b32_e32 v12, v2, v210, vcc
	v_fmamk_f32 v2, v86, 0x3e0293ee, v151
	v_cmp_lt_i32_e32 vcc, -10, v6
	v_add_f32_e32 v2, v2, v4
	s_and_b64 vcc, s[34:35], vcc
	v_cndmask_b32_e32 v13, v2, v210, vcc
	v_fmamk_f32 v2, v87, 0x3e0293ee, v151
	v_cmp_lt_i32_e32 vcc, -11, v6
	v_add_f32_e32 v2, v2, v5
	s_and_b64 vcc, s[34:35], vcc
	v_cndmask_b32_e32 v14, v2, v210, vcc
	ds_read_b128 v[2:5], v226 offset:448
	v_cmp_lt_i32_e32 vcc, -16, v6
	s_and_b64 vcc, s[34:35], vcc
	v_exp_f32_e32 v101, v7
	v_exp_f32_e32 v105, v8
	s_waitcnt lgkmcnt(0)
; #define MFMA32(a, b, c) __builtin_amdgcn_mfma_f32_32x32x16_bf16((a), (b), (c), 0, 0, 0)
; __device__ __forceinline__ unsigned pk2(float lo, float hi) { const f32x2v v = {lo, hi}; return __builtin_bit_cast(unsigned, __builtin_convertvector(v, bf16x2v)); }
; __device__ __forceinline__ float fast_exp2(float x) { return __builtin_amdgcn_exp2f(x); }
; template <int MODE>
; __device__ __forceinline__ void attn_item(LAS unsigned char* lds, const AttnArgs& a, const int tid) {
;     ...
;                 float ls = 0.f;
; #pragma unroll
;                 for (int i = 0; i < 16; ++i) { const float pv = fast_exp2(s[kt][i]); s[kt][i] = pv; ls += pv; }
;                 l += ls;
; #pragma unroll
;                 for (int ss = 0; ss < 2; ++ss) { u32x4 w;
;                     w.x = pk2(s[kt][8 * ss + 0], s[kt][8 * ss + 1]); w.y = pk2(s[kt][8 * ss + 2], s[kt][8 * ss + 3]);
;                     w.z = pk2(s[kt][8 * ss + 4], s[kt][8 * ss + 5]); w.w = pk2(s[kt][8 * ss + 6], s[kt][8 * ss + 7]);
;                     pf[ss] = __builtin_bit_cast(bf16x8, w); }
; #pragma unroll
;                 for (int jj = 0; jj < 8; ++jj) { const int j = 8 * kt + jj;
;                     o[jj & 3] = MFMA32(vf[j % VD], pf[jj >> 2], o[jj & 3]);
;                     if (j + VD < 16) AT_VLD(j + VD); }
;             }
	v_add_f32_e32 v2, v15, v2
	v_cndmask_b32_e32 v15, v2, v210, vcc
	v_fmamk_f32 v2, v89, 0x3e0293ee, v151
	v_cmp_lt_i32_e32 vcc, s62, v6
	v_add_f32_e32 v2, v2, v3
	s_and_b64 vcc, s[34:35], vcc
	v_cndmask_b32_e32 v80, v2, v210, vcc
	v_fmamk_f32 v2, v90, 0x3e0293ee, v151
	v_cmp_lt_i32_e32 vcc, s63, v6
	v_add_f32_e32 v2, v2, v4
	s_and_b64 vcc, s[34:35], vcc
	v_cndmask_b32_e32 v81, v2, v210, vcc
	v_fmamk_f32 v2, v91, 0x3e0293ee, v151
	v_cmp_lt_i32_e32 vcc, s97, v6
	v_add_f32_e32 v2, v2, v5
	s_and_b64 vcc, s[34:35], vcc
	v_cndmask_b32_e32 v82, v2, v210, vcc
	ds_read_b128 v[2:5], v226 offset:480
	v_cmp_lt_i32_e32 vcc, s40, v6
	s_and_b64 vcc, s[34:35], vcc
	v_exp_f32_e32 v103, v9
	v_exp_f32_e32 v107, v10
	s_waitcnt lgkmcnt(0)
	v_add_f32_e32 v2, v83, v2
	v_cndmask_b32_e32 v83, v2, v210, vcc
	v_fmamk_f32 v2, v93, 0x3e0293ee, v151
	v_cmp_lt_i32_e32 vcc, s81, v6
	v_add_f32_e32 v2, v2, v3
	s_and_b64 vcc, s[34:35], vcc
	v_cndmask_b32_e32 v84, v2, v210, vcc
	v_fmamk_f32 v2, v94, 0x3e0293ee, v151
	v_cmp_lt_i32_e32 vcc, s23, v6
	v_add_f32_e32 v2, v2, v4
	s_and_b64 vcc, s[34:35], vcc
	v_cndmask_b32_e32 v4, v2, v210, vcc
	v_fmamk_f32 v2, v95, 0x3e0293ee, v151
	v_cmp_lt_i32_e32 vcc, s0, v6
	v_add_f32_e32 v2, v2, v5
	s_and_b64 vcc, s[34:35], vcc
	v_cndmask_b32_e32 v5, v2, v210, vcc
	v_pk_add_f32 v[2:3], v[100:101], v[0:1]
	v_exp_f32_e32 v109, v11
	v_pk_add_f32 v[2:3], v[104:105], v[2:3]
	v_exp_f32_e32 v157, v12
	v_pk_add_f32 v[2:3], v[102:103], v[2:3]
	v_exp_f32_e32 v111, v13
	v_pk_add_f32 v[2:3], v[106:107], v[2:3]
	v_exp_f32_e32 v161, v14
	ds_read_b64_tr_b16 v[10:11], v223 offset:57344
	ds_read_b64_tr_b16 v[12:13], v224 offset:57344
	v_exp_f32_e32 v159, v15
	v_pk_add_f32 v[2:3], v[108:109], v[2:3]
	v_exp_f32_e32 v165, v80
	v_pk_add_f32 v[2:3], v[156:157], v[2:3]
	v_exp_f32_e32 v163, v81
	v_pk_add_f32 v[2:3], v[110:111], v[2:3]
	v_exp_f32_e32 v169, v82
	v_pk_add_f32 v[2:3], v[160:161], v[2:3]
	v_cvt_pk_bf16_f32 v6, v101, v105
	v_cvt_pk_bf16_f32 v7, v103, v107
	v_cvt_pk_bf16_f32 v8, v109, v157
	v_cvt_pk_bf16_f32 v9, v111, v161
	v_exp_f32_e32 v167, v83
	v_pk_add_f32 v[2:3], v[158:159], v[2:3]
	v_mfma_f32_32x32x16_bf16 v[64:79], v[236:239], v[6:9], v[64:79]
	v_exp_f32_e32 v173, v84
	v_pk_add_f32 v[2:3], v[164:165], v[2:3]
	v_exp_f32_e32 v171, v4
	v_pk_add_f32 v[2:3], v[162:163], v[2:3]
	v_exp_f32_e32 v155, v5
	v_pk_add_f32 v[2:3], v[168:169], v[2:3]
	ds_read_b64_tr_b16 v[84:85], v217 offset:61440
	ds_read_b64_tr_b16 v[86:87], v218 offset:61440
	v_mfma_f32_32x32x16_bf16 v[48:63], v[240:243], v[6:9], v[48:63]
	ds_read_b64_tr_b16 v[80:81], v219 offset:61440
	ds_read_b64_tr_b16 v[82:83], v220 offset:61440
	v_add_f32_e64 v2, v166, v2
	v_add_f32_e64 v3, v167, v3
	v_cvt_pk_bf16_f32 v4, v167, v173
	v_pk_add_f32 v[2:3], v[172:173], v[2:3]
	v_cvt_pk_bf16_f32 v5, v171, v155
	v_pk_add_f32 v[2:3], v[170:171], v[2:3]
	v_mfma_f32_32x32x16_bf16 v[32:47], v[96:99], v[6:9], v[32:47]
	v_add_f32_e64 v14, v154, v2
	v_add_f32_e64 v15, v155, v3
	v_cvt_pk_bf16_f32 v2, v159, v165
	v_cvt_pk_bf16_f32 v3, v163, v169
	v_add_f32_e32 v154, v14, v15
	s_waitcnt lgkmcnt(4)
	v_mfma_f32_32x32x16_bf16 v[16:31], v[10:13], v[6:9], v[16:31]
	ds_read_b64_tr_b16 v[6:7], v221 offset:61440
	ds_read_b64_tr_b16 v[8:9], v222 offset:61440
	ds_read_b64_tr_b16 v[10:11], v223 offset:61440
	ds_read_b64_tr_b16 v[12:13], v224 offset:61440
	s_waitcnt lgkmcnt(6)
	v_mfma_f32_32x32x16_bf16 v[64:79], v[84:87], v[2:5], v[64:79]
	s_waitcnt lgkmcnt(4)
	v_mfma_f32_32x32x16_bf16 v[48:63], v[80:83], v[2:5], v[48:63]
	s_waitcnt lgkmcnt(2)
	v_mfma_f32_32x32x16_bf16 v[32:47], v[6:9], v[2:5], v[32:47]
	s_waitcnt lgkmcnt(0)
	v_mfma_f32_32x32x16_bf16 v[16:31], v[10:13], v[2:5], v[16:31]

; __device__ __forceinline__ unsigned cvt_pk_bf16(float lo, float hi) { unsigned r; asm volatile("v_cvt_pk_bf16_f32 %0, %1, %2" : "=v"(r) : "v"(lo), "v"(hi)); return r; }
; #define EO_LOAD(rr, slot) do { const size_t o_ = (size_t)(row0 + ((rr) >> 2) * 128 + ((rr) & 3) * 16) * DM + col0; _Pragma("unroll") for (int q_ = 0; q_ < 4; ++q_) xr[slot][q_] = *(const f32x4*)(Xin + o_ + (q_ >> 1) * 128 + (q_ & 1) * 16); } while (0)
;     __device__ __forceinline__ void operator()(const f32x4 (&acc)[2][2][4][2], const pg8::Unit& u, int wr, int wc, int fr, int fq) const {
;     ...
;         const int row0 = u.pm * 256 + wr * 64 + fr, col0 = u.pn * 256 + wc * 32 + 4 * fq;
;         f32x4 xr[3][4];
;     ...
;         EO_LOAD(0, 0); EO_LOAD(1, 1);
; #pragma unroll
;         for (int rr = 0; rr < 8; ++rr) { const int ai = rr >> 2, m = rr & 3, row = row0 + ai * 128 + m * 16; const size_t o = (size_t)row * DM + col0; float s = 0.f;
;             if (rr + 2 < 8) EO_LOAD(rr + 2, (rr + 2) % 3);
; #pragma unroll
;             for (int q = 0; q < 4; ++q) { const int bj = q >> 1, n = q & 1; const size_t idx = o + bj * 128 + n * 16; const f32x4 v = xr[rr % 3][q] + acc[ai][bj][m][n]; *(f32x4*)(Out + idx) = v;
;                 if (ssq) { u32x2 w; w.x = cvt_pk_bf16(v[0], v[1]); w.y = cvt_pk_bf16(v[2], v[3]); *(u32x2*)(HBo + idx) = w; s += (v[0] * v[0] + v[1] * v[1]) + (v[2] * v[2] + v[3] * v[3]); } }
;             if (ssq) { s += __shfl_xor(s, 16); s += __shfl_xor(s, 32); if (fq == 0) atomicAdd(ssq + row, s); } }
.LBB0_124:
	s_lshl_b32 s6, s39, 8
	v_mov_b32_e32 v130, v179
	v_mov_b32_e32 v215, v181
	v_and_b32_e32 v220, 1, v215
	v_mul_u32_u24_e32 v220, 24, v220
	s_add_i32 s6, s6, s44
	v_readlane_b32 s72, v251, 6
	v_add_u32_e32 v190, s6, v130
	s_lshl_b32 s6, s38, 8
	s_or_b32 s6, s6, s45
	v_lshl_add_u32 v192, v215, 2, s6
	v_ashrrev_i32_e32 v191, 31, v190
	v_ashrrev_i32_e32 v193, 31, v192
	v_lshlrev_b64 v[130:131], 13, v[190:191]
	v_lshl_add_u64 v[130:131], s[10:11], 0, v[130:131]
	v_lshlrev_b64 v[132:133], 2, v[192:193]
	v_add_u32_e32 v196, 16, v190
	v_lshl_add_u64 v[130:131], v[130:131], 0, v[132:133]
	v_ashrrev_i32_e32 v197, 31, v196
	global_load_dwordx4 v[198:201], v[130:131], off
	global_load_dwordx4 v[170:173], v[130:131], off offset:64
	global_load_dwordx4 v[166:169], v[130:131], off offset:512
	global_load_dwordx4 v[162:165], v[130:131], off offset:576
	v_lshlrev_b64 v[130:131], 13, v[196:197]
	v_lshl_add_u64 v[130:131], s[10:11], 0, v[130:131]
	v_lshl_add_u64 v[130:131], v[130:131], 0, v[132:133]
	v_add_u32_e32 v194, 32, v190
	global_load_dwordx4 v[158:161], v[130:131], off
	global_load_dwordx4 v[154:157], v[130:131], off offset:64
	global_load_dwordx4 v[150:153], v[130:131], off offset:512
	global_load_dwordx4 v[146:149], v[130:131], off offset:576
	v_lshlrev_b64 v[130:131], 11, v[190:191]
	v_ashrrev_i32_e32 v195, 31, v194
	v_lshl_add_u64 v[218:219], v[130:131], 0, v[192:193]
	v_lshlrev_b64 v[130:131], 13, v[194:195]
	v_lshl_add_u64 v[130:131], s[10:11], 0, v[130:131]
	v_lshl_add_u64 v[130:131], v[130:131], 0, v[132:133]
	global_load_dwordx4 v[142:145], v[130:131], off
	global_load_dwordx4 v[138:141], v[130:131], off offset:64
	global_load_dwordx4 v[134:137], v[130:131], off offset:512
	s_nop 0
	global_load_dwordx4 v[130:133], v[130:131], off offset:576
	v_readlane_b32 s86, v251, 20
	v_readlane_b32 s87, v251, 21
	v_mov_b32_e32 v216, 0
	s_andn2_b64 vcc, exec, s[12:13]
	v_readlane_b32 s73, v251, 7
	v_readlane_b32 s74, v251, 8
	v_readlane_b32 s75, v251, 9
	v_readlane_b32 s76, v251, 10
	v_readlane_b32 s77, v251, 11
	v_readlane_b32 s78, v251, 12
	v_readlane_b32 s79, v251, 13
	v_readlane_b32 s80, v251, 14
	v_readlane_b32 s81, v251, 15
	v_readlane_b32 s82, v251, 16
	v_readlane_b32 s83, v251, 17
	v_readlane_b32 s84, v251, 18
	v_readlane_b32 s85, v251, 19
	s_waitcnt vmcnt(8)
	v_pk_add_f32 v[128:129], v[128:129], v[200:201]
	v_cndmask_b32_e64 v200, 0, 1, s[12:13]
	v_pk_add_f32 v[126:127], v[126:127], v[198:199]
	v_lshl_add_u64 v[198:199], v[218:219], 2, s[86:87]
	v_cmp_ne_u32_e64 s[6:7], 1, v200
	v_lshl_add_u64 v[200:201], v[218:219], 1, s[22:23]
	global_store_dwordx4 v[198:199], v[126:129], off
	s_cbranch_vccnz .LBB0_126
.LBB0_126:
	v_pk_add_f32 v[124:125], v[124:125], v[172:173]
	v_pk_add_f32 v[122:123], v[122:123], v[170:171]
	s_and_b64 vcc, exec, s[6:7]
	global_store_dwordx4 v[198:199], v[122:125], off offset:64
	s_cbranch_vccnz .LBB0_128
.LBB0_128:
	v_readlane_b32 s54, v250, 12
	v_pk_add_f32 v[120:121], v[120:121], v[168:169]
	v_pk_add_f32 v[118:119], v[118:119], v[166:167]
	s_and_b64 vcc, exec, s[6:7]
	v_readlane_b32 s55, v250, 13
	global_store_dwordx4 v[198:199], v[118:121], off offset:512
	s_cbranch_vccnz .LBB0_130
.LBB0_130:
	v_pk_add_f32 v[116:117], v[116:117], v[164:165]
	v_pk_add_f32 v[114:115], v[114:115], v[162:163]
	s_and_b64 vcc, exec, s[6:7]
	s_mov_b64 s[36:37], 0
	global_store_dwordx4 v[198:199], v[114:117], off offset:576
	s_cbranch_vccnz .LBB0_132
	s_mov_b64 s[36:37], s[14:15]
.LBB0_132:
	s_cmp_eq_u64 s[36:37], 0
	v_cmp_eq_u32_e64 s[8:9], 0, v215
	s_cbranch_scc1 .LBB0_136
	v_mul_f32_e32 v216, v126, v126
	v_fmac_f32_e32 v216, v127, v127
	v_fmac_f32_e32 v216, v128, v128
	v_fmac_f32_e32 v216, v129, v129
	v_fmac_f32_e32 v216, v122, v122
	v_fmac_f32_e32 v216, v123, v123
	v_fmac_f32_e32 v216, v124, v124
	v_fmac_f32_e32 v216, v125, v125
	v_fmac_f32_e32 v216, v118, v118
	v_fmac_f32_e32 v216, v119, v119
	v_fmac_f32_e32 v216, v120, v120
	v_fmac_f32_e32 v216, v121, v121
	v_fmac_f32_e32 v216, v114, v114
	v_fmac_f32_e32 v216, v115, v115
	v_fmac_f32_e32 v216, v116, v116
	v_fmac_f32_e32 v216, v117, v117
	v_cvt_pk_bf16_f32 v126, v126, v127
	v_cvt_pk_bf16_f32 v127, v128, v129
	v_cvt_pk_bf16_f32 v128, v122, v123
	v_cvt_pk_bf16_f32 v129, v124, v125
	v_cvt_pk_bf16_f32 v118, v118, v119
	v_cvt_pk_bf16_f32 v119, v120, v121
	v_cvt_pk_bf16_f32 v120, v114, v115
	v_cvt_pk_bf16_f32 v121, v116, v117
	v_add_co_u32_e32 v200, vcc, v220, v200
	s_nop 1
	v_addc_co_u32_e32 v201, vcc, 0, v201, vcc
	v_permlane16_swap_b32_e32 v126, v128
	v_permlane16_swap_b32_e32 v127, v129
	v_permlane16_swap_b32_e32 v118, v120
	v_permlane16_swap_b32_e32 v119, v121
	global_store_dwordx4 v[200:201], v[126:129], off
	global_store_dwordx4 v[200:201], v[118:121], off offset:256
	v_and_b32_e32 v115, 64, v204
	v_xor_b32_e32 v114, 16, v204
	v_add_u32_e32 v115, 64, v115
	v_cmp_lt_i32_e32 vcc, v114, v115
	v_xor_b32_e32 v116, 32, v204
	s_nop 0
	v_cndmask_b32_e32 v114, v204, v114, vcc
	v_lshlrev_b32_e32 v114, 2, v114
	ds_bpermute_b32 v114, v114, v216
	v_cmp_lt_i32_e32 vcc, v116, v115
	s_waitcnt lgkmcnt(0)
	v_add_f32_e32 v114, v216, v114
	v_cndmask_b32_e32 v115, v204, v116, vcc
	v_lshlrev_b32_e32 v115, 2, v115
	ds_bpermute_b32 v115, v115, v114
	s_and_saveexec_b64 s[38:39], s[8:9]
	s_cbranch_execz .LBB0_135
	v_lshl_add_u64 v[116:117], v[190:191], 2, s[36:37]
	s_waitcnt lgkmcnt(0)
	v_add_f32_e32 v114, v114, v115
	global_atomic_add_f32 v[116:117], v114, off

; #define EO_LOAD(rr, slot) do { const size_t o_ = (size_t)(row0 + ((rr) >> 2) * 128 + ((rr) & 3) * 16) * DM + col0; _Pragma("unroll") for (int q_ = 0; q_ < 4; ++q_) xr[slot][q_] = *(const f32x4*)(Xin + o_ + (q_ >> 1) * 128 + (q_ & 1) * 16); } while (0)
;     __device__ __forceinline__ void operator()(const f32x4 (&acc)[2][2][4][2], const pg8::Unit& u, int wr, int wc, int fr, int fq) const {
;     ...
;         EO_LOAD(0, 0); EO_LOAD(1, 1);
; #pragma unroll
;         for (int rr = 0; rr < 8; ++rr) { const int ai = rr >> 2, m = rr & 3, row = row0 + ai * 128 + m * 16; const size_t o = (size_t)row * DM + col0; float s = 0.f;
;             if (rr + 2 < 8) EO_LOAD(rr + 2, (rr + 2) % 3);
.LBB0_136:
	v_add_u32_e32 v162, 48, v190
	v_ashrrev_i32_e32 v163, 31, v162
	s_waitcnt lgkmcnt(0)
	v_lshlrev_b64 v[114:115], 13, v[162:163]
	v_lshl_add_u64 v[114:115], s[10:11], 0, v[114:115]
	v_lshl_add_u64 v[114:115], v[192:193], 2, v[114:115]
	global_load_dwordx4 v[126:129], v[114:115], off
	global_load_dwordx4 v[122:125], v[114:115], off offset:64
	global_load_dwordx4 v[118:121], v[114:115], off offset:512
	s_nop 0
	global_load_dwordx4 v[114:117], v[114:115], off offset:576
	v_lshlrev_b64 v[164:165], 11, v[196:197]
	v_readlane_b32 s72, v251, 6
	v_lshl_add_u64 v[166:167], v[164:165], 0, v[192:193]
	v_readlane_b32 s86, v251, 20
	v_readlane_b32 s87, v251, 21
	s_cmp_eq_u64 s[12:13], 0
	s_cbranch_scc1 .Lmy_eo_r1_n
	s_waitcnt vmcnt(15)
	s_branch .Lmy_eo_r1_d

; __device__ __forceinline__ unsigned cvt_pk_bf16(float lo, float hi) { unsigned r; asm volatile("v_cvt_pk_bf16_f32 %0, %1, %2" : "=v"(r) : "v"(lo), "v"(hi)); return r; }
; #define EO_LOAD(rr, slot) do { const size_t o_ = (size_t)(row0 + ((rr) >> 2) * 128 + ((rr) & 3) * 16) * DM + col0; _Pragma("unroll") for (int q_ = 0; q_ < 4; ++q_) xr[slot][q_] = *(const f32x4*)(Xin + o_ + (q_ >> 1) * 128 + (q_ & 1) * 16); } while (0)
;     __device__ __forceinline__ void operator()(const f32x4 (&acc)[2][2][4][2], const pg8::Unit& u, int wr, int wc, int fr, int fq) const {
;     ...
;         for (int rr = 0; rr < 8; ++rr) { const int ai = rr >> 2, m = rr & 3, row = row0 + ai * 128 + m * 16; const size_t o = (size_t)row * DM + col0; float s = 0.f;
;             if (rr + 2 < 8) EO_LOAD(rr + 2, (rr + 2) % 3);
; #pragma unroll
;             for (int q = 0; q < 4; ++q) { const int bj = q >> 1, n = q & 1; const size_t idx = o + bj * 128 + n * 16; const f32x4 v = xr[rr % 3][q] + acc[ai][bj][m][n]; *(f32x4*)(Out + idx) = v;
;                 if (ssq) { u32x2 w; w.x = cvt_pk_bf16(v[0], v[1]); w.y = cvt_pk_bf16(v[2], v[3]); *(u32x2*)(HBo + idx) = w; s += (v[0] * v[0] + v[1] * v[1]) + (v[2] * v[2] + v[3] * v[3]); } }
;             if (ssq) { s += __shfl_xor(s, 16); s += __shfl_xor(s, 32); if (fq == 0) atomicAdd(ssq + row, s); } }
.Lmy_eo_r1_d:
	v_pk_add_f32 v[112:113], v[112:113], v[160:161]
	v_pk_add_f32 v[110:111], v[110:111], v[158:159]
	v_lshl_add_u64 v[160:161], v[166:167], 2, s[86:87]
	v_mov_b32_e32 v164, 0
	s_and_b64 vcc, exec, s[6:7]
	v_lshl_add_u64 v[158:159], v[166:167], 1, s[22:23]
	v_readlane_b32 s73, v251, 7
	v_readlane_b32 s74, v251, 8
	v_readlane_b32 s75, v251, 9
	v_readlane_b32 s76, v251, 10
	v_readlane_b32 s77, v251, 11
	v_readlane_b32 s78, v251, 12
	v_readlane_b32 s79, v251, 13
	v_readlane_b32 s80, v251, 14
	v_readlane_b32 s81, v251, 15
	v_readlane_b32 s82, v251, 16
	v_readlane_b32 s83, v251, 17
	v_readlane_b32 s84, v251, 18
	v_readlane_b32 s85, v251, 19
	global_store_dwordx4 v[160:161], v[110:113], off
	s_cbranch_vccnz .LBB0_138
.LBB0_138:
	v_pk_add_f32 v[108:109], v[108:109], v[156:157]
	v_pk_add_f32 v[106:107], v[106:107], v[154:155]
	s_and_b64 vcc, exec, s[6:7]
	global_store_dwordx4 v[160:161], v[106:109], off offset:64
	s_cbranch_vccnz .LBB0_140
.LBB0_140:
	v_pk_add_f32 v[104:105], v[104:105], v[152:153]
	v_pk_add_f32 v[102:103], v[102:103], v[150:151]
	s_and_b64 vcc, exec, s[6:7]
	global_store_dwordx4 v[160:161], v[102:105], off offset:512
	s_cbranch_vccnz .LBB0_142
.LBB0_142:
	v_pk_add_f32 v[100:101], v[100:101], v[148:149]
	v_pk_add_f32 v[98:99], v[98:99], v[146:147]
	s_and_b64 vcc, exec, s[6:7]
	s_mov_b64 s[36:37], 0
	global_store_dwordx4 v[160:161], v[98:101], off offset:576
	s_cbranch_vccnz .LBB0_144
	s_mov_b64 s[36:37], s[14:15]
.LBB0_144:
	s_cmp_eq_u64 s[36:37], 0
	s_cbranch_scc1 .LBB0_148
	v_mul_f32_e32 v164, v110, v110
	v_fmac_f32_e32 v164, v111, v111
	v_fmac_f32_e32 v164, v112, v112
	v_fmac_f32_e32 v164, v113, v113
	v_fmac_f32_e32 v164, v106, v106
	v_fmac_f32_e32 v164, v107, v107
	v_fmac_f32_e32 v164, v108, v108
	v_fmac_f32_e32 v164, v109, v109
	v_fmac_f32_e32 v164, v102, v102
	v_fmac_f32_e32 v164, v103, v103
	v_fmac_f32_e32 v164, v104, v104
	v_fmac_f32_e32 v164, v105, v105
	v_fmac_f32_e32 v164, v98, v98
	v_fmac_f32_e32 v164, v99, v99
	v_fmac_f32_e32 v164, v100, v100
	v_fmac_f32_e32 v164, v101, v101
	v_cvt_pk_bf16_f32 v110, v110, v111
	v_cvt_pk_bf16_f32 v111, v112, v113
	v_cvt_pk_bf16_f32 v112, v106, v107
	v_cvt_pk_bf16_f32 v113, v108, v109
	v_cvt_pk_bf16_f32 v102, v102, v103
	v_cvt_pk_bf16_f32 v103, v104, v105
	v_cvt_pk_bf16_f32 v104, v98, v99
	v_cvt_pk_bf16_f32 v105, v100, v101
	v_add_co_u32_e32 v158, vcc, v220, v158
	s_nop 1
	v_addc_co_u32_e32 v159, vcc, 0, v159, vcc
	v_permlane16_swap_b32_e32 v110, v112
	v_permlane16_swap_b32_e32 v111, v113
	v_permlane16_swap_b32_e32 v102, v104
	v_permlane16_swap_b32_e32 v103, v105
	global_store_dwordx4 v[158:159], v[110:113], off
	global_store_dwordx4 v[158:159], v[102:105], off offset:256
	v_and_b32_e32 v99, 64, v204
	v_xor_b32_e32 v98, 16, v204
	v_add_u32_e32 v99, 64, v99
	v_cmp_lt_i32_e32 vcc, v98, v99
	v_xor_b32_e32 v100, 32, v204
	s_nop 0
	v_cndmask_b32_e32 v98, v204, v98, vcc
	v_lshlrev_b32_e32 v98, 2, v98
	ds_bpermute_b32 v98, v98, v164
	v_cmp_lt_i32_e32 vcc, v100, v99
	s_waitcnt lgkmcnt(0)
	v_add_f32_e32 v98, v164, v98
	v_cndmask_b32_e32 v99, v204, v100, vcc
	v_lshlrev_b32_e32 v99, 2, v99
	ds_bpermute_b32 v99, v99, v98
	s_and_saveexec_b64 s[38:39], s[8:9]
	s_cbranch_execz .LBB0_147
	v_lshl_add_u64 v[100:101], v[190:191], 2, s[36:37]
	s_waitcnt lgkmcnt(0)
	v_add_f32_e32 v98, v98, v99
	global_atomic_add_f32 v[100:101], v98, off offset:64

; __device__ __forceinline__ unsigned cvt_pk_bf16(float lo, float hi) { unsigned r; asm volatile("v_cvt_pk_bf16_f32 %0, %1, %2" : "=v"(r) : "v"(lo), "v"(hi)); return r; }
; #define EO_LOAD(rr, slot) do { const size_t o_ = (size_t)(row0 + ((rr) >> 2) * 128 + ((rr) & 3) * 16) * DM + col0; _Pragma("unroll") for (int q_ = 0; q_ < 4; ++q_) xr[slot][q_] = *(const f32x4*)(Xin + o_ + (q_ >> 1) * 128 + (q_ & 1) * 16); } while (0)
;     __device__ __forceinline__ void operator()(const f32x4 (&acc)[2][2][4][2], const pg8::Unit& u, int wr, int wc, int fr, int fq) const {
;     ...
;         EO_LOAD(0, 0); EO_LOAD(1, 1);
; #pragma unroll
;         for (int rr = 0; rr < 8; ++rr) { const int ai = rr >> 2, m = rr & 3, row = row0 + ai * 128 + m * 16; const size_t o = (size_t)row * DM + col0; float s = 0.f;
;             if (rr + 2 < 8) EO_LOAD(rr + 2, (rr + 2) % 3);
; #pragma unroll
;             for (int q = 0; q < 4; ++q) { const int bj = q >> 1, n = q & 1; const size_t idx = o + bj * 128 + n * 16; const f32x4 v = xr[rr % 3][q] + acc[ai][bj][m][n]; *(f32x4*)(Out + idx) = v;
;                 if (ssq) { u32x2 w; w.x = cvt_pk_bf16(v[0], v[1]); w.y = cvt_pk_bf16(v[2], v[3]); *(u32x2*)(HBo + idx) = w; s += (v[0] * v[0] + v[1] * v[1]) + (v[2] * v[2] + v[3] * v[3]); } }
.LBB0_148:
	v_add_u32_e32 v146, 0x80, v190
	v_ashrrev_i32_e32 v147, 31, v146
	s_waitcnt lgkmcnt(0)
	v_lshlrev_b64 v[98:99], 13, v[146:147]
	v_lshl_add_u64 v[98:99], s[10:11], 0, v[98:99]
	v_lshl_add_u64 v[98:99], v[192:193], 2, v[98:99]
	global_load_dwordx4 v[110:113], v[98:99], off
	global_load_dwordx4 v[106:109], v[98:99], off offset:64
	global_load_dwordx4 v[102:105], v[98:99], off offset:512
	s_nop 0
	global_load_dwordx4 v[98:101], v[98:99], off offset:576
	v_lshlrev_b64 v[148:149], 11, v[194:195]
	v_readlane_b32 s72, v251, 6
	v_lshl_add_u64 v[150:151], v[148:149], 0, v[192:193]
	v_readlane_b32 s86, v251, 20
	v_readlane_b32 s87, v251, 21
	s_cmp_eq_u64 s[12:13], 0
	s_cbranch_scc1 .Lmy_eo_r2_n
	s_waitcnt vmcnt(22)
	s_branch .Lmy_eo_r2_d

; __device__ __forceinline__ unsigned cvt_pk_bf16(float lo, float hi) { unsigned r; asm volatile("v_cvt_pk_bf16_f32 %0, %1, %2" : "=v"(r) : "v"(lo), "v"(hi)); return r; }
; #define EO_LOAD(rr, slot) do { const size_t o_ = (size_t)(row0 + ((rr) >> 2) * 128 + ((rr) & 3) * 16) * DM + col0; _Pragma("unroll") for (int q_ = 0; q_ < 4; ++q_) xr[slot][q_] = *(const f32x4*)(Xin + o_ + (q_ >> 1) * 128 + (q_ & 1) * 16); } while (0)
;     __device__ __forceinline__ void operator()(const f32x4 (&acc)[2][2][4][2], const pg8::Unit& u, int wr, int wc, int fr, int fq) const {
;     ...
;         for (int rr = 0; rr < 8; ++rr) { const int ai = rr >> 2, m = rr & 3, row = row0 + ai * 128 + m * 16; const size_t o = (size_t)row * DM + col0; float s = 0.f;
;             if (rr + 2 < 8) EO_LOAD(rr + 2, (rr + 2) % 3);
; #pragma unroll
;             for (int q = 0; q < 4; ++q) { const int bj = q >> 1, n = q & 1; const size_t idx = o + bj * 128 + n * 16; const f32x4 v = xr[rr % 3][q] + acc[ai][bj][m][n]; *(f32x4*)(Out + idx) = v;
;                 if (ssq) { u32x2 w; w.x = cvt_pk_bf16(v[0], v[1]); w.y = cvt_pk_bf16(v[2], v[3]); *(u32x2*)(HBo + idx) = w; s += (v[0] * v[0] + v[1] * v[1]) + (v[2] * v[2] + v[3] * v[3]); } }
;             if (ssq) { s += __shfl_xor(s, 16); s += __shfl_xor(s, 32); if (fq == 0) atomicAdd(ssq + row, s); } }
.Lmy_eo_r2_d:
	v_pk_add_f32 v[96:97], v[96:97], v[144:145]
	v_pk_add_f32 v[94:95], v[94:95], v[142:143]
	v_lshl_add_u64 v[144:145], v[150:151], 2, s[86:87]
	v_mov_b32_e32 v148, 0
	s_and_b64 vcc, exec, s[6:7]
	v_lshl_add_u64 v[142:143], v[150:151], 1, s[22:23]
	v_readlane_b32 s73, v251, 7
	v_readlane_b32 s74, v251, 8
	v_readlane_b32 s75, v251, 9
	v_readlane_b32 s76, v251, 10
	v_readlane_b32 s77, v251, 11
	v_readlane_b32 s78, v251, 12
	v_readlane_b32 s79, v251, 13
	v_readlane_b32 s80, v251, 14
	v_readlane_b32 s81, v251, 15
	v_readlane_b32 s82, v251, 16
	v_readlane_b32 s83, v251, 17
	v_readlane_b32 s84, v251, 18
	v_readlane_b32 s85, v251, 19
	global_store_dwordx4 v[144:145], v[94:97], off
	s_cbranch_vccnz .LBB0_150
.LBB0_150:
	v_pk_add_f32 v[92:93], v[92:93], v[140:141]
	v_pk_add_f32 v[90:91], v[90:91], v[138:139]
	s_and_b64 vcc, exec, s[6:7]
	global_store_dwordx4 v[144:145], v[90:93], off offset:64
	s_cbranch_vccnz .LBB0_152
.LBB0_152:
	v_pk_add_f32 v[88:89], v[88:89], v[136:137]
	v_pk_add_f32 v[86:87], v[86:87], v[134:135]
	s_and_b64 vcc, exec, s[6:7]
	global_store_dwordx4 v[144:145], v[86:89], off offset:512
	s_cbranch_vccnz .LBB0_154
.LBB0_154:
	v_pk_add_f32 v[84:85], v[84:85], v[132:133]
	v_pk_add_f32 v[82:83], v[82:83], v[130:131]
	s_and_b64 vcc, exec, s[6:7]
	s_mov_b64 s[36:37], 0
	global_store_dwordx4 v[144:145], v[82:85], off offset:576
	s_cbranch_vccnz .LBB0_156
	s_mov_b64 s[36:37], s[14:15]
.LBB0_156:
	s_cmp_eq_u64 s[36:37], 0
	s_cbranch_scc1 .LBB0_160
	v_mul_f32_e32 v148, v94, v94
	v_fmac_f32_e32 v148, v95, v95
	v_fmac_f32_e32 v148, v96, v96
	v_fmac_f32_e32 v148, v97, v97
	v_fmac_f32_e32 v148, v90, v90
	v_fmac_f32_e32 v148, v91, v91
	v_fmac_f32_e32 v148, v92, v92
	v_fmac_f32_e32 v148, v93, v93
	v_fmac_f32_e32 v148, v86, v86
	v_fmac_f32_e32 v148, v87, v87
	v_fmac_f32_e32 v148, v88, v88
	v_fmac_f32_e32 v148, v89, v89
	v_fmac_f32_e32 v148, v82, v82
	v_fmac_f32_e32 v148, v83, v83
	v_fmac_f32_e32 v148, v84, v84
	v_fmac_f32_e32 v148, v85, v85
	v_cvt_pk_bf16_f32 v94, v94, v95
	v_cvt_pk_bf16_f32 v95, v96, v97
	v_cvt_pk_bf16_f32 v96, v90, v91
	v_cvt_pk_bf16_f32 v97, v92, v93
	v_cvt_pk_bf16_f32 v86, v86, v87
	v_cvt_pk_bf16_f32 v87, v88, v89
	v_cvt_pk_bf16_f32 v88, v82, v83
	v_cvt_pk_bf16_f32 v89, v84, v85
	v_add_co_u32_e32 v142, vcc, v220, v142
	s_nop 1
	v_addc_co_u32_e32 v143, vcc, 0, v143, vcc
	v_permlane16_swap_b32_e32 v94, v96
	v_permlane16_swap_b32_e32 v95, v97
	v_permlane16_swap_b32_e32 v86, v88
	v_permlane16_swap_b32_e32 v87, v89
	global_store_dwordx4 v[142:143], v[94:97], off
	global_store_dwordx4 v[142:143], v[86:89], off offset:256
	v_and_b32_e32 v83, 64, v204
	v_xor_b32_e32 v82, 16, v204
	v_add_u32_e32 v83, 64, v83
	v_cmp_lt_i32_e32 vcc, v82, v83
	v_xor_b32_e32 v84, 32, v204
	s_nop 0
	v_cndmask_b32_e32 v82, v204, v82, vcc
	v_lshlrev_b32_e32 v82, 2, v82
	ds_bpermute_b32 v82, v82, v148
	v_cmp_lt_i32_e32 vcc, v84, v83
	s_waitcnt lgkmcnt(0)
	v_add_f32_e32 v82, v148, v82
	v_cndmask_b32_e32 v83, v204, v84, vcc
	v_lshlrev_b32_e32 v83, 2, v83
	ds_bpermute_b32 v83, v83, v82
	s_and_saveexec_b64 s[38:39], s[8:9]
	s_cbranch_execz .LBB0_159
	v_lshl_add_u64 v[84:85], v[190:191], 2, s[36:37]
	s_waitcnt lgkmcnt(0)
	v_add_f32_e32 v82, v82, v83
	global_atomic_add_f32 v[84:85], v82, off offset:128

; __device__ __forceinline__ unsigned cvt_pk_bf16(float lo, float hi) { unsigned r; asm volatile("v_cvt_pk_bf16_f32 %0, %1, %2" : "=v"(r) : "v"(lo), "v"(hi)); return r; }
; #define EO_LOAD(rr, slot) do { const size_t o_ = (size_t)(row0 + ((rr) >> 2) * 128 + ((rr) & 3) * 16) * DM + col0; _Pragma("unroll") for (int q_ = 0; q_ < 4; ++q_) xr[slot][q_] = *(const f32x4*)(Xin + o_ + (q_ >> 1) * 128 + (q_ & 1) * 16); } while (0)
;     __device__ __forceinline__ void operator()(const f32x4 (&acc)[2][2][4][2], const pg8::Unit& u, int wr, int wc, int fr, int fq) const {
;     ...
;         EO_LOAD(0, 0); EO_LOAD(1, 1);
; #pragma unroll
;         for (int rr = 0; rr < 8; ++rr) { const int ai = rr >> 2, m = rr & 3, row = row0 + ai * 128 + m * 16; const size_t o = (size_t)row * DM + col0; float s = 0.f;
;             if (rr + 2 < 8) EO_LOAD(rr + 2, (rr + 2) % 3);
; #pragma unroll
;             for (int q = 0; q < 4; ++q) { const int bj = q >> 1, n = q & 1; const size_t idx = o + bj * 128 + n * 16; const f32x4 v = xr[rr % 3][q] + acc[ai][bj][m][n]; *(f32x4*)(Out + idx) = v;
;                 if (ssq) { u32x2 w; w.x = cvt_pk_bf16(v[0], v[1]); w.y = cvt_pk_bf16(v[2], v[3]); *(u32x2*)(HBo + idx) = w; s += (v[0] * v[0] + v[1] * v[1]) + (v[2] * v[2] + v[3] * v[3]); } }
.LBB0_160:
	v_add_u32_e32 v130, 0x90, v190
	v_ashrrev_i32_e32 v131, 31, v130
	s_waitcnt lgkmcnt(0)
	v_lshlrev_b64 v[82:83], 13, v[130:131]
	v_lshl_add_u64 v[82:83], s[10:11], 0, v[82:83]
	v_lshl_add_u64 v[82:83], v[192:193], 2, v[82:83]
	global_load_dwordx4 v[94:97], v[82:83], off
	global_load_dwordx4 v[90:93], v[82:83], off offset:64
	global_load_dwordx4 v[86:89], v[82:83], off offset:512
	s_nop 0
	global_load_dwordx4 v[82:85], v[82:83], off offset:576
	v_lshlrev_b64 v[132:133], 11, v[162:163]
	v_readlane_b32 s72, v251, 6
	v_lshl_add_u64 v[134:135], v[132:133], 0, v[192:193]
	v_readlane_b32 s86, v251, 20
	v_readlane_b32 s87, v251, 21
	s_cmp_eq_u64 s[12:13], 0
	s_cbranch_scc1 .Lmy_eo_r3_n
	s_waitcnt vmcnt(22)
	s_branch .Lmy_eo_r3_d

; __device__ __forceinline__ unsigned cvt_pk_bf16(float lo, float hi) { unsigned r; asm volatile("v_cvt_pk_bf16_f32 %0, %1, %2" : "=v"(r) : "v"(lo), "v"(hi)); return r; }
; #define EO_LOAD(rr, slot) do { const size_t o_ = (size_t)(row0 + ((rr) >> 2) * 128 + ((rr) & 3) * 16) * DM + col0; _Pragma("unroll") for (int q_ = 0; q_ < 4; ++q_) xr[slot][q_] = *(const f32x4*)(Xin + o_ + (q_ >> 1) * 128 + (q_ & 1) * 16); } while (0)
;     __device__ __forceinline__ void operator()(const f32x4 (&acc)[2][2][4][2], const pg8::Unit& u, int wr, int wc, int fr, int fq) const {
;     ...
;         for (int rr = 0; rr < 8; ++rr) { const int ai = rr >> 2, m = rr & 3, row = row0 + ai * 128 + m * 16; const size_t o = (size_t)row * DM + col0; float s = 0.f;
;             if (rr + 2 < 8) EO_LOAD(rr + 2, (rr + 2) % 3);
; #pragma unroll
;             for (int q = 0; q < 4; ++q) { const int bj = q >> 1, n = q & 1; const size_t idx = o + bj * 128 + n * 16; const f32x4 v = xr[rr % 3][q] + acc[ai][bj][m][n]; *(f32x4*)(Out + idx) = v;
;                 if (ssq) { u32x2 w; w.x = cvt_pk_bf16(v[0], v[1]); w.y = cvt_pk_bf16(v[2], v[3]); *(u32x2*)(HBo + idx) = w; s += (v[0] * v[0] + v[1] * v[1]) + (v[2] * v[2] + v[3] * v[3]); } }
;             if (ssq) { s += __shfl_xor(s, 16); s += __shfl_xor(s, 32); if (fq == 0) atomicAdd(ssq + row, s); } }
.Lmy_eo_r3_d:
	v_pk_add_f32 v[80:81], v[80:81], v[128:129]
	v_pk_add_f32 v[78:79], v[78:79], v[126:127]
	v_lshl_add_u64 v[128:129], v[134:135], 2, s[86:87]
	v_mov_b32_e32 v132, 0
	s_and_b64 vcc, exec, s[6:7]
	v_lshl_add_u64 v[126:127], v[134:135], 1, s[22:23]
	v_readlane_b32 s73, v251, 7
	v_readlane_b32 s74, v251, 8
	v_readlane_b32 s75, v251, 9
	v_readlane_b32 s76, v251, 10
	v_readlane_b32 s77, v251, 11
	v_readlane_b32 s78, v251, 12
	v_readlane_b32 s79, v251, 13
	v_readlane_b32 s80, v251, 14
	v_readlane_b32 s81, v251, 15
	v_readlane_b32 s82, v251, 16
	v_readlane_b32 s83, v251, 17
	v_readlane_b32 s84, v251, 18
	v_readlane_b32 s85, v251, 19
	global_store_dwordx4 v[128:129], v[78:81], off
	s_cbranch_vccnz .LBB0_162
.LBB0_162:
	v_pk_add_f32 v[76:77], v[76:77], v[124:125]
	v_pk_add_f32 v[74:75], v[74:75], v[122:123]
	s_and_b64 vcc, exec, s[6:7]
	global_store_dwordx4 v[128:129], v[74:77], off offset:64
	s_cbranch_vccnz .LBB0_164
.LBB0_164:
	v_pk_add_f32 v[72:73], v[72:73], v[120:121]
	v_pk_add_f32 v[70:71], v[70:71], v[118:119]
	s_and_b64 vcc, exec, s[6:7]
	global_store_dwordx4 v[128:129], v[70:73], off offset:512
	s_cbranch_vccnz .LBB0_166
.LBB0_166:
	v_pk_add_f32 v[68:69], v[68:69], v[116:117]
	v_pk_add_f32 v[66:67], v[66:67], v[114:115]
	s_and_b64 vcc, exec, s[6:7]
	s_mov_b64 s[36:37], 0
	global_store_dwordx4 v[128:129], v[66:69], off offset:576
	s_cbranch_vccnz .LBB0_168
	s_mov_b64 s[36:37], s[14:15]
.LBB0_168:
	s_cmp_eq_u64 s[36:37], 0
	s_cbranch_scc1 .LBB0_172
	v_mul_f32_e32 v132, v78, v78
	v_fmac_f32_e32 v132, v79, v79
	v_fmac_f32_e32 v132, v80, v80
	v_fmac_f32_e32 v132, v81, v81
	v_fmac_f32_e32 v132, v74, v74
	v_fmac_f32_e32 v132, v75, v75
	v_fmac_f32_e32 v132, v76, v76
	v_fmac_f32_e32 v132, v77, v77
	v_fmac_f32_e32 v132, v70, v70
	v_fmac_f32_e32 v132, v71, v71
	v_fmac_f32_e32 v132, v72, v72
	v_fmac_f32_e32 v132, v73, v73
	v_fmac_f32_e32 v132, v66, v66
	v_fmac_f32_e32 v132, v67, v67
	v_fmac_f32_e32 v132, v68, v68
	v_fmac_f32_e32 v132, v69, v69
	v_cvt_pk_bf16_f32 v78, v78, v79
	v_cvt_pk_bf16_f32 v79, v80, v81
	v_cvt_pk_bf16_f32 v80, v74, v75
	v_cvt_pk_bf16_f32 v81, v76, v77
	v_cvt_pk_bf16_f32 v70, v70, v71
	v_cvt_pk_bf16_f32 v71, v72, v73
	v_cvt_pk_bf16_f32 v72, v66, v67
	v_cvt_pk_bf16_f32 v73, v68, v69
	v_add_co_u32_e32 v126, vcc, v220, v126
	s_nop 1
	v_addc_co_u32_e32 v127, vcc, 0, v127, vcc
	v_permlane16_swap_b32_e32 v78, v80
	v_permlane16_swap_b32_e32 v79, v81
	v_permlane16_swap_b32_e32 v70, v72
	v_permlane16_swap_b32_e32 v71, v73
	global_store_dwordx4 v[126:127], v[78:81], off
	global_store_dwordx4 v[126:127], v[70:73], off offset:256
	v_and_b32_e32 v67, 64, v204
	v_xor_b32_e32 v66, 16, v204
	v_add_u32_e32 v67, 64, v67
	v_cmp_lt_i32_e32 vcc, v66, v67
	v_xor_b32_e32 v68, 32, v204
	s_nop 0
	v_cndmask_b32_e32 v66, v204, v66, vcc
	v_lshlrev_b32_e32 v66, 2, v66
	ds_bpermute_b32 v66, v66, v132
	v_cmp_lt_i32_e32 vcc, v68, v67
	s_waitcnt lgkmcnt(0)
	v_add_f32_e32 v66, v132, v66
	v_cndmask_b32_e32 v67, v204, v68, vcc
	v_lshlrev_b32_e32 v67, 2, v67
	ds_bpermute_b32 v67, v67, v66
	s_and_saveexec_b64 s[38:39], s[8:9]
	s_cbranch_execz .LBB0_171
	v_lshl_add_u64 v[68:69], v[190:191], 2, s[36:37]
	s_waitcnt lgkmcnt(0)
	v_add_f32_e32 v66, v66, v67
	global_atomic_add_f32 v[68:69], v66, off offset:192

; __device__ __forceinline__ unsigned cvt_pk_bf16(float lo, float hi) { unsigned r; asm volatile("v_cvt_pk_bf16_f32 %0, %1, %2" : "=v"(r) : "v"(lo), "v"(hi)); return r; }
; #define EO_LOAD(rr, slot) do { const size_t o_ = (size_t)(row0 + ((rr) >> 2) * 128 + ((rr) & 3) * 16) * DM + col0; _Pragma("unroll") for (int q_ = 0; q_ < 4; ++q_) xr[slot][q_] = *(const f32x4*)(Xin + o_ + (q_ >> 1) * 128 + (q_ & 1) * 16); } while (0)
;     __device__ __forceinline__ void operator()(const f32x4 (&acc)[2][2][4][2], const pg8::Unit& u, int wr, int wc, int fr, int fq) const {
;     ...
;         EO_LOAD(0, 0); EO_LOAD(1, 1);
; #pragma unroll
;         for (int rr = 0; rr < 8; ++rr) { const int ai = rr >> 2, m = rr & 3, row = row0 + ai * 128 + m * 16; const size_t o = (size_t)row * DM + col0; float s = 0.f;
;             if (rr + 2 < 8) EO_LOAD(rr + 2, (rr + 2) % 3);
; #pragma unroll
;             for (int q = 0; q < 4; ++q) { const int bj = q >> 1, n = q & 1; const size_t idx = o + bj * 128 + n * 16; const f32x4 v = xr[rr % 3][q] + acc[ai][bj][m][n]; *(f32x4*)(Out + idx) = v;
;                 if (ssq) { u32x2 w; w.x = cvt_pk_bf16(v[0], v[1]); w.y = cvt_pk_bf16(v[2], v[3]); *(u32x2*)(HBo + idx) = w; s += (v[0] * v[0] + v[1] * v[1]) + (v[2] * v[2] + v[3] * v[3]); } }
.LBB0_172:
	v_add_u32_e32 v114, 0xa0, v190
	v_ashrrev_i32_e32 v115, 31, v114
	s_waitcnt lgkmcnt(0)
	v_lshlrev_b64 v[66:67], 13, v[114:115]
	v_lshl_add_u64 v[66:67], s[10:11], 0, v[66:67]
	v_lshl_add_u64 v[66:67], v[192:193], 2, v[66:67]
	global_load_dwordx4 v[78:81], v[66:67], off
	global_load_dwordx4 v[74:77], v[66:67], off offset:64
	global_load_dwordx4 v[70:73], v[66:67], off offset:512
	s_nop 0
	global_load_dwordx4 v[66:69], v[66:67], off offset:576
	v_lshlrev_b64 v[116:117], 11, v[146:147]
	v_readlane_b32 s72, v251, 6
	v_lshl_add_u64 v[118:119], v[116:117], 0, v[192:193]
	v_readlane_b32 s86, v251, 20
	v_readlane_b32 s87, v251, 21
	s_cmp_eq_u64 s[12:13], 0
	s_cbranch_scc1 .Lmy_eo_r4_n
	s_waitcnt vmcnt(22)
	s_branch .Lmy_eo_r4_d

; __device__ __forceinline__ unsigned cvt_pk_bf16(float lo, float hi) { unsigned r; asm volatile("v_cvt_pk_bf16_f32 %0, %1, %2" : "=v"(r) : "v"(lo), "v"(hi)); return r; }
; #define EO_LOAD(rr, slot) do { const size_t o_ = (size_t)(row0 + ((rr) >> 2) * 128 + ((rr) & 3) * 16) * DM + col0; _Pragma("unroll") for (int q_ = 0; q_ < 4; ++q_) xr[slot][q_] = *(const f32x4*)(Xin + o_ + (q_ >> 1) * 128 + (q_ & 1) * 16); } while (0)
;     __device__ __forceinline__ void operator()(const f32x4 (&acc)[2][2][4][2], const pg8::Unit& u, int wr, int wc, int fr, int fq) const {
;     ...
;         for (int rr = 0; rr < 8; ++rr) { const int ai = rr >> 2, m = rr & 3, row = row0 + ai * 128 + m * 16; const size_t o = (size_t)row * DM + col0; float s = 0.f;
;             if (rr + 2 < 8) EO_LOAD(rr + 2, (rr + 2) % 3);
; #pragma unroll
;             for (int q = 0; q < 4; ++q) { const int bj = q >> 1, n = q & 1; const size_t idx = o + bj * 128 + n * 16; const f32x4 v = xr[rr % 3][q] + acc[ai][bj][m][n]; *(f32x4*)(Out + idx) = v;
;                 if (ssq) { u32x2 w; w.x = cvt_pk_bf16(v[0], v[1]); w.y = cvt_pk_bf16(v[2], v[3]); *(u32x2*)(HBo + idx) = w; s += (v[0] * v[0] + v[1] * v[1]) + (v[2] * v[2] + v[3] * v[3]); } }
;             if (ssq) { s += __shfl_xor(s, 16); s += __shfl_xor(s, 32); if (fq == 0) atomicAdd(ssq + row, s); } }
.Lmy_eo_r4_d:
	v_pk_add_f32 v[64:65], v[64:65], v[112:113]
	v_pk_add_f32 v[62:63], v[62:63], v[110:111]
	v_lshl_add_u64 v[112:113], v[118:119], 2, s[86:87]
	v_mov_b32_e32 v116, 0
	s_and_b64 vcc, exec, s[6:7]
	v_lshl_add_u64 v[110:111], v[118:119], 1, s[22:23]
	v_readlane_b32 s73, v251, 7
	v_readlane_b32 s74, v251, 8
	v_readlane_b32 s75, v251, 9
	v_readlane_b32 s76, v251, 10
	v_readlane_b32 s77, v251, 11
	v_readlane_b32 s78, v251, 12
	v_readlane_b32 s79, v251, 13
	v_readlane_b32 s80, v251, 14
	v_readlane_b32 s81, v251, 15
	v_readlane_b32 s82, v251, 16
	v_readlane_b32 s83, v251, 17
	v_readlane_b32 s84, v251, 18
	v_readlane_b32 s85, v251, 19
	global_store_dwordx4 v[112:113], v[62:65], off
	s_cbranch_vccnz .LBB0_174
.LBB0_174:
	v_pk_add_f32 v[60:61], v[60:61], v[108:109]
	v_pk_add_f32 v[58:59], v[58:59], v[106:107]
	s_and_b64 vcc, exec, s[6:7]
	global_store_dwordx4 v[112:113], v[58:61], off offset:64
	s_cbranch_vccnz .LBB0_176
.LBB0_176:
	v_pk_add_f32 v[56:57], v[56:57], v[104:105]
	v_pk_add_f32 v[54:55], v[54:55], v[102:103]
	s_and_b64 vcc, exec, s[6:7]
	global_store_dwordx4 v[112:113], v[54:57], off offset:512
	s_cbranch_vccnz .LBB0_178
.LBB0_178:
	v_pk_add_f32 v[52:53], v[52:53], v[100:101]
	v_pk_add_f32 v[50:51], v[50:51], v[98:99]
	s_and_b64 vcc, exec, s[6:7]
	s_mov_b64 s[36:37], 0
	global_store_dwordx4 v[112:113], v[50:53], off offset:576
	s_cbranch_vccnz .LBB0_180
	s_mov_b64 s[36:37], s[14:15]
.LBB0_180:
	s_cmp_eq_u64 s[36:37], 0
	s_cbranch_scc1 .LBB0_184
	v_mul_f32_e32 v116, v62, v62
	v_fmac_f32_e32 v116, v63, v63
	v_fmac_f32_e32 v116, v64, v64
	v_fmac_f32_e32 v116, v65, v65
	v_fmac_f32_e32 v116, v58, v58
	v_fmac_f32_e32 v116, v59, v59
	v_fmac_f32_e32 v116, v60, v60
	v_fmac_f32_e32 v116, v61, v61
	v_fmac_f32_e32 v116, v54, v54
	v_fmac_f32_e32 v116, v55, v55
	v_fmac_f32_e32 v116, v56, v56
	v_fmac_f32_e32 v116, v57, v57
	v_fmac_f32_e32 v116, v50, v50
	v_fmac_f32_e32 v116, v51, v51
	v_fmac_f32_e32 v116, v52, v52
	v_fmac_f32_e32 v116, v53, v53
	v_cvt_pk_bf16_f32 v62, v62, v63
	v_cvt_pk_bf16_f32 v63, v64, v65
	v_cvt_pk_bf16_f32 v64, v58, v59
	v_cvt_pk_bf16_f32 v65, v60, v61
	v_cvt_pk_bf16_f32 v54, v54, v55
	v_cvt_pk_bf16_f32 v55, v56, v57
	v_cvt_pk_bf16_f32 v56, v50, v51
	v_cvt_pk_bf16_f32 v57, v52, v53
	v_add_co_u32_e32 v110, vcc, v220, v110
	s_nop 1
	v_addc_co_u32_e32 v111, vcc, 0, v111, vcc
	v_permlane16_swap_b32_e32 v62, v64
	v_permlane16_swap_b32_e32 v63, v65
	v_permlane16_swap_b32_e32 v54, v56
	v_permlane16_swap_b32_e32 v55, v57
	global_store_dwordx4 v[110:111], v[62:65], off
	global_store_dwordx4 v[110:111], v[54:57], off offset:256
	v_and_b32_e32 v51, 64, v204
	v_xor_b32_e32 v50, 16, v204
	v_add_u32_e32 v51, 64, v51
	v_cmp_lt_i32_e32 vcc, v50, v51
	v_xor_b32_e32 v52, 32, v204
	s_nop 0
	v_cndmask_b32_e32 v50, v204, v50, vcc
	v_lshlrev_b32_e32 v50, 2, v50
	ds_bpermute_b32 v50, v50, v116
	v_cmp_lt_i32_e32 vcc, v52, v51
	s_waitcnt lgkmcnt(0)
	v_add_f32_e32 v50, v116, v50
	v_cndmask_b32_e32 v51, v204, v52, vcc
	v_lshlrev_b32_e32 v51, 2, v51
	ds_bpermute_b32 v51, v51, v50
	s_and_saveexec_b64 s[38:39], s[8:9]
	s_cbranch_execz .LBB0_183
	v_lshl_add_u64 v[52:53], v[190:191], 2, s[36:37]
	s_waitcnt lgkmcnt(0)
	v_add_f32_e32 v50, v50, v51
	global_atomic_add_f32 v[52:53], v50, off offset:512

; __device__ __forceinline__ unsigned cvt_pk_bf16(float lo, float hi) { unsigned r; asm volatile("v_cvt_pk_bf16_f32 %0, %1, %2" : "=v"(r) : "v"(lo), "v"(hi)); return r; }
; #define EO_LOAD(rr, slot) do { const size_t o_ = (size_t)(row0 + ((rr) >> 2) * 128 + ((rr) & 3) * 16) * DM + col0; _Pragma("unroll") for (int q_ = 0; q_ < 4; ++q_) xr[slot][q_] = *(const f32x4*)(Xin + o_ + (q_ >> 1) * 128 + (q_ & 1) * 16); } while (0)
;     __device__ __forceinline__ void operator()(const f32x4 (&acc)[2][2][4][2], const pg8::Unit& u, int wr, int wc, int fr, int fq) const {
;     ...
;         EO_LOAD(0, 0); EO_LOAD(1, 1);
; #pragma unroll
;         for (int rr = 0; rr < 8; ++rr) { const int ai = rr >> 2, m = rr & 3, row = row0 + ai * 128 + m * 16; const size_t o = (size_t)row * DM + col0; float s = 0.f;
;             if (rr + 2 < 8) EO_LOAD(rr + 2, (rr + 2) % 3);
; #pragma unroll
;             for (int q = 0; q < 4; ++q) { const int bj = q >> 1, n = q & 1; const size_t idx = o + bj * 128 + n * 16; const f32x4 v = xr[rr % 3][q] + acc[ai][bj][m][n]; *(f32x4*)(Out + idx) = v;
;                 if (ssq) { u32x2 w; w.x = cvt_pk_bf16(v[0], v[1]); w.y = cvt_pk_bf16(v[2], v[3]); *(u32x2*)(HBo + idx) = w; s += (v[0] * v[0] + v[1] * v[1]) + (v[2] * v[2] + v[3] * v[3]); } }
.LBB0_184:
	v_add_u32_e32 v98, 0xb0, v190
	v_ashrrev_i32_e32 v99, 31, v98
	s_waitcnt lgkmcnt(0)
	v_lshlrev_b64 v[50:51], 13, v[98:99]
	v_lshl_add_u64 v[50:51], s[10:11], 0, v[50:51]
	v_lshl_add_u64 v[50:51], v[192:193], 2, v[50:51]
	global_load_dwordx4 v[62:65], v[50:51], off
	global_load_dwordx4 v[58:61], v[50:51], off offset:64
	global_load_dwordx4 v[54:57], v[50:51], off offset:512
	s_nop 0
	global_load_dwordx4 v[50:53], v[50:51], off offset:576
	v_lshlrev_b64 v[100:101], 11, v[130:131]
	v_readlane_b32 s72, v251, 6
	v_lshl_add_u64 v[102:103], v[100:101], 0, v[192:193]
	v_readlane_b32 s86, v251, 20
	v_readlane_b32 s87, v251, 21
	s_cmp_eq_u64 s[12:13], 0
	s_cbranch_scc1 .Lmy_eo_r5_n
	s_waitcnt vmcnt(22)
	s_branch .Lmy_eo_r5_d

; __device__ __forceinline__ unsigned cvt_pk_bf16(float lo, float hi) { unsigned r; asm volatile("v_cvt_pk_bf16_f32 %0, %1, %2" : "=v"(r) : "v"(lo), "v"(hi)); return r; }
; #define EO_LOAD(rr, slot) do { const size_t o_ = (size_t)(row0 + ((rr) >> 2) * 128 + ((rr) & 3) * 16) * DM + col0; _Pragma("unroll") for (int q_ = 0; q_ < 4; ++q_) xr[slot][q_] = *(const f32x4*)(Xin + o_ + (q_ >> 1) * 128 + (q_ & 1) * 16); } while (0)
;     __device__ __forceinline__ void operator()(const f32x4 (&acc)[2][2][4][2], const pg8::Unit& u, int wr, int wc, int fr, int fq) const {
;     ...
;         for (int rr = 0; rr < 8; ++rr) { const int ai = rr >> 2, m = rr & 3, row = row0 + ai * 128 + m * 16; const size_t o = (size_t)row * DM + col0; float s = 0.f;
;             if (rr + 2 < 8) EO_LOAD(rr + 2, (rr + 2) % 3);
; #pragma unroll
;             for (int q = 0; q < 4; ++q) { const int bj = q >> 1, n = q & 1; const size_t idx = o + bj * 128 + n * 16; const f32x4 v = xr[rr % 3][q] + acc[ai][bj][m][n]; *(f32x4*)(Out + idx) = v;
;                 if (ssq) { u32x2 w; w.x = cvt_pk_bf16(v[0], v[1]); w.y = cvt_pk_bf16(v[2], v[3]); *(u32x2*)(HBo + idx) = w; s += (v[0] * v[0] + v[1] * v[1]) + (v[2] * v[2] + v[3] * v[3]); } }
;             if (ssq) { s += __shfl_xor(s, 16); s += __shfl_xor(s, 32); if (fq == 0) atomicAdd(ssq + row, s); } }
.Lmy_eo_r5_d:
	v_pk_add_f32 v[48:49], v[48:49], v[96:97]
	v_pk_add_f32 v[46:47], v[46:47], v[94:95]
	v_lshl_add_u64 v[96:97], v[102:103], 2, s[86:87]
	v_mov_b32_e32 v100, 0
	s_and_b64 vcc, exec, s[6:7]
	v_lshl_add_u64 v[94:95], v[102:103], 1, s[22:23]
	v_readlane_b32 s73, v251, 7
	v_readlane_b32 s74, v251, 8
	v_readlane_b32 s75, v251, 9
	v_readlane_b32 s76, v251, 10
	v_readlane_b32 s77, v251, 11
	v_readlane_b32 s78, v251, 12
	v_readlane_b32 s79, v251, 13
	v_readlane_b32 s80, v251, 14
	v_readlane_b32 s81, v251, 15
	v_readlane_b32 s82, v251, 16
	v_readlane_b32 s83, v251, 17
	v_readlane_b32 s84, v251, 18
	v_readlane_b32 s85, v251, 19
	global_store_dwordx4 v[96:97], v[46:49], off
	s_cbranch_vccnz .LBB0_186
.LBB0_186:
	v_pk_add_f32 v[44:45], v[44:45], v[92:93]
	v_pk_add_f32 v[42:43], v[42:43], v[90:91]
	s_and_b64 vcc, exec, s[6:7]
	global_store_dwordx4 v[96:97], v[42:45], off offset:64
	s_cbranch_vccnz .LBB0_188
.LBB0_188:
	v_pk_add_f32 v[40:41], v[40:41], v[88:89]
	v_pk_add_f32 v[38:39], v[38:39], v[86:87]
	s_and_b64 vcc, exec, s[6:7]
	global_store_dwordx4 v[96:97], v[38:41], off offset:512
	s_cbranch_vccnz .LBB0_190
.LBB0_190:
	v_pk_add_f32 v[36:37], v[36:37], v[84:85]
	v_pk_add_f32 v[34:35], v[34:35], v[82:83]
	s_and_b64 vcc, exec, s[6:7]
	s_mov_b64 s[36:37], 0
	global_store_dwordx4 v[96:97], v[34:37], off offset:576
	s_cbranch_vccnz .LBB0_192
	s_mov_b64 s[36:37], s[14:15]
.LBB0_192:
	s_cmp_eq_u64 s[36:37], 0
	s_cbranch_scc1 .LBB0_196
	v_mul_f32_e32 v100, v46, v46
	v_fmac_f32_e32 v100, v47, v47
	v_fmac_f32_e32 v100, v48, v48
	v_fmac_f32_e32 v100, v49, v49
	v_fmac_f32_e32 v100, v42, v42
	v_fmac_f32_e32 v100, v43, v43
	v_fmac_f32_e32 v100, v44, v44
	v_fmac_f32_e32 v100, v45, v45
	v_fmac_f32_e32 v100, v38, v38
	v_fmac_f32_e32 v100, v39, v39
	v_fmac_f32_e32 v100, v40, v40
	v_fmac_f32_e32 v100, v41, v41
	v_fmac_f32_e32 v100, v34, v34
	v_fmac_f32_e32 v100, v35, v35
	v_fmac_f32_e32 v100, v36, v36
	v_fmac_f32_e32 v100, v37, v37
	v_cvt_pk_bf16_f32 v46, v46, v47
	v_cvt_pk_bf16_f32 v47, v48, v49
	v_cvt_pk_bf16_f32 v48, v42, v43
	v_cvt_pk_bf16_f32 v49, v44, v45
	v_cvt_pk_bf16_f32 v38, v38, v39
	v_cvt_pk_bf16_f32 v39, v40, v41
	v_cvt_pk_bf16_f32 v40, v34, v35
	v_cvt_pk_bf16_f32 v41, v36, v37
	v_add_co_u32_e32 v94, vcc, v220, v94
	s_nop 1
	v_addc_co_u32_e32 v95, vcc, 0, v95, vcc
	v_permlane16_swap_b32_e32 v46, v48
	v_permlane16_swap_b32_e32 v47, v49
	v_permlane16_swap_b32_e32 v38, v40
	v_permlane16_swap_b32_e32 v39, v41
	global_store_dwordx4 v[94:95], v[46:49], off
	global_store_dwordx4 v[94:95], v[38:41], off offset:256
	v_and_b32_e32 v35, 64, v204
	v_xor_b32_e32 v34, 16, v204
	v_add_u32_e32 v35, 64, v35
	v_cmp_lt_i32_e32 vcc, v34, v35
	v_xor_b32_e32 v36, 32, v204
	s_nop 0
	v_cndmask_b32_e32 v34, v204, v34, vcc
	v_lshlrev_b32_e32 v34, 2, v34
	ds_bpermute_b32 v34, v34, v100
	v_cmp_lt_i32_e32 vcc, v36, v35
	s_waitcnt lgkmcnt(0)
	v_add_f32_e32 v34, v100, v34
	v_cndmask_b32_e32 v35, v204, v36, vcc
	v_lshlrev_b32_e32 v35, 2, v35
	ds_bpermute_b32 v35, v35, v34
	s_and_saveexec_b64 s[38:39], s[8:9]
	s_cbranch_execz .LBB0_195
	v_lshl_add_u64 v[36:37], v[190:191], 2, s[36:37]
	s_waitcnt lgkmcnt(0)
	v_add_f32_e32 v34, v34, v35
	global_atomic_add_f32 v[36:37], v34, off offset:576

; __device__ __forceinline__ unsigned cvt_pk_bf16(float lo, float hi) { unsigned r; asm volatile("v_cvt_pk_bf16_f32 %0, %1, %2" : "=v"(r) : "v"(lo), "v"(hi)); return r; }
; #define EO_LOAD(rr, slot) do { const size_t o_ = (size_t)(row0 + ((rr) >> 2) * 128 + ((rr) & 3) * 16) * DM + col0; _Pragma("unroll") for (int q_ = 0; q_ < 4; ++q_) xr[slot][q_] = *(const f32x4*)(Xin + o_ + (q_ >> 1) * 128 + (q_ & 1) * 16); } while (0)
;     __device__ __forceinline__ void operator()(const f32x4 (&acc)[2][2][4][2], const pg8::Unit& u, int wr, int wc, int fr, int fq) const {
;     ...
;         for (int rr = 0; rr < 8; ++rr) { const int ai = rr >> 2, m = rr & 3, row = row0 + ai * 128 + m * 16; const size_t o = (size_t)row * DM + col0; float s = 0.f;
;             if (rr + 2 < 8) EO_LOAD(rr + 2, (rr + 2) % 3);
; #pragma unroll
;             for (int q = 0; q < 4; ++q) { const int bj = q >> 1, n = q & 1; const size_t idx = o + bj * 128 + n * 16; const f32x4 v = xr[rr % 3][q] + acc[ai][bj][m][n]; *(f32x4*)(Out + idx) = v;
;                 if (ssq) { u32x2 w; w.x = cvt_pk_bf16(v[0], v[1]); w.y = cvt_pk_bf16(v[2], v[3]); *(u32x2*)(HBo + idx) = w; s += (v[0] * v[0] + v[1] * v[1]) + (v[2] * v[2] + v[3] * v[3]); } }
.LBB0_196:
	s_waitcnt lgkmcnt(0)
	v_lshlrev_b64 v[34:35], 11, v[114:115]
	v_readlane_b32 s72, v251, 6
	v_lshl_add_u64 v[34:35], v[34:35], 0, v[192:193]
	v_readlane_b32 s86, v251, 20
	v_readlane_b32 s87, v251, 21
	s_cmp_eq_u64 s[12:13], 0
	s_cbranch_scc1 .Lmy_eo_r6_n
	s_waitcnt vmcnt(18)
	s_branch .Lmy_eo_r6_d

; __device__ __forceinline__ unsigned cvt_pk_bf16(float lo, float hi) { unsigned r; asm volatile("v_cvt_pk_bf16_f32 %0, %1, %2" : "=v"(r) : "v"(lo), "v"(hi)); return r; }
; #define EO_LOAD(rr, slot) do { const size_t o_ = (size_t)(row0 + ((rr) >> 2) * 128 + ((rr) & 3) * 16) * DM + col0; _Pragma("unroll") for (int q_ = 0; q_ < 4; ++q_) xr[slot][q_] = *(const f32x4*)(Xin + o_ + (q_ >> 1) * 128 + (q_ & 1) * 16); } while (0)
;     __device__ __forceinline__ void operator()(const f32x4 (&acc)[2][2][4][2], const pg8::Unit& u, int wr, int wc, int fr, int fq) const {
;     ...
;         for (int rr = 0; rr < 8; ++rr) { const int ai = rr >> 2, m = rr & 3, row = row0 + ai * 128 + m * 16; const size_t o = (size_t)row * DM + col0; float s = 0.f;
;             if (rr + 2 < 8) EO_LOAD(rr + 2, (rr + 2) % 3);
; #pragma unroll
;             for (int q = 0; q < 4; ++q) { const int bj = q >> 1, n = q & 1; const size_t idx = o + bj * 128 + n * 16; const f32x4 v = xr[rr % 3][q] + acc[ai][bj][m][n]; *(f32x4*)(Out + idx) = v;
;                 if (ssq) { u32x2 w; w.x = cvt_pk_bf16(v[0], v[1]); w.y = cvt_pk_bf16(v[2], v[3]); *(u32x2*)(HBo + idx) = w; s += (v[0] * v[0] + v[1] * v[1]) + (v[2] * v[2] + v[3] * v[3]); } }
;             if (ssq) { s += __shfl_xor(s, 16); s += __shfl_xor(s, 32); if (fq == 0) atomicAdd(ssq + row, s); } }
.Lmy_eo_r6_d:
	v_pk_add_f32 v[32:33], v[32:33], v[80:81]
	v_pk_add_f32 v[30:31], v[30:31], v[78:79]
	v_lshl_add_u64 v[36:37], v[34:35], 2, s[86:87]
	v_mov_b32_e32 v38, 0
	s_and_b64 vcc, exec, s[6:7]
	v_lshl_add_u64 v[34:35], v[34:35], 1, s[22:23]
	v_readlane_b32 s73, v251, 7
	v_readlane_b32 s74, v251, 8
	v_readlane_b32 s75, v251, 9
	v_readlane_b32 s76, v251, 10
	v_readlane_b32 s77, v251, 11
	v_readlane_b32 s78, v251, 12
	v_readlane_b32 s79, v251, 13
	v_readlane_b32 s80, v251, 14
	v_readlane_b32 s81, v251, 15
	v_readlane_b32 s82, v251, 16
	v_readlane_b32 s83, v251, 17
	v_readlane_b32 s84, v251, 18
	v_readlane_b32 s85, v251, 19
	global_store_dwordx4 v[36:37], v[30:33], off
	s_cbranch_vccnz .LBB0_198
.LBB0_198:
	v_pk_add_f32 v[28:29], v[28:29], v[76:77]
	v_pk_add_f32 v[26:27], v[26:27], v[74:75]
	s_and_b64 vcc, exec, s[6:7]
	global_store_dwordx4 v[36:37], v[26:29], off offset:64
	s_cbranch_vccnz .LBB0_200
.LBB0_200:
	v_pk_add_f32 v[24:25], v[24:25], v[72:73]
	v_pk_add_f32 v[22:23], v[22:23], v[70:71]
	s_and_b64 vcc, exec, s[6:7]
	global_store_dwordx4 v[36:37], v[22:25], off offset:512
	s_cbranch_vccnz .LBB0_202
.LBB0_202:
	v_pk_add_f32 v[20:21], v[20:21], v[68:69]
	v_pk_add_f32 v[18:19], v[18:19], v[66:67]
	s_and_b64 vcc, exec, s[6:7]
	s_mov_b64 s[36:37], 0
	global_store_dwordx4 v[36:37], v[18:21], off offset:576
	s_cbranch_vccnz .LBB0_204
	s_mov_b64 s[36:37], s[14:15]
.LBB0_204:
	s_cmp_eq_u64 s[36:37], 0
	s_cbranch_scc1 .LBB0_208
	v_mul_f32_e32 v38, v30, v30
	v_fmac_f32_e32 v38, v31, v31
	v_fmac_f32_e32 v38, v32, v32
	v_fmac_f32_e32 v38, v33, v33
	v_fmac_f32_e32 v38, v26, v26
	v_fmac_f32_e32 v38, v27, v27
	v_fmac_f32_e32 v38, v28, v28
	v_fmac_f32_e32 v38, v29, v29
	v_fmac_f32_e32 v38, v22, v22
	v_fmac_f32_e32 v38, v23, v23
	v_fmac_f32_e32 v38, v24, v24
	v_fmac_f32_e32 v38, v25, v25
	v_fmac_f32_e32 v38, v18, v18
	v_fmac_f32_e32 v38, v19, v19
	v_fmac_f32_e32 v38, v20, v20
	v_fmac_f32_e32 v38, v21, v21
	v_cvt_pk_bf16_f32 v30, v30, v31
	v_cvt_pk_bf16_f32 v31, v32, v33
	v_cvt_pk_bf16_f32 v32, v26, v27
	v_cvt_pk_bf16_f32 v33, v28, v29
	v_cvt_pk_bf16_f32 v22, v22, v23
	v_cvt_pk_bf16_f32 v23, v24, v25
	v_cvt_pk_bf16_f32 v24, v18, v19
	v_cvt_pk_bf16_f32 v25, v20, v21
	v_add_co_u32_e32 v34, vcc, v220, v34
	s_nop 1
	v_addc_co_u32_e32 v35, vcc, 0, v35, vcc
	v_permlane16_swap_b32_e32 v30, v32
	v_permlane16_swap_b32_e32 v31, v33
	v_permlane16_swap_b32_e32 v22, v24
	v_permlane16_swap_b32_e32 v23, v25
	global_store_dwordx4 v[34:35], v[30:33], off
	global_store_dwordx4 v[34:35], v[22:25], off offset:256
	v_and_b32_e32 v19, 64, v204
	v_xor_b32_e32 v18, 16, v204
	v_add_u32_e32 v19, 64, v19
	v_cmp_lt_i32_e32 vcc, v18, v19
	v_xor_b32_e32 v20, 32, v204
	s_nop 0
	v_cndmask_b32_e32 v18, v204, v18, vcc
	v_lshlrev_b32_e32 v18, 2, v18
	ds_bpermute_b32 v18, v18, v38
	v_cmp_lt_i32_e32 vcc, v20, v19
	s_waitcnt lgkmcnt(0)
	v_add_f32_e32 v18, v38, v18
	v_cndmask_b32_e32 v19, v204, v20, vcc
	v_lshlrev_b32_e32 v19, 2, v19
	ds_bpermute_b32 v19, v19, v18
	s_and_saveexec_b64 s[38:39], s[8:9]
	s_cbranch_execz .LBB0_207
	v_lshl_add_u64 v[20:21], v[190:191], 2, s[36:37]
	s_waitcnt lgkmcnt(0)
	v_add_f32_e32 v18, v18, v19
	global_atomic_add_f32 v[20:21], v18, off offset:640

; __device__ __forceinline__ unsigned cvt_pk_bf16(float lo, float hi) { unsigned r; asm volatile("v_cvt_pk_bf16_f32 %0, %1, %2" : "=v"(r) : "v"(lo), "v"(hi)); return r; }
; #define EO_LOAD(rr, slot) do { const size_t o_ = (size_t)(row0 + ((rr) >> 2) * 128 + ((rr) & 3) * 16) * DM + col0; _Pragma("unroll") for (int q_ = 0; q_ < 4; ++q_) xr[slot][q_] = *(const f32x4*)(Xin + o_ + (q_ >> 1) * 128 + (q_ & 1) * 16); } while (0)
;     __device__ __forceinline__ void operator()(const f32x4 (&acc)[2][2][4][2], const pg8::Unit& u, int wr, int wc, int fr, int fq) const {
;     ...
;         for (int rr = 0; rr < 8; ++rr) { const int ai = rr >> 2, m = rr & 3, row = row0 + ai * 128 + m * 16; const size_t o = (size_t)row * DM + col0; float s = 0.f;
;             if (rr + 2 < 8) EO_LOAD(rr + 2, (rr + 2) % 3);
; #pragma unroll
;             for (int q = 0; q < 4; ++q) { const int bj = q >> 1, n = q & 1; const size_t idx = o + bj * 128 + n * 16; const f32x4 v = xr[rr % 3][q] + acc[ai][bj][m][n]; *(f32x4*)(Out + idx) = v;
;                 if (ssq) { u32x2 w; w.x = cvt_pk_bf16(v[0], v[1]); w.y = cvt_pk_bf16(v[2], v[3]); *(u32x2*)(HBo + idx) = w; s += (v[0] * v[0] + v[1] * v[1]) + (v[2] * v[2] + v[3] * v[3]); } }
.LBB0_208:
	s_waitcnt lgkmcnt(0)
	v_lshlrev_b64 v[18:19], 11, v[98:99]
	v_readlane_b32 s72, v251, 6
	v_lshl_add_u64 v[18:19], v[18:19], 0, v[192:193]
	v_readlane_b32 s86, v251, 20
	v_readlane_b32 s87, v251, 21
	s_cmp_eq_u64 s[12:13], 0
	s_cbranch_scc1 .Lmy_eo_r7_n
	s_waitcnt vmcnt(14)
	s_branch .Lmy_eo_r7_d

; __device__ __forceinline__ unsigned cvt_pk_bf16(float lo, float hi) { unsigned r; asm volatile("v_cvt_pk_bf16_f32 %0, %1, %2" : "=v"(r) : "v"(lo), "v"(hi)); return r; }
; #define EO_LOAD(rr, slot) do { const size_t o_ = (size_t)(row0 + ((rr) >> 2) * 128 + ((rr) & 3) * 16) * DM + col0; _Pragma("unroll") for (int q_ = 0; q_ < 4; ++q_) xr[slot][q_] = *(const f32x4*)(Xin + o_ + (q_ >> 1) * 128 + (q_ & 1) * 16); } while (0)
;     __device__ __forceinline__ void operator()(const f32x4 (&acc)[2][2][4][2], const pg8::Unit& u, int wr, int wc, int fr, int fq) const {
;     ...
;         for (int rr = 0; rr < 8; ++rr) { const int ai = rr >> 2, m = rr & 3, row = row0 + ai * 128 + m * 16; const size_t o = (size_t)row * DM + col0; float s = 0.f;
;             if (rr + 2 < 8) EO_LOAD(rr + 2, (rr + 2) % 3);
; #pragma unroll
;             for (int q = 0; q < 4; ++q) { const int bj = q >> 1, n = q & 1; const size_t idx = o + bj * 128 + n * 16; const f32x4 v = xr[rr % 3][q] + acc[ai][bj][m][n]; *(f32x4*)(Out + idx) = v;
;                 if (ssq) { u32x2 w; w.x = cvt_pk_bf16(v[0], v[1]); w.y = cvt_pk_bf16(v[2], v[3]); *(u32x2*)(HBo + idx) = w; s += (v[0] * v[0] + v[1] * v[1]) + (v[2] * v[2] + v[3] * v[3]); } }
;             if (ssq) { s += __shfl_xor(s, 16); s += __shfl_xor(s, 32); if (fq == 0) atomicAdd(ssq + row, s); } }
.Lmy_eo_r7_d:
	v_pk_add_f32 v[16:17], v[16:17], v[64:65]
	v_pk_add_f32 v[14:15], v[14:15], v[62:63]
	v_lshl_add_u64 v[20:21], v[18:19], 2, s[86:87]
	v_mov_b32_e32 v22, 0
	s_and_b64 vcc, exec, s[6:7]
	v_lshl_add_u64 v[18:19], v[18:19], 1, s[22:23]
	v_readlane_b32 s73, v251, 7
	v_readlane_b32 s74, v251, 8
	v_readlane_b32 s75, v251, 9
	v_readlane_b32 s76, v251, 10
	v_readlane_b32 s77, v251, 11
	v_readlane_b32 s78, v251, 12
	v_readlane_b32 s79, v251, 13
	v_readlane_b32 s80, v251, 14
	v_readlane_b32 s81, v251, 15
	v_readlane_b32 s82, v251, 16
	v_readlane_b32 s83, v251, 17
	v_readlane_b32 s84, v251, 18
	v_readlane_b32 s85, v251, 19
	global_store_dwordx4 v[20:21], v[14:17], off
	s_cbranch_vccnz .LBB0_210
.LBB0_210:
	v_readlane_b32 s20, v250, 9
	v_pk_add_f32 v[12:13], v[12:13], v[60:61]
	v_pk_add_f32 v[10:11], v[10:11], v[58:59]
	s_and_b64 vcc, exec, s[6:7]
	v_readlane_b32 s21, v250, 10
	global_store_dwordx4 v[20:21], v[10:13], off offset:64
	s_cbranch_vccnz .LBB0_212
.LBB0_212:
	v_pk_add_f32 v[8:9], v[8:9], v[56:57]
	v_pk_add_f32 v[6:7], v[6:7], v[54:55]
	s_and_b64 vcc, exec, s[6:7]
	global_store_dwordx4 v[20:21], v[6:9], off offset:512
	s_cbranch_vccnz .LBB0_214
.LBB0_214:
	v_pk_add_f32 v[4:5], v[4:5], v[52:53]
	v_pk_add_f32 v[2:3], v[2:3], v[50:51]
	s_and_b64 vcc, exec, s[6:7]
	s_mov_b64 s[6:7], 0
	global_store_dwordx4 v[20:21], v[2:5], off offset:576
	s_cbranch_vccnz .LBB0_216
	s_mov_b64 s[6:7], s[14:15]
.LBB0_216:
	s_cmp_eq_u64 s[6:7], 0
	s_cbranch_scc1 .LBB0_220
	v_mul_f32_e32 v22, v14, v14
	v_fmac_f32_e32 v22, v15, v15
	v_fmac_f32_e32 v22, v16, v16
	v_fmac_f32_e32 v22, v17, v17
	v_fmac_f32_e32 v22, v10, v10
	v_fmac_f32_e32 v22, v11, v11
	v_fmac_f32_e32 v22, v12, v12
	v_fmac_f32_e32 v22, v13, v13
	v_fmac_f32_e32 v22, v6, v6
	v_fmac_f32_e32 v22, v7, v7
	v_fmac_f32_e32 v22, v8, v8
	v_fmac_f32_e32 v22, v9, v9
	v_fmac_f32_e32 v22, v2, v2
	v_fmac_f32_e32 v22, v3, v3
	v_fmac_f32_e32 v22, v4, v4
	v_fmac_f32_e32 v22, v5, v5
	v_cvt_pk_bf16_f32 v14, v14, v15
	v_cvt_pk_bf16_f32 v15, v16, v17
	v_cvt_pk_bf16_f32 v16, v10, v11
	v_cvt_pk_bf16_f32 v17, v12, v13
	v_cvt_pk_bf16_f32 v6, v6, v7
	v_cvt_pk_bf16_f32 v7, v8, v9
	v_cvt_pk_bf16_f32 v8, v2, v3
	v_cvt_pk_bf16_f32 v9, v4, v5
	v_add_co_u32_e32 v18, vcc, v220, v18
	s_nop 1
	v_addc_co_u32_e32 v19, vcc, 0, v19, vcc
	v_permlane16_swap_b32_e32 v14, v16
	v_permlane16_swap_b32_e32 v15, v17
	v_permlane16_swap_b32_e32 v6, v8
	v_permlane16_swap_b32_e32 v7, v9
	global_store_dwordx4 v[18:19], v[14:17], off
	global_store_dwordx4 v[18:19], v[6:9], off offset:256
	v_and_b32_e32 v3, 64, v204
	v_xor_b32_e32 v2, 16, v204
	v_add_u32_e32 v3, 64, v3
	v_cmp_lt_i32_e32 vcc, v2, v3
	v_xor_b32_e32 v4, 32, v204
	s_nop 0
	v_cndmask_b32_e32 v2, v204, v2, vcc
	v_lshlrev_b32_e32 v2, 2, v2
	ds_bpermute_b32 v2, v2, v22
	v_cmp_lt_i32_e32 vcc, v4, v3
	s_waitcnt lgkmcnt(0)
	v_add_f32_e32 v2, v22, v2
	v_cndmask_b32_e32 v3, v204, v4, vcc
	v_lshlrev_b32_e32 v3, 2, v3
	ds_bpermute_b32 v3, v3, v2
	s_and_saveexec_b64 s[36:37], s[8:9]
	s_cbranch_execz .LBB0_219
	v_lshl_add_u64 v[4:5], v[190:191], 2, s[6:7]
	s_waitcnt lgkmcnt(0)
	v_add_f32_e32 v2, v2, v3
	global_atomic_add_f32 v[4:5], v2, off offset:704

; #define LAS __attribute__((address_space(3)))
;     __device__ __forceinline__ void operator()(const f32x4 (&acc)[2][2][4][2], const pg8::Unit& u, int wr, int wc, int fr, int fq) const {
;     ...
;             for (int m = 0; m < 4; ++m) { bf16_t* rowp = Z + (size_t)(row0 + ai * 128 + m * 16) * ldc + col0;
;                 const float rs = rsv[m];
; #pragma unroll
;                 for (int bj = 0; bj < 2; ++bj) { float mm = rs;
;                     if (W) { const f32x4 pp = *(const LAS f32x4*)(part + (lrow0 + ai * 128 + m * 16) * 8 + bj * 4);
;                         const float tot = (W == 128) ? ((pp[0] + pp[1]) + (pp[2] + pp[3])) : (wc < 2 ? pp[0] + pp[1] : pp[2] + pp[3]);
;                         mm = rs * rsqrtf(tot * rs * rs * invW + EPS); }
;                     f32x4 v0 = acc[ai][bj][m][0] * mm * g0, v1 = acc[ai][bj][m][1] * mm * g1;
.LBB0_315:
	s_lshl_b32 s0, s0, 8
	s_or_b32 s0, s0, s54
	v_lshl_add_u32 v156, v179, 3, s0
	v_mad_u64_u32 v[166:167], s[0:1], v154, s31, 0
	v_mov_b32_e32 v186, v167
	v_ashrrev_i32_e32 v157, 31, v156
	v_mad_u64_u32 v[186:187], s[0:1], v155, s31, v[186:187]
	v_lshl_add_u64 v[156:157], v[156:157], 1, s[42:43]
	v_mov_b32_e32 v167, v186
	v_cvt_pk_bf16_f32 v186, v140, v141
	v_cvt_pk_bf16_f32 v187, v138, v139
	v_cndmask_b32_e64 v138, 0, 1, s[10:11]
	v_lshl_add_u64 v[166:167], v[166:167], 1, v[156:157]
	s_and_b64 vcc, exec, s[6:7]
	v_cmp_ne_u32_e64 s[10:11], 1, v138
	v_cvt_pk_bf16_f32 v188, v168, v169
	v_cvt_pk_bf16_f32 v189, v170, v171
	global_store_dwordx4 v[166:167], v[186:189], off
	s_cbranch_vccnz .LBB0_325
	s_add_i32 s0, 0, 0x20000
	v_add_u32_e32 v138, s0, v184
	ds_read_b128 v[138:141], v138 offset:16
	s_and_b64 vcc, exec, s[10:11]
	s_mov_b64 s[0:1], -1
	s_cbranch_vccnz .LBB0_322
	s_andn2_b64 vcc, exec, s[34:35]
	s_cbranch_vccnz .LBB0_319
	s_waitcnt lgkmcnt(0)
	v_add_f32_e32 v155, v140, v141
	s_mov_b64 s[0:1], 0

; #define LAS __attribute__((address_space(3)))
;     __device__ __forceinline__ void operator()(const f32x4 (&acc)[2][2][4][2], const pg8::Unit& u, int wr, int wc, int fr, int fq) const {
;     ...
;             for (int m = 0; m < 4; ++m) { bf16_t* rowp = Z + (size_t)(row0 + ai * 128 + m * 16) * ldc + col0;
;                 const float rs = rsv[m];
; #pragma unroll
;                 for (int bj = 0; bj < 2; ++bj) { float mm = rs;
;                     if (W) { const f32x4 pp = *(const LAS f32x4*)(part + (lrow0 + ai * 128 + m * 16) * 8 + bj * 4);
;                         const float tot = (W == 128) ? ((pp[0] + pp[1]) + (pp[2] + pp[3])) : (wc < 2 ? pp[0] + pp[1] : pp[2] + pp[3]);
;                         mm = rs * rsqrtf(tot * rs * rs * invW + EPS); }
;                     f32x4 v0 = acc[ai][bj][m][0] * mm * g0, v1 = acc[ai][bj][m][1] * mm * g1;
.LBB0_327:
	v_cvt_pk_bf16_f32 v136, v136, v137
	v_cvt_pk_bf16_f32 v137, v134, v135
	s_and_b64 vcc, exec, s[6:7]
	v_mov_b32_e32 v134, v162
	v_cvt_pk_bf16_f32 v138, v132, v133
	v_cvt_pk_bf16_f32 v139, v130, v131
	global_store_dwordx4 v[166:167], v[136:139], off offset:256
	s_cbranch_vccnz .LBB0_337
	s_add_i32 s0, 0, 0x20000
	v_add_u32_e32 v130, s0, v184
	ds_read_b128 v[130:133], v130 offset:512
	s_and_b64 vcc, exec, s[10:11]
	s_mov_b64 s[0:1], -1
	s_cbranch_vccnz .LBB0_334
	s_andn2_b64 vcc, exec, s[34:35]
	s_cbranch_vccnz .LBB0_331
	s_waitcnt lgkmcnt(0)
	v_add_f32_e32 v134, v132, v133
	s_mov_b64 s[0:1], 0

; #define LAS __attribute__((address_space(3)))
;     __device__ __forceinline__ void operator()(const f32x4 (&acc)[2][2][4][2], const pg8::Unit& u, int wr, int wc, int fr, int fq) const {
;     ...
;             for (int m = 0; m < 4; ++m) { bf16_t* rowp = Z + (size_t)(row0 + ai * 128 + m * 16) * ldc + col0;
;                 const float rs = rsv[m];
; #pragma unroll
;                 for (int bj = 0; bj < 2; ++bj) { float mm = rs;
;                     if (W) { const f32x4 pp = *(const LAS f32x4*)(part + (lrow0 + ai * 128 + m * 16) * 8 + bj * 4);
;                         const float tot = (W == 128) ? ((pp[0] + pp[1]) + (pp[2] + pp[3])) : (wc < 2 ? pp[0] + pp[1] : pp[2] + pp[3]);
;                         mm = rs * rsqrtf(tot * rs * rs * invW + EPS); }
;                     f32x4 v0 = acc[ai][bj][m][0] * mm * g0, v1 = acc[ai][bj][m][1] * mm * g1;
.LBB0_339:
	v_add_u32_e32 v134, 16, v154
	v_mad_i64_i32 v[134:135], s[0:1], v134, s31, 0
	v_lshl_add_u64 v[134:135], v[134:135], 1, v[156:157]
	s_and_b64 vcc, exec, s[6:7]
	v_cvt_pk_bf16_f32 v166, v132, v133
	v_cvt_pk_bf16_f32 v167, v130, v131
	v_cvt_pk_bf16_f32 v168, v138, v139
	v_cvt_pk_bf16_f32 v169, v136, v137
	global_store_dwordx4 v[134:135], v[166:169], off
	s_cbranch_vccnz .LBB0_349
	s_add_i32 s0, 0, 0x20000
	v_add_u32_e32 v130, s0, v184
	ds_read_b128 v[130:133], v130 offset:528
	s_and_b64 vcc, exec, s[10:11]
	s_mov_b64 s[0:1], -1
	s_cbranch_vccnz .LBB0_346
	s_andn2_b64 vcc, exec, s[34:35]
	s_cbranch_vccnz .LBB0_343
	s_waitcnt lgkmcnt(0)
	v_add_f32_e32 v136, v132, v133
	s_mov_b64 s[0:1], 0

; #define LAS __attribute__((address_space(3)))
;     __device__ __forceinline__ void operator()(const f32x4 (&acc)[2][2][4][2], const pg8::Unit& u, int wr, int wc, int fr, int fq) const {
;     ...
;             for (int m = 0; m < 4; ++m) { bf16_t* rowp = Z + (size_t)(row0 + ai * 128 + m * 16) * ldc + col0;
;                 const float rs = rsv[m];
; #pragma unroll
;                 for (int bj = 0; bj < 2; ++bj) { float mm = rs;
;                     if (W) { const f32x4 pp = *(const LAS f32x4*)(part + (lrow0 + ai * 128 + m * 16) * 8 + bj * 4);
;                         const float tot = (W == 128) ? ((pp[0] + pp[1]) + (pp[2] + pp[3])) : (wc < 2 ? pp[0] + pp[1] : pp[2] + pp[3]);
;                         mm = rs * rsqrtf(tot * rs * rs * invW + EPS); }
;                     f32x4 v0 = acc[ai][bj][m][0] * mm * g0, v1 = acc[ai][bj][m][1] * mm * g1;
.LBB0_351:
	v_cvt_pk_bf16_f32 v128, v128, v129
	v_cvt_pk_bf16_f32 v129, v126, v127
	s_and_b64 vcc, exec, s[6:7]
	v_mov_b32_e32 v126, v160
	v_cvt_pk_bf16_f32 v130, v124, v125
	v_cvt_pk_bf16_f32 v131, v122, v123
	global_store_dwordx4 v[134:135], v[128:131], off offset:256
	s_cbranch_vccnz .LBB0_361
	s_add_i32 s0, 0, 0x20000
	v_add_u32_e32 v122, s0, v184
	ds_read_b128 v[122:125], v122 offset:1024
	s_and_b64 vcc, exec, s[10:11]
	s_mov_b64 s[0:1], -1
	s_cbranch_vccnz .LBB0_358
	s_andn2_b64 vcc, exec, s[34:35]
	s_cbranch_vccnz .LBB0_355
	s_waitcnt lgkmcnt(0)
	v_add_f32_e32 v126, v124, v125
	s_mov_b64 s[0:1], 0

; #define LAS __attribute__((address_space(3)))
;     __device__ __forceinline__ void operator()(const f32x4 (&acc)[2][2][4][2], const pg8::Unit& u, int wr, int wc, int fr, int fq) const {
;     ...
;             for (int m = 0; m < 4; ++m) { bf16_t* rowp = Z + (size_t)(row0 + ai * 128 + m * 16) * ldc + col0;
;                 const float rs = rsv[m];
; #pragma unroll
;                 for (int bj = 0; bj < 2; ++bj) { float mm = rs;
;                     if (W) { const f32x4 pp = *(const LAS f32x4*)(part + (lrow0 + ai * 128 + m * 16) * 8 + bj * 4);
;                         const float tot = (W == 128) ? ((pp[0] + pp[1]) + (pp[2] + pp[3])) : (wc < 2 ? pp[0] + pp[1] : pp[2] + pp[3]);
;                         mm = rs * rsqrtf(tot * rs * rs * invW + EPS); }
;                     f32x4 v0 = acc[ai][bj][m][0] * mm * g0, v1 = acc[ai][bj][m][1] * mm * g1;
.LBB0_363:
	v_add_u32_e32 v126, 32, v154
	v_mad_i64_i32 v[126:127], s[0:1], v126, s31, 0
	v_lshl_add_u64 v[126:127], v[126:127], 1, v[156:157]
	s_and_b64 vcc, exec, s[6:7]
	v_cvt_pk_bf16_f32 v132, v124, v125
	v_cvt_pk_bf16_f32 v133, v122, v123
	v_cvt_pk_bf16_f32 v134, v130, v131
	v_cvt_pk_bf16_f32 v135, v128, v129
	global_store_dwordx4 v[126:127], v[132:135], off
	s_cbranch_vccnz .LBB0_373
	s_add_i32 s0, 0, 0x20000
	v_add_u32_e32 v122, s0, v184
	ds_read_b128 v[122:125], v122 offset:1040
	s_and_b64 vcc, exec, s[10:11]
	s_mov_b64 s[0:1], -1
	s_cbranch_vccnz .LBB0_370
	s_andn2_b64 vcc, exec, s[34:35]
	s_cbranch_vccnz .LBB0_367
	s_waitcnt lgkmcnt(0)
	v_add_f32_e32 v128, v124, v125
	s_mov_b64 s[0:1], 0

; #define LAS __attribute__((address_space(3)))
;     __device__ __forceinline__ void operator()(const f32x4 (&acc)[2][2][4][2], const pg8::Unit& u, int wr, int wc, int fr, int fq) const {
;     ...
;             for (int m = 0; m < 4; ++m) { bf16_t* rowp = Z + (size_t)(row0 + ai * 128 + m * 16) * ldc + col0;
;                 const float rs = rsv[m];
; #pragma unroll
;                 for (int bj = 0; bj < 2; ++bj) { float mm = rs;
;                     if (W) { const f32x4 pp = *(const LAS f32x4*)(part + (lrow0 + ai * 128 + m * 16) * 8 + bj * 4);
;                         const float tot = (W == 128) ? ((pp[0] + pp[1]) + (pp[2] + pp[3])) : (wc < 2 ? pp[0] + pp[1] : pp[2] + pp[3]);
;                         mm = rs * rsqrtf(tot * rs * rs * invW + EPS); }
;                     f32x4 v0 = acc[ai][bj][m][0] * mm * g0, v1 = acc[ai][bj][m][1] * mm * g1;
.LBB0_375:
	v_cvt_pk_bf16_f32 v120, v120, v121
	v_cvt_pk_bf16_f32 v121, v118, v119
	s_and_b64 vcc, exec, s[6:7]
	v_mov_b32_e32 v118, v0
	v_cvt_pk_bf16_f32 v122, v116, v117
	v_cvt_pk_bf16_f32 v123, v114, v115
	global_store_dwordx4 v[126:127], v[120:123], off offset:256
	s_cbranch_vccnz .LBB0_385
	s_add_i32 s0, 0, 0x20000
	v_add_u32_e32 v114, s0, v184
	ds_read_b128 v[114:117], v114 offset:1536
	s_and_b64 vcc, exec, s[10:11]
	s_mov_b64 s[0:1], -1
	s_cbranch_vccnz .LBB0_382
	s_andn2_b64 vcc, exec, s[34:35]
	s_cbranch_vccnz .LBB0_379
	s_waitcnt lgkmcnt(0)
	v_add_f32_e32 v118, v116, v117
	s_mov_b64 s[0:1], 0

; #define LAS __attribute__((address_space(3)))
;     __device__ __forceinline__ void operator()(const f32x4 (&acc)[2][2][4][2], const pg8::Unit& u, int wr, int wc, int fr, int fq) const {
;     ...
;             for (int m = 0; m < 4; ++m) { bf16_t* rowp = Z + (size_t)(row0 + ai * 128 + m * 16) * ldc + col0;
;                 const float rs = rsv[m];
; #pragma unroll
;                 for (int bj = 0; bj < 2; ++bj) { float mm = rs;
;                     if (W) { const f32x4 pp = *(const LAS f32x4*)(part + (lrow0 + ai * 128 + m * 16) * 8 + bj * 4);
;                         const float tot = (W == 128) ? ((pp[0] + pp[1]) + (pp[2] + pp[3])) : (wc < 2 ? pp[0] + pp[1] : pp[2] + pp[3]);
;                         mm = rs * rsqrtf(tot * rs * rs * invW + EPS); }
;                     f32x4 v0 = acc[ai][bj][m][0] * mm * g0, v1 = acc[ai][bj][m][1] * mm * g1;
.LBB0_387:
	v_add_u32_e32 v118, 48, v154
	v_mad_i64_i32 v[118:119], s[0:1], v118, s31, 0
	v_lshl_add_u64 v[118:119], v[118:119], 1, v[156:157]
	s_and_b64 vcc, exec, s[6:7]
	v_cvt_pk_bf16_f32 v124, v116, v117
	v_cvt_pk_bf16_f32 v125, v114, v115
	v_cvt_pk_bf16_f32 v126, v122, v123
	v_cvt_pk_bf16_f32 v127, v120, v121
	global_store_dwordx4 v[118:119], v[124:127], off
	s_cbranch_vccnz .LBB0_397
	s_add_i32 s0, 0, 0x20000
	v_add_u32_e32 v114, s0, v184
	ds_read_b128 v[114:117], v114 offset:1552
	s_and_b64 vcc, exec, s[10:11]
	s_mov_b64 s[0:1], -1
	s_cbranch_vccnz .LBB0_394
	s_andn2_b64 vcc, exec, s[34:35]
	s_cbranch_vccnz .LBB0_391
	s_waitcnt lgkmcnt(0)
	v_add_f32_e32 v120, v116, v117
	s_mov_b64 s[0:1], 0

; __device__ __forceinline__ unsigned cvt_pk_bf16(float lo, float hi) { unsigned r; asm volatile("v_cvt_pk_bf16_f32 %0, %1, %2" : "=v"(r) : "v"(lo), "v"(hi)); return r; }
; #define LAS __attribute__((address_space(3)))
; __device__ __forceinline__ float gelu_tanh_f(float x) { const float u = 0.7978845608028654f * (x + 0.044715f * x * x * x); return x * fast_rcp(1.f + fast_exp2(-2.f * LOG2E * u)); }
;     __device__ __forceinline__ void operator()(const f32x4 (&acc)[2][2][4][2], const pg8::Unit& u, int wr, int wc, int fr, int fq) const {
;     ...
;             for (int m = 0; m < 4; ++m) rsv[m] = ssq ? rsqrtf(ssq[row0 + ai * 128 + m * 16] * (1.f / DM) + EPS) : 1.f;
; #pragma unroll
;             for (int m = 0; m < 4; ++m) { bf16_t* rowp = Z + (size_t)(row0 + ai * 128 + m * 16) * ldc + col0;
;                 const float rs = rsv[m];
; #pragma unroll
;                 for (int bj = 0; bj < 2; ++bj) { float mm = rs;
;                     if (W) { const f32x4 pp = *(const LAS f32x4*)(part + (lrow0 + ai * 128 + m * 16) * 8 + bj * 4);
;                         const float tot = (W == 128) ? ((pp[0] + pp[1]) + (pp[2] + pp[3])) : (wc < 2 ? pp[0] + pp[1] : pp[2] + pp[3]);
;                         mm = rs * rsqrtf(tot * rs * rs * invW + EPS); }
;                     f32x4 v0 = acc[ai][bj][m][0] * mm * g0, v1 = acc[ai][bj][m][1] * mm * g1;
;                     if (act) {
; #pragma unroll
;                         for (int j = 0; j < 4; ++j) { v0[j] = gelu_tanh_f(v0[j]); v1[j] = gelu_tanh_f(v1[j]); } }
;                     u32x4 w; w.x = cvt_pk_bf16(v0[0], v0[1]); w.y = cvt_pk_bf16(v0[2], v0[3]); w.z = cvt_pk_bf16(v1[0], v1[1]); w.w = cvt_pk_bf16(v1[2], v1[3]);
;                     __builtin_nontemporal_store(w, (u32x4*)(rowp + bj * 128)); } } }
.LBB0_399:
	v_cvt_pk_bf16_f32 v112, v112, v113
	v_cvt_pk_bf16_f32 v113, v110, v111
	v_cvt_pk_bf16_f32 v114, v108, v109
	s_nop 0
	v_cvt_pk_bf16_f32 v115, v106, v107
	global_store_dwordx4 v[118:119], v[112:115], off offset:256
	s_and_b64 vcc, exec, s[12:13]
	s_nop 0
	v_mov_b32_e32 v112, 1.0
	v_mov_b32_e32 v114, 1.0
	s_cbranch_vccz .LBB0_406
	s_and_b64 vcc, exec, s[12:13]
	s_cbranch_vccz .LBB0_407

; #define LAS __attribute__((address_space(3)))
;     __device__ __forceinline__ void operator()(const f32x4 (&acc)[2][2][4][2], const pg8::Unit& u, int wr, int wc, int fr, int fq) const {
;     ...
;             for (int m = 0; m < 4; ++m) { bf16_t* rowp = Z + (size_t)(row0 + ai * 128 + m * 16) * ldc + col0;
;                 const float rs = rsv[m];
; #pragma unroll
;                 for (int bj = 0; bj < 2; ++bj) { float mm = rs;
;                     if (W) { const f32x4 pp = *(const LAS f32x4*)(part + (lrow0 + ai * 128 + m * 16) * 8 + bj * 4);
;                         const float tot = (W == 128) ? ((pp[0] + pp[1]) + (pp[2] + pp[3])) : (wc < 2 ? pp[0] + pp[1] : pp[2] + pp[3]);
;                         mm = rs * rsqrtf(tot * rs * rs * invW + EPS); }
;                     f32x4 v0 = acc[ai][bj][m][0] * mm * g0, v1 = acc[ai][bj][m][1] * mm * g1;
.LBB0_421:
	v_add_u32_e32 v111, 0x80, v154
	v_mad_i64_i32 v[116:117], s[0:1], v111, s31, 0
	v_lshl_add_u64 v[116:117], v[116:117], 1, v[156:157]
	s_and_b64 vcc, exec, s[6:7]
	v_cvt_pk_bf16_f32 v122, v108, v109
	v_cvt_pk_bf16_f32 v123, v106, v107
	v_cvt_pk_bf16_f32 v124, v120, v121
	v_cvt_pk_bf16_f32 v125, v118, v119
	global_store_dwordx4 v[116:117], v[122:125], off
	s_cbranch_vccnz .LBB0_431
	s_add_i32 s0, 0, 0x20000
	v_add_u32_e32 v106, s0, v184
	ds_read_b128 v[106:109], v106 offset:4112
	s_and_b64 vcc, exec, s[10:11]
	s_mov_b64 s[0:1], -1
	s_cbranch_vccnz .LBB0_428
	s_andn2_b64 vcc, exec, s[34:35]
	s_cbranch_vccnz .LBB0_425
	s_waitcnt lgkmcnt(0)
	v_add_f32_e32 v111, v108, v109
	s_mov_b64 s[0:1], 0

; #define LAS __attribute__((address_space(3)))
;     __device__ __forceinline__ void operator()(const f32x4 (&acc)[2][2][4][2], const pg8::Unit& u, int wr, int wc, int fr, int fq) const {
;     ...
;             for (int m = 0; m < 4; ++m) { bf16_t* rowp = Z + (size_t)(row0 + ai * 128 + m * 16) * ldc + col0;
;                 const float rs = rsv[m];
; #pragma unroll
;                 for (int bj = 0; bj < 2; ++bj) { float mm = rs;
;                     if (W) { const f32x4 pp = *(const LAS f32x4*)(part + (lrow0 + ai * 128 + m * 16) * 8 + bj * 4);
;                         const float tot = (W == 128) ? ((pp[0] + pp[1]) + (pp[2] + pp[3])) : (wc < 2 ? pp[0] + pp[1] : pp[2] + pp[3]);
;                         mm = rs * rsqrtf(tot * rs * rs * invW + EPS); }
;                     f32x4 v0 = acc[ai][bj][m][0] * mm * g0, v1 = acc[ai][bj][m][1] * mm * g1;
.LBB0_433:
	v_cvt_pk_bf16_f32 v104, v104, v105
	v_cvt_pk_bf16_f32 v105, v102, v103
	s_and_b64 vcc, exec, s[6:7]
	v_mov_b32_e32 v102, v112
	v_cvt_pk_bf16_f32 v106, v100, v101
	v_cvt_pk_bf16_f32 v107, v98, v99
	global_store_dwordx4 v[116:117], v[104:107], off offset:256
	s_cbranch_vccnz .LBB0_443
	s_add_i32 s0, 0, 0x20000
	v_add_u32_e32 v98, s0, v184
	ds_read_b128 v[98:101], v98 offset:4608
	s_and_b64 vcc, exec, s[10:11]
	s_mov_b64 s[0:1], -1
	s_cbranch_vccnz .LBB0_440
	s_andn2_b64 vcc, exec, s[34:35]
	s_cbranch_vccnz .LBB0_437
	s_waitcnt lgkmcnt(0)
	v_add_f32_e32 v102, v100, v101
	s_mov_b64 s[0:1], 0

; #define LAS __attribute__((address_space(3)))
;     __device__ __forceinline__ void operator()(const f32x4 (&acc)[2][2][4][2], const pg8::Unit& u, int wr, int wc, int fr, int fq) const {
;     ...
;             for (int m = 0; m < 4; ++m) { bf16_t* rowp = Z + (size_t)(row0 + ai * 128 + m * 16) * ldc + col0;
;                 const float rs = rsv[m];
; #pragma unroll
;                 for (int bj = 0; bj < 2; ++bj) { float mm = rs;
;                     if (W) { const f32x4 pp = *(const LAS f32x4*)(part + (lrow0 + ai * 128 + m * 16) * 8 + bj * 4);
;                         const float tot = (W == 128) ? ((pp[0] + pp[1]) + (pp[2] + pp[3])) : (wc < 2 ? pp[0] + pp[1] : pp[2] + pp[3]);
;                         mm = rs * rsqrtf(tot * rs * rs * invW + EPS); }
;                     f32x4 v0 = acc[ai][bj][m][0] * mm * g0, v1 = acc[ai][bj][m][1] * mm * g1;
.LBB0_445:
	v_add_u32_e32 v102, 0x90, v154
	v_mad_i64_i32 v[102:103], s[0:1], v102, s31, 0
	v_lshl_add_u64 v[102:103], v[102:103], 1, v[156:157]
	s_and_b64 vcc, exec, s[6:7]
	v_cvt_pk_bf16_f32 v114, v100, v101
	v_cvt_pk_bf16_f32 v115, v98, v99
	v_cvt_pk_bf16_f32 v116, v106, v107
	v_cvt_pk_bf16_f32 v117, v104, v105
	global_store_dwordx4 v[102:103], v[114:117], off
	s_cbranch_vccnz .LBB0_455
	s_add_i32 s0, 0, 0x20000
	v_add_u32_e32 v98, s0, v184
	ds_read_b128 v[98:101], v98 offset:4624
	s_and_b64 vcc, exec, s[10:11]
	s_mov_b64 s[0:1], -1
	s_cbranch_vccnz .LBB0_452
	s_andn2_b64 vcc, exec, s[34:35]
	s_cbranch_vccnz .LBB0_449
	s_waitcnt lgkmcnt(0)
	v_add_f32_e32 v104, v100, v101
	s_mov_b64 s[0:1], 0

; #define LAS __attribute__((address_space(3)))
;     __device__ __forceinline__ void operator()(const f32x4 (&acc)[2][2][4][2], const pg8::Unit& u, int wr, int wc, int fr, int fq) const {
;     ...
;             for (int m = 0; m < 4; ++m) { bf16_t* rowp = Z + (size_t)(row0 + ai * 128 + m * 16) * ldc + col0;
;                 const float rs = rsv[m];
; #pragma unroll
;                 for (int bj = 0; bj < 2; ++bj) { float mm = rs;
;                     if (W) { const f32x4 pp = *(const LAS f32x4*)(part + (lrow0 + ai * 128 + m * 16) * 8 + bj * 4);
;                         const float tot = (W == 128) ? ((pp[0] + pp[1]) + (pp[2] + pp[3])) : (wc < 2 ? pp[0] + pp[1] : pp[2] + pp[3]);
;                         mm = rs * rsqrtf(tot * rs * rs * invW + EPS); }
;                     f32x4 v0 = acc[ai][bj][m][0] * mm * g0, v1 = acc[ai][bj][m][1] * mm * g1;
.LBB0_457:
	v_cvt_pk_bf16_f32 v98, v88, v89
	v_cvt_pk_bf16_f32 v99, v86, v87
	s_and_b64 vcc, exec, s[6:7]
	v_mov_b32_e32 v86, v110
	v_cvt_pk_bf16_f32 v100, v84, v85
	v_cvt_pk_bf16_f32 v101, v82, v83
	global_store_dwordx4 v[102:103], v[98:101], off offset:256
	s_cbranch_vccnz .LBB0_467
	s_add_i32 s0, 0, 0x20000
	v_add_u32_e32 v82, s0, v184
	ds_read_b128 v[82:85], v82 offset:5120
	s_and_b64 vcc, exec, s[10:11]
	s_mov_b64 s[0:1], -1
	s_cbranch_vccnz .LBB0_464
	s_andn2_b64 vcc, exec, s[34:35]
	s_cbranch_vccnz .LBB0_461
	s_waitcnt lgkmcnt(0)
	v_add_f32_e32 v86, v84, v85
	s_mov_b64 s[0:1], 0

; #define LAS __attribute__((address_space(3)))
;     __device__ __forceinline__ void operator()(const f32x4 (&acc)[2][2][4][2], const pg8::Unit& u, int wr, int wc, int fr, int fq) const {
;     ...
;             for (int m = 0; m < 4; ++m) { bf16_t* rowp = Z + (size_t)(row0 + ai * 128 + m * 16) * ldc + col0;
;                 const float rs = rsv[m];
; #pragma unroll
;                 for (int bj = 0; bj < 2; ++bj) { float mm = rs;
;                     if (W) { const f32x4 pp = *(const LAS f32x4*)(part + (lrow0 + ai * 128 + m * 16) * 8 + bj * 4);
;                         const float tot = (W == 128) ? ((pp[0] + pp[1]) + (pp[2] + pp[3])) : (wc < 2 ? pp[0] + pp[1] : pp[2] + pp[3]);
;                         mm = rs * rsqrtf(tot * rs * rs * invW + EPS); }
;                     f32x4 v0 = acc[ai][bj][m][0] * mm * g0, v1 = acc[ai][bj][m][1] * mm * g1;
.LBB0_469:
	v_add_u32_e32 v86, 0xa0, v154
	v_mad_i64_i32 v[86:87], s[0:1], v86, s31, 0
	v_lshl_add_u64 v[86:87], v[86:87], 1, v[156:157]
	s_and_b64 vcc, exec, s[6:7]
	v_cvt_pk_bf16_f32 v100, v84, v85
	v_cvt_pk_bf16_f32 v101, v82, v83
	v_cvt_pk_bf16_f32 v102, v98, v99
	v_cvt_pk_bf16_f32 v103, v88, v89
	global_store_dwordx4 v[86:87], v[100:103], off
	s_cbranch_vccnz .LBB0_479
	s_add_i32 s0, 0, 0x20000
	v_add_u32_e32 v82, s0, v184
	ds_read_b128 v[82:85], v82 offset:5136
	s_and_b64 vcc, exec, s[10:11]
	s_mov_b64 s[0:1], -1
	s_cbranch_vccnz .LBB0_476
	s_andn2_b64 vcc, exec, s[34:35]
	s_cbranch_vccnz .LBB0_473
	s_waitcnt lgkmcnt(0)
	v_add_f32_e32 v88, v84, v85
	s_mov_b64 s[0:1], 0

; #define LAS __attribute__((address_space(3)))
;     __device__ __forceinline__ void operator()(const f32x4 (&acc)[2][2][4][2], const pg8::Unit& u, int wr, int wc, int fr, int fq) const {
;     ...
;             for (int m = 0; m < 4; ++m) { bf16_t* rowp = Z + (size_t)(row0 + ai * 128 + m * 16) * ldc + col0;
;                 const float rs = rsv[m];
; #pragma unroll
;                 for (int bj = 0; bj < 2; ++bj) { float mm = rs;
;                     if (W) { const f32x4 pp = *(const LAS f32x4*)(part + (lrow0 + ai * 128 + m * 16) * 8 + bj * 4);
;                         const float tot = (W == 128) ? ((pp[0] + pp[1]) + (pp[2] + pp[3])) : (wc < 2 ? pp[0] + pp[1] : pp[2] + pp[3]);
;                         mm = rs * rsqrtf(tot * rs * rs * invW + EPS); }
;                     f32x4 v0 = acc[ai][bj][m][0] * mm * g0, v1 = acc[ai][bj][m][1] * mm * g1;
.LBB0_481:
	v_cvt_pk_bf16_f32 v80, v80, v81
	v_cvt_pk_bf16_f32 v81, v78, v79
	s_and_b64 vcc, exec, s[6:7]
	v_mov_b32_e32 v78, v0
	v_cvt_pk_bf16_f32 v82, v76, v77
	v_cvt_pk_bf16_f32 v83, v74, v75
	global_store_dwordx4 v[86:87], v[80:83], off offset:256
	s_cbranch_vccnz .LBB0_491
	s_add_i32 s0, 0, 0x20000
	v_add_u32_e32 v74, s0, v184
	ds_read_b128 v[74:77], v74 offset:5632
	s_and_b64 vcc, exec, s[10:11]
	s_mov_b64 s[0:1], -1
	s_cbranch_vccnz .LBB0_488
	s_andn2_b64 vcc, exec, s[34:35]
	s_cbranch_vccnz .LBB0_485
	s_waitcnt lgkmcnt(0)
	v_add_f32_e32 v78, v76, v77
	s_mov_b64 s[0:1], 0

; #define LAS __attribute__((address_space(3)))
;     __device__ __forceinline__ void operator()(const f32x4 (&acc)[2][2][4][2], const pg8::Unit& u, int wr, int wc, int fr, int fq) const {
;     ...
;             for (int m = 0; m < 4; ++m) { bf16_t* rowp = Z + (size_t)(row0 + ai * 128 + m * 16) * ldc + col0;
;                 const float rs = rsv[m];
; #pragma unroll
;                 for (int bj = 0; bj < 2; ++bj) { float mm = rs;
;                     if (W) { const f32x4 pp = *(const LAS f32x4*)(part + (lrow0 + ai * 128 + m * 16) * 8 + bj * 4);
;                         const float tot = (W == 128) ? ((pp[0] + pp[1]) + (pp[2] + pp[3])) : (wc < 2 ? pp[0] + pp[1] : pp[2] + pp[3]);
;                         mm = rs * rsqrtf(tot * rs * rs * invW + EPS); }
;                     f32x4 v0 = acc[ai][bj][m][0] * mm * g0, v1 = acc[ai][bj][m][1] * mm * g1;
.LBB0_493:
	v_add_u32_e32 v78, 0xb0, v154
	v_mad_i64_i32 v[78:79], s[0:1], v78, s31, 0
	v_lshl_add_u64 v[78:79], v[78:79], 1, v[156:157]
	s_and_b64 vcc, exec, s[6:7]
	v_cvt_pk_bf16_f32 v84, v76, v77
	v_cvt_pk_bf16_f32 v85, v74, v75
	v_cvt_pk_bf16_f32 v86, v82, v83
	v_cvt_pk_bf16_f32 v87, v80, v81
	global_store_dwordx4 v[78:79], v[84:87], off
	s_cbranch_vccnz .LBB0_503
	s_add_i32 s0, 0, 0x20000
	v_add_u32_e32 v74, s0, v184
	ds_read_b128 v[74:77], v74 offset:5648
	s_and_b64 vcc, exec, s[10:11]
	s_mov_b64 s[0:1], -1
	s_cbranch_vccnz .LBB0_500
	s_andn2_b64 vcc, exec, s[34:35]
	s_cbranch_vccnz .LBB0_497
	s_waitcnt lgkmcnt(0)
	v_add_f32_e32 v80, v76, v77
	s_mov_b64 s[0:1], 0

; __device__ __forceinline__ unsigned cvt_pk_bf16(float lo, float hi) { unsigned r; asm volatile("v_cvt_pk_bf16_f32 %0, %1, %2" : "=v"(r) : "v"(lo), "v"(hi)); return r; }
; #define LAS __attribute__((address_space(3)))
; __device__ __forceinline__ float gelu_tanh_f(float x) { const float u = 0.7978845608028654f * (x + 0.044715f * x * x * x); return x * fast_rcp(1.f + fast_exp2(-2.f * LOG2E * u)); }
;     __device__ __forceinline__ void operator()(const f32x4 (&acc)[2][2][4][2], const pg8::Unit& u, int wr, int wc, int fr, int fq) const {
;     ...
;             for (int m = 0; m < 4; ++m) { bf16_t* rowp = Z + (size_t)(row0 + ai * 128 + m * 16) * ldc + col0;
;                 const float rs = rsv[m];
; #pragma unroll
;                 for (int bj = 0; bj < 2; ++bj) { float mm = rs;
;                     if (W) { const f32x4 pp = *(const LAS f32x4*)(part + (lrow0 + ai * 128 + m * 16) * 8 + bj * 4);
;                         const float tot = (W == 128) ? ((pp[0] + pp[1]) + (pp[2] + pp[3])) : (wc < 2 ? pp[0] + pp[1] : pp[2] + pp[3]);
;                         mm = rs * rsqrtf(tot * rs * rs * invW + EPS); }
;                     f32x4 v0 = acc[ai][bj][m][0] * mm * g0, v1 = acc[ai][bj][m][1] * mm * g1;
;                     if (act) {
; #pragma unroll
;                         for (int j = 0; j < 4; ++j) { v0[j] = gelu_tanh_f(v0[j]); v1[j] = gelu_tanh_f(v1[j]); } }
;                     u32x4 w; w.x = cvt_pk_bf16(v0[0], v0[1]); w.y = cvt_pk_bf16(v0[2], v0[3]); w.z = cvt_pk_bf16(v1[0], v1[1]); w.w = cvt_pk_bf16(v1[2], v1[3]);
;                     __builtin_nontemporal_store(w, (u32x4*)(rowp + bj * 128)); } } }
.LBB0_505:
	s_mov_b64 s[6:7], 0
	v_cvt_pk_bf16_f32 v72, v72, v73
	v_cvt_pk_bf16_f32 v73, v70, v71
	v_cvt_pk_bf16_f32 v74, v68, v69
	v_cvt_pk_bf16_f32 v75, v66, v67
	global_store_dwordx4 v[78:79], v[72:75], off offset:256
